# wave-sum exchange steps via v_permlane16/32_swap instead of ds_bpermute (E1, LN, E2); xb loads of the N=1024 GEMM epilogue widened to 16 B
# speedup vs baseline: 1.0596x; 1.0030x over previous
.LBB0_86:
	v_add_u32_e32 v83, s2, v66
	s_movk_i32 s0, 0x4400
	v_cmp_gt_i32_e32 vcc, s0, v83
	v_ashrrev_i32_e32 v67, 31, v66
	s_waitcnt lgkmcnt(0)
	v_lshlrev_b64 v[34:35], 12, v[66:67]
	v_cndmask_b32_e32 v64, v66, v83, vcc
	v_ashrrev_i32_e32 v65, 31, v64
	v_lshlrev_b64 v[36:37], 12, v[64:65]
	v_lshl_add_u64 v[62:63], v[60:61], 0, v[36:37]
	v_lshl_add_u64 v[68:69], v[60:61], 0, v[34:35]
	global_load_dwordx4 v[46:49], v[62:63], off
	global_load_dwordx4 v[42:45], v[62:63], off offset:1024
	global_load_dwordx4 v[38:41], v[62:63], off offset:2048
	global_load_dwordx4 v[34:37], v[62:63], off offset:3072
	global_load_dwordx4 v[50:53], v[68:69], off offset:3072
	global_load_dwordx4 v[54:57], v[68:69], off offset:2048
	s_mov_b64 s[44:45], -1
	s_waitcnt vmcnt(0)
	v_mov_b32_e32 v71, v50
	s_waitcnt vmcnt(0)
	v_mov_b32_e32 v70, v54
	v_mov_b32_e32 v72, v55
	v_mov_b32_e32 v73, v51
	v_pk_add_f32 v[70:71], v[70:71], v[72:73]
	v_mov_b32_e32 v72, v56
	v_mov_b32_e32 v73, v52
	v_pk_add_f32 v[70:71], v[70:71], v[72:73]
	v_mov_b32_e32 v72, v57
	v_mov_b32_e32 v73, v53
	v_pk_add_f32 v[70:71], v[70:71], v[72:73]
	global_load_dwordx4 v[72:75], v[68:69], off offset:1024
	global_load_dwordx4 v[76:79], v[68:69], off
	s_waitcnt vmcnt(1)
	v_mov_b32_e32 v81, v72
	s_waitcnt vmcnt(0)
	v_mov_b32_e32 v80, v76
	v_mov_b32_e32 v84, v77
	v_mov_b32_e32 v85, v73
	v_pk_add_f32 v[80:81], v[80:81], v[84:85]
	v_mov_b32_e32 v84, v78
	v_mov_b32_e32 v85, v74
	v_pk_add_f32 v[80:81], v[80:81], v[84:85]
	v_mov_b32_e32 v84, v79
	v_mov_b32_e32 v85, v75
	v_pk_add_f32 v[80:81], v[80:81], v[84:85]
	s_nop 0
	v_add_f32_e32 v0, 0, v80
	v_add_f32_e32 v0, v0, v81
	v_add_f32_e32 v0, v0, v70
	v_add_f32_e32 v0, v0, v71
	s_nop 1
	v_add_f32_dpp v0, v0, v0 quad_perm:[1,0,3,2] row_mask:0xf bank_mask:0xf bound_ctrl:1
	s_nop 1
	v_add_f32_dpp v0, v0, v0 quad_perm:[2,3,0,1] row_mask:0xf bank_mask:0xf bound_ctrl:1
	s_nop 1
	v_add_f32_dpp v0, v0, v0 row_half_mirror row_mask:0xf bank_mask:0xf bound_ctrl:1
	s_nop 1
	v_add_f32_dpp v0, v0, v0 row_mirror row_mask:0xf bank_mask:0xf bound_ctrl:1
	v_mov_b32_e32 v70, v0
	v_mov_b32_e32 v255, v0
	s_nop 1
	v_permlane16_swap_b32_e32 v70, v255
	s_nop 1
	v_add_f32_e32 v0, v70, v255
	v_mov_b32_e32 v70, v0
	v_mov_b32_e32 v255, v0
	s_nop 1
	v_permlane32_swap_b32_e32 v70, v255
	s_nop 1
	v_add_f32_e32 v0, v70, v255
	v_mul_f32_e32 v0, 0x3a800000, v0
	v_pk_add_f32 v[80:81], v[76:77], v[0:1] op_sel_hi:[1,0] neg_lo:[0,1] neg_hi:[0,1]
	v_pk_add_f32 v[72:73], v[72:73], v[0:1] op_sel_hi:[1,0] neg_lo:[0,1] neg_hi:[0,1]
	v_mov_b32_e32 v76, v81
	v_mov_b32_e32 v77, v73
	v_pk_add_f32 v[84:85], v[78:79], v[0:1] op_sel_hi:[1,0] neg_lo:[0,1] neg_hi:[0,1]
	v_pk_add_f32 v[70:71], v[74:75], v[0:1] op_sel_hi:[1,0] neg_lo:[0,1] neg_hi:[0,1]
	v_mov_b32_e32 v74, v80
	v_mov_b32_e32 v75, v72
	v_pk_mul_f32 v[76:77], v[76:77], v[76:77]
	s_nop 0
	v_pk_fma_f32 v[74:75], v[74:75], v[74:75], v[76:77]
	v_mov_b32_e32 v76, v84
	v_mov_b32_e32 v77, v70
	v_pk_fma_f32 v[74:75], v[76:77], v[76:77], v[74:75]
	v_mov_b32_e32 v76, v85
	v_mov_b32_e32 v77, v71
	v_pk_fma_f32 v[78:79], v[76:77], v[76:77], v[74:75]
	v_pk_add_f32 v[76:77], v[54:55], v[0:1] op_sel_hi:[1,0] neg_lo:[0,1] neg_hi:[0,1]
	v_pk_add_f32 v[74:75], v[56:57], v[0:1] op_sel_hi:[1,0] neg_lo:[0,1] neg_hi:[0,1]
	v_pk_add_f32 v[56:57], v[50:51], v[0:1] op_sel_hi:[1,0] neg_lo:[0,1] neg_hi:[0,1]
	v_pk_add_f32 v[54:55], v[52:53], v[0:1] op_sel_hi:[1,0] neg_lo:[0,1] neg_hi:[0,1]
	v_mov_b32_e32 v52, v57
	v_mov_b32_e32 v53, v77
	v_mov_b32_e32 v50, v56
	v_mov_b32_e32 v51, v76
	v_pk_mul_f32 v[52:53], v[52:53], v[52:53]
	v_add_f32_e32 v0, v78, v79
	v_pk_fma_f32 v[50:51], v[50:51], v[50:51], v[52:53]
	v_mov_b32_e32 v52, v54
	v_mov_b32_e32 v53, v74
	v_pk_fma_f32 v[50:51], v[52:53], v[52:53], v[50:51]
	v_mov_b32_e32 v52, v55
	v_mov_b32_e32 v53, v75
	v_pk_fma_f32 v[50:51], v[52:53], v[52:53], v[50:51]
	s_nop 0
	v_add_f32_e32 v0, v51, v0
	v_add_f32_e32 v0, v50, v0
	s_nop 1
	v_add_f32_dpp v0, v0, v0 quad_perm:[1,0,3,2] row_mask:0xf bank_mask:0xf bound_ctrl:1
	s_nop 1
	v_add_f32_dpp v0, v0, v0 quad_perm:[2,3,0,1] row_mask:0xf bank_mask:0xf bound_ctrl:1
	s_nop 1
	v_add_f32_dpp v0, v0, v0 row_half_mirror row_mask:0xf bank_mask:0xf bound_ctrl:1
	s_nop 1
	v_add_f32_dpp v0, v0, v0 row_mirror row_mask:0xf bank_mask:0xf bound_ctrl:1
	v_mov_b32_e32 v50, v0
	v_mov_b32_e32 v255, v0
	s_nop 1
	v_permlane16_swap_b32_e32 v50, v255
	s_nop 1
	v_add_f32_e32 v0, v50, v255
	v_mov_b32_e32 v50, v0
	v_mov_b32_e32 v255, v0
	s_nop 1
	v_permlane32_swap_b32_e32 v50, v255
	s_nop 1
	v_add_f32_e32 v0, v50, v255
	v_fmamk_f32 v0, v0, 0x3a800000, v122
	v_cmp_gt_f32_e32 vcc, s84, v0
	v_mul_f32_e32 v50, 0x4b800000, v0
	s_nop 0
	v_cndmask_b32_e32 v0, v0, v50, vcc
	v_rsq_f32_e32 v0, v0
	s_nop 0
	v_mul_f32_e32 v50, 0x45800000, v0
	v_cndmask_b32_e32 v78, v0, v50, vcc
	v_pk_mul_f32 v[50:51], v[80:81], v[78:79] op_sel_hi:[1,0]
	v_pk_mul_f32 v[52:53], v[84:85], v[78:79] op_sel_hi:[1,0]
	v_cndmask_b32_e64 v0, 0, 1, s[40:41]
	v_pk_fma_f32 v[50:51], v[2:3], v[50:51], v[10:11]
	v_pk_fma_f32 v[52:53], v[4:5], v[52:53], v[12:13]
	v_cmp_ne_u32_e64 s[0:1], 1, v0
	s_andn2_b64 vcc, exec, s[40:41]
	s_cbranch_vccnz .LBB0_88
	s_mov_b64 s[44:45], 0
	global_store_dwordx4 v[68:69], v[50:53], off nt

.LBB0_102:
	v_mov_b32_e32 v50, v46
	v_mov_b32_e32 v51, v42
	v_mov_b32_e32 v52, v47
	v_mov_b32_e32 v53, v43
	v_pk_add_f32 v[50:51], v[50:51], v[52:53]
	v_mov_b32_e32 v52, v48
	v_mov_b32_e32 v53, v44
	v_pk_add_f32 v[50:51], v[50:51], v[52:53]
	v_mov_b32_e32 v52, v49
	v_mov_b32_e32 v53, v45
	v_pk_add_f32 v[50:51], v[50:51], v[52:53]
	v_mov_b32_e32 v52, v39
	v_add_f32_e32 v50, 0, v50
	v_add_f32_e32 v54, v50, v51
	v_mov_b32_e32 v50, v38
	v_mov_b32_e32 v51, v34
	v_mov_b32_e32 v53, v35
	v_pk_add_f32 v[50:51], v[50:51], v[52:53]
	v_mov_b32_e32 v52, v40
	v_mov_b32_e32 v53, v36
	v_pk_add_f32 v[50:51], v[50:51], v[52:53]
	v_mov_b32_e32 v52, v41
	v_mov_b32_e32 v53, v37
	v_pk_add_f32 v[50:51], v[50:51], v[52:53]
	v_cmp_ne_u32_e32 vcc, v66, v64
	v_add_f32_e32 v50, v54, v50
	v_add_f32_e32 v50, v50, v51
	s_nop 1
	v_add_f32_dpp v50, v50, v50 quad_perm:[1,0,3,2] row_mask:0xf bank_mask:0xf bound_ctrl:1
	s_nop 1
	v_add_f32_dpp v50, v50, v50 quad_perm:[2,3,0,1] row_mask:0xf bank_mask:0xf bound_ctrl:1
	s_nop 1
	v_add_f32_dpp v50, v50, v50 row_half_mirror row_mask:0xf bank_mask:0xf bound_ctrl:1
	s_nop 1
	v_add_f32_dpp v50, v50, v50 row_mirror row_mask:0xf bank_mask:0xf bound_ctrl:1
	v_mov_b32_e32 v51, v50
	v_mov_b32_e32 v255, v50
	s_nop 1
	v_permlane16_swap_b32_e32 v51, v255
	s_nop 1
	v_add_f32_e32 v50, v51, v255
	v_mov_b32_e32 v51, v50
	v_mov_b32_e32 v255, v50
	s_nop 1
	v_permlane32_swap_b32_e32 v51, v255
	s_nop 1
	v_add_f32_e32 v50, v51, v255
	v_mul_f32_e32 v56, 0x3a800000, v50
	v_pk_add_f32 v[54:55], v[46:47], v[56:57] op_sel_hi:[1,0] neg_lo:[0,1] neg_hi:[0,1]
	v_pk_add_f32 v[52:53], v[42:43], v[56:57] op_sel_hi:[1,0] neg_lo:[0,1] neg_hi:[0,1]
	v_pk_add_f32 v[50:51], v[44:45], v[56:57] op_sel_hi:[1,0] neg_lo:[0,1] neg_hi:[0,1]
	v_mov_b32_e32 v44, v55
	v_mov_b32_e32 v45, v53
	v_pk_add_f32 v[48:49], v[48:49], v[56:57] op_sel_hi:[1,0] neg_lo:[0,1] neg_hi:[0,1]
	v_mov_b32_e32 v42, v54
	v_mov_b32_e32 v43, v52
	v_pk_mul_f32 v[44:45], v[44:45], v[44:45]
	s_nop 0
	v_pk_fma_f32 v[42:43], v[42:43], v[42:43], v[44:45]
	v_mov_b32_e32 v44, v48
	v_mov_b32_e32 v45, v50
	v_pk_fma_f32 v[42:43], v[44:45], v[44:45], v[42:43]
	v_mov_b32_e32 v44, v49
	v_mov_b32_e32 v45, v51
	v_pk_fma_f32 v[46:47], v[44:45], v[44:45], v[42:43]
	v_pk_add_f32 v[44:45], v[38:39], v[56:57] op_sel_hi:[1,0] neg_lo:[0,1] neg_hi:[0,1]
	v_pk_add_f32 v[42:43], v[40:41], v[56:57] op_sel_hi:[1,0] neg_lo:[0,1] neg_hi:[0,1]
	v_pk_add_f32 v[40:41], v[34:35], v[56:57] op_sel_hi:[1,0] neg_lo:[0,1] neg_hi:[0,1]
	v_pk_add_f32 v[38:39], v[36:37], v[56:57] op_sel_hi:[1,0] neg_lo:[0,1] neg_hi:[0,1]
	v_mov_b32_e32 v36, v41
	v_mov_b32_e32 v37, v45
	v_mov_b32_e32 v34, v40
	v_mov_b32_e32 v35, v44
	v_pk_mul_f32 v[36:37], v[36:37], v[36:37]
	s_nop 0
	v_pk_fma_f32 v[34:35], v[34:35], v[34:35], v[36:37]
	v_mov_b32_e32 v36, v38
	v_mov_b32_e32 v37, v42
	v_pk_fma_f32 v[34:35], v[36:37], v[36:37], v[34:35]
	v_mov_b32_e32 v36, v39
	v_mov_b32_e32 v37, v43
	v_pk_fma_f32 v[34:35], v[36:37], v[36:37], v[34:35]
	v_add_f32_e32 v36, v46, v47
	v_add_f32_e32 v35, v35, v36
	v_add_f32_e32 v34, v34, v35
	s_nop 1
	v_add_f32_dpp v34, v34, v34 quad_perm:[1,0,3,2] row_mask:0xf bank_mask:0xf bound_ctrl:1
	s_nop 1
	v_add_f32_dpp v34, v34, v34 quad_perm:[2,3,0,1] row_mask:0xf bank_mask:0xf bound_ctrl:1
	s_nop 1
	v_add_f32_dpp v34, v34, v34 row_half_mirror row_mask:0xf bank_mask:0xf bound_ctrl:1
	s_nop 1
	v_add_f32_dpp v34, v34, v34 row_mirror row_mask:0xf bank_mask:0xf bound_ctrl:1
	ds_bpermute_b32 v35, v59, v34
	s_waitcnt lgkmcnt(0)
	v_add_f32_e32 v34, v34, v35
	ds_bpermute_b32 v35, v82, v34
	s_and_saveexec_b64 s[44:45], vcc
	s_cbranch_execz .LBB0_85
	s_waitcnt lgkmcnt(0)
	v_add_f32_e32 v34, v34, v35
	v_fmamk_f32 v34, v34, 0x3a800000, v122
	v_mul_f32_e32 v35, 0x4b800000, v34
	v_cmp_gt_f32_e32 vcc, s84, v34
	s_mov_b64 s[46:47], -1
	s_nop 0
	v_cndmask_b32_e32 v34, v34, v35, vcc
	v_rsq_f32_e32 v34, v34
	s_nop 0
	v_mul_f32_e32 v35, 0x45800000, v34
	v_cndmask_b32_e32 v46, v34, v35, vcc
	v_pk_mul_f32 v[34:35], v[54:55], v[46:47] op_sel_hi:[1,0]
	v_pk_mul_f32 v[36:37], v[48:49], v[46:47] op_sel_hi:[1,0]
	v_pk_fma_f32 v[34:35], v[2:3], v[34:35], v[10:11]
	v_pk_fma_f32 v[36:37], v[4:5], v[36:37], v[12:13]
	s_and_b64 vcc, exec, s[0:1]
	s_cbranch_vccnz .LBB0_105
	s_mov_b64 s[46:47], 0
	global_store_dwordx4 v[62:63], v[34:37], off nt

.LBB0_140:
	s_andn2_b64 vcc, exec, s[0:1]
	s_cbranch_vccnz .LBB0_152
	v_and_b32_e32 v135, 63, v144
	v_lshrrev_b32_e32 v136, 6, v144
	v_lshlrev_b32_e32 v0, 10, v136
	s_nop 0
	v_readfirstlane_b32 s44, v0
	v_lshrrev_b32_e32 v137, 3, v135
	v_lshl_add_u32 v137, v136, 3, v137
	v_lshrrev_b32_e32 v138, 1, v137
	v_xor_b32_e32 v138, v138, v135
	v_and_b32_e32 v138, 7, v138
	v_lshlrev_b32_e32 v138, 4, v138
	s_movk_i32 s1, 0x1600
	s_movk_i32 s2, 0x1600
	v_add_u32_e32 v139, 0, v137
	v_mul_lo_u32 v114, v139, s1
	v_add_u32_e32 v114, v114, v138
	v_mul_lo_u32 v119, v139, s2
	v_add_u32_e32 v119, v119, v138
	v_add_u32_e32 v139, 32, v137
	v_mul_lo_u32 v115, v139, s1
	v_add_u32_e32 v115, v115, v138
	v_mul_lo_u32 v120, v139, s2
	v_add_u32_e32 v120, v120, v138
	v_add_u32_e32 v139, 64, v137
	v_mul_lo_u32 v116, v139, s1
	v_add_u32_e32 v116, v116, v138
	v_mul_lo_u32 v121, v139, s2
	v_add_u32_e32 v121, v121, v138
	v_add_u32_e32 v139, 96, v137
	v_mul_lo_u32 v117, v139, s1
	v_add_u32_e32 v117, v117, v138
	v_mul_lo_u32 v126, v139, s2
	v_add_u32_e32 v126, v126, v138
	v_add_u32_e32 v139, 128, v137
	v_mul_lo_u32 v118, v139, s1
	v_add_u32_e32 v118, v118, v138
	v_and_b32_e32 v139, 15, v135
	v_lshrrev_b32_e32 v140, 4, v135
	v_lshrrev_b32_e32 v141, 1, v136
	v_and_b32_e32 v142, 1, v136
	v_bfe_u32 v143, v135, 1, 3
	v_add_u32_e32 v138, 0, v140
	v_xor_b32_e32 v138, v138, v143
	v_lshlrev_b32_e32 v138, 4, v138
	v_lshl_add_u32 v133, v139, 7, v138
	v_lshl_add_u32 v127, v141, 13, v133
	v_lshl_add_u32 v129, v142, 13, v133
	v_add_u32_e32 v129, 0x4000, v129
	v_add_u32_e32 v133, 0x8000, v133
	v_lshl_add_u32 v131, v141, 12, v129
	v_mov_b32_e32 v0, v131
	v_xor_b32_e32 v137, 1, v141
	v_lshl_add_u32 v131, v137, 12, v129
	v_mov_b32_e32 v129, v0
	v_add_u32_e32 v138, 4, v140
	v_xor_b32_e32 v138, v138, v143
	v_lshlrev_b32_e32 v138, 4, v138
	v_lshl_add_u32 v134, v139, 7, v138
	v_lshl_add_u32 v128, v141, 13, v134
	v_lshl_add_u32 v130, v142, 13, v134
	v_add_u32_e32 v130, 0x4000, v130
	v_add_u32_e32 v134, 0x8000, v134
	v_lshl_add_u32 v132, v141, 12, v130
	v_mov_b32_e32 v0, v132
	v_xor_b32_e32 v137, 1, v141
	v_lshl_add_u32 v132, v137, 12, v130
	v_mov_b32_e32 v130, v0
	v_lshl_add_u32 v135, v141, 6, v139
	v_lshlrev_b32_e32 v136, 2, v140
	v_lshl_add_u32 v136, v142, 6, v136
	v_lshl_add_u32 v138, v137, 5, v136
	v_lshl_add_u32 v136, v141, 5, v136
	v_add_u32_e32 v0, 0, v135
	v_lshlrev_b32_e32 v137, 11, v0
	v_lshl_add_u32 v196, v136, 1, v137
	v_lshl_add_u32 v197, v138, 1, v137
	v_lshlrev_b32_e32 v137, 12, v0
	v_lshl_add_u32 v204, v136, 2, v137
	v_lshl_add_u32 v205, v138, 2, v137
	v_add_u32_e32 v0, 16, v135
	v_lshlrev_b32_e32 v137, 11, v0
	v_lshl_add_u32 v198, v136, 1, v137
	v_lshl_add_u32 v199, v138, 1, v137
	v_lshlrev_b32_e32 v137, 12, v0
	v_lshl_add_u32 v206, v136, 2, v137
	v_lshl_add_u32 v207, v138, 2, v137
	v_add_u32_e32 v0, 32, v135
	v_lshlrev_b32_e32 v137, 11, v0
	v_lshl_add_u32 v200, v136, 1, v137
	v_lshl_add_u32 v201, v138, 1, v137
	v_lshlrev_b32_e32 v137, 12, v0
	v_lshl_add_u32 v208, v136, 2, v137
	v_lshl_add_u32 v209, v138, 2, v137
	v_add_u32_e32 v0, 48, v135
	v_lshlrev_b32_e32 v137, 11, v0
	v_lshl_add_u32 v202, v136, 1, v137
	v_lshl_add_u32 v203, v138, 1, v137
	v_lshlrev_b32_e32 v137, 12, v0
	v_lshl_add_u32 v210, v136, 2, v137
	v_lshl_add_u32 v211, v138, 2, v137
	v_add_u32_e32 v0, 128, v139
	v_lshlrev_b32_e32 v137, 11, v0
	v_lshl_add_u32 v212, v136, 1, v137
	v_lshlrev_b32_e32 v137, 12, v0
	v_lshl_add_u32 v213, v136, 2, v137
	v_and_b32_e32 v137, 1, v140
	v_lshlrev_b32_e32 v137, 4, v137
	v_lshrrev_b32_e32 v0, 1, v140
	v_lshl_add_u32 v137, v0, 3, v137
	v_lshlrev_b32_e32 v0, 2, v140
	v_sub_u32_e32 v137, v137, v0
	v_lshlrev_b32_e32 v137, 1, v137
	v_add_u32_e32 v196, v196, v137
	v_add_u32_e32 v197, v197, v137
	v_add_u32_e32 v198, v198, v137
	v_add_u32_e32 v199, v199, v137
	v_add_u32_e32 v200, v200, v137
	v_add_u32_e32 v201, v201, v137
	v_add_u32_e32 v202, v202, v137
	v_add_u32_e32 v203, v203, v137
	v_add_u32_e32 v212, v212, v137
	v_cmp_gt_u32_e32 vcc, 8, v139
	s_nop 3
	s_mov_b64 s[48:49], vcc
	s_mov_b32 s50, 0x3fb504f3
	s_mov_b32 s0, s91

.Lg4_last_join:
	s_setprio 0
	s_waitcnt lgkmcnt(9)
	v_mfma_f32_16x16x32_bf16 v[2:5], v[164:167], v[74:77], v[2:5]
	v_mfma_f32_16x16x32_bf16 v[6:9], v[168:171], v[74:77], v[6:9]
	v_mfma_f32_16x16x32_bf16 v[10:13], v[172:175], v[74:77], v[10:13]
	v_mfma_f32_16x16x32_bf16 v[14:17], v[176:179], v[74:77], v[14:17]
	v_mfma_f32_16x16x32_bf16 v[18:21], v[164:167], v[78:81], v[18:21]
	v_mfma_f32_16x16x32_bf16 v[22:25], v[168:171], v[78:81], v[22:25]
	v_mfma_f32_16x16x32_bf16 v[26:29], v[172:175], v[78:81], v[26:29]
	v_mfma_f32_16x16x32_bf16 v[30:33], v[176:179], v[78:81], v[30:33]
	v_mfma_f32_16x16x32_bf16 v[34:37], v[164:167], v[82:85], v[34:37]
	v_mfma_f32_16x16x32_bf16 v[38:41], v[168:171], v[82:85], v[38:41]
	v_mfma_f32_16x16x32_bf16 v[42:45], v[172:175], v[82:85], v[42:45]
	v_mfma_f32_16x16x32_bf16 v[46:49], v[176:179], v[82:85], v[46:49]
	v_mfma_f32_16x16x32_bf16 v[50:53], v[164:167], v[86:89], v[50:53]
	v_mfma_f32_16x16x32_bf16 v[54:57], v[168:171], v[86:89], v[54:57]
	v_mfma_f32_16x16x32_bf16 v[58:61], v[172:175], v[86:89], v[58:61]
	v_mfma_f32_16x16x32_bf16 v[62:65], v[176:179], v[86:89], v[62:65]
	v_mfma_f32_16x16x32_bf16 v[66:69], v[164:167], v[106:109], v[66:69]
	v_mfma_f32_16x16x32_bf16 v[70:73], v[168:171], v[106:109], v[70:73]
	s_waitcnt lgkmcnt(0)
	v_mfma_f32_16x16x32_bf16 v[2:5], v[180:183], v[90:93], v[2:5]
	v_mfma_f32_16x16x32_bf16 v[6:9], v[184:187], v[90:93], v[6:9]
	v_mfma_f32_16x16x32_bf16 v[10:13], v[188:191], v[90:93], v[10:13]
	v_mfma_f32_16x16x32_bf16 v[14:17], v[192:195], v[90:93], v[14:17]
	v_mfma_f32_16x16x32_bf16 v[18:21], v[180:183], v[94:97], v[18:21]
	v_mfma_f32_16x16x32_bf16 v[22:25], v[184:187], v[94:97], v[22:25]
	v_mfma_f32_16x16x32_bf16 v[26:29], v[188:191], v[94:97], v[26:29]
	v_mfma_f32_16x16x32_bf16 v[30:33], v[192:195], v[94:97], v[30:33]
	v_mfma_f32_16x16x32_bf16 v[34:37], v[180:183], v[98:101], v[34:37]
	v_mfma_f32_16x16x32_bf16 v[38:41], v[184:187], v[98:101], v[38:41]
	v_mfma_f32_16x16x32_bf16 v[42:45], v[188:191], v[98:101], v[42:45]
	v_mfma_f32_16x16x32_bf16 v[46:49], v[192:195], v[98:101], v[46:49]
	v_mfma_f32_16x16x32_bf16 v[50:53], v[180:183], v[102:105], v[50:53]
	v_mfma_f32_16x16x32_bf16 v[54:57], v[184:187], v[102:105], v[54:57]
	v_mfma_f32_16x16x32_bf16 v[58:61], v[188:191], v[102:105], v[58:61]
	v_mfma_f32_16x16x32_bf16 v[62:65], v[192:195], v[102:105], v[62:65]
	v_mfma_f32_16x16x32_bf16 v[66:69], v[180:183], v[110:113], v[66:69]
	v_mfma_f32_16x16x32_bf16 v[70:73], v[184:187], v[110:113], v[70:73]
	s_add_u32 s45, s45, 1
	s_cmpk_lt_u32 s45, 22
	s_cbranch_scc1 .Lg4_kloop
	s_nop 7
	s_nop 7
	global_load_dwordx4 v[214:217], v196, s[40:41]
	global_load_dwordx4 v[218:221], v197, s[40:41]
	global_load_dwordx4 v[222:225], v198, s[40:41]
	global_load_dwordx4 v[226:229], v199, s[40:41]
	s_waitcnt vmcnt(3)
	s_nop 0
	v_permlane16_swap_b32_e32 v214, v216
	v_permlane16_swap_b32_e32 v215, v217
	s_nop 1
	v_lshlrev_b32_e32 v135, 16, v214
	v_and_b32_e32 v136, 0xffff0000, v214
	v_lshlrev_b32_e32 v137, 16, v215
	v_and_b32_e32 v138, 0xffff0000, v215
	v_fma_f32 v2, v135, s50, v2
	v_fma_f32 v3, v136, s50, v3
	v_fma_f32 v4, v137, s50, v4
	v_fma_f32 v5, v138, s50, v5
	global_store_dwordx4 v204, v[2:5], s[42:43]
	v_lshlrev_b32_e32 v135, 16, v216
	v_and_b32_e32 v136, 0xffff0000, v216
	v_lshlrev_b32_e32 v137, 16, v217
	v_and_b32_e32 v138, 0xffff0000, v217
	v_fma_f32 v6, v135, s50, v6
	v_fma_f32 v7, v136, s50, v7
	v_fma_f32 v8, v137, s50, v8
	v_fma_f32 v9, v138, s50, v9
	global_store_dwordx4 v204, v[6:9], s[42:43] offset:64
	s_waitcnt vmcnt(4)
	s_nop 0
	v_permlane16_swap_b32_e32 v218, v220
	v_permlane16_swap_b32_e32 v219, v221
	s_nop 1
	v_lshlrev_b32_e32 v135, 16, v218
	v_and_b32_e32 v136, 0xffff0000, v218
	v_lshlrev_b32_e32 v137, 16, v219
	v_and_b32_e32 v138, 0xffff0000, v219
	v_fma_f32 v10, v135, s50, v10
	v_fma_f32 v11, v136, s50, v11
	v_fma_f32 v12, v137, s50, v12
	v_fma_f32 v13, v138, s50, v13
	global_store_dwordx4 v205, v[10:13], s[42:43]
	v_lshlrev_b32_e32 v135, 16, v220
	v_and_b32_e32 v136, 0xffff0000, v220
	v_lshlrev_b32_e32 v137, 16, v221
	v_and_b32_e32 v138, 0xffff0000, v221
	v_fma_f32 v14, v135, s50, v14
	v_fma_f32 v15, v136, s50, v15
	v_fma_f32 v16, v137, s50, v16
	v_fma_f32 v17, v138, s50, v17
	global_store_dwordx4 v205, v[14:17], s[42:43] offset:64
	global_load_dwordx4 v[214:217], v200, s[40:41]
	global_load_dwordx4 v[218:221], v201, s[40:41]
	s_waitcnt vmcnt(7)
	s_nop 0
	v_permlane16_swap_b32_e32 v222, v224
	v_permlane16_swap_b32_e32 v223, v225
	s_nop 1
	v_lshlrev_b32_e32 v135, 16, v222
	v_and_b32_e32 v136, 0xffff0000, v222
	v_lshlrev_b32_e32 v137, 16, v223
	v_and_b32_e32 v138, 0xffff0000, v223
	v_fma_f32 v18, v135, s50, v18
	v_fma_f32 v19, v136, s50, v19
	v_fma_f32 v20, v137, s50, v20
	v_fma_f32 v21, v138, s50, v21
	global_store_dwordx4 v206, v[18:21], s[42:43]
	v_lshlrev_b32_e32 v135, 16, v224
	v_and_b32_e32 v136, 0xffff0000, v224
	v_lshlrev_b32_e32 v137, 16, v225
	v_and_b32_e32 v138, 0xffff0000, v225
	v_fma_f32 v22, v135, s50, v22
	v_fma_f32 v23, v136, s50, v23
	v_fma_f32 v24, v137, s50, v24
	v_fma_f32 v25, v138, s50, v25
	global_store_dwordx4 v206, v[22:25], s[42:43] offset:64
	s_waitcnt vmcnt(8)
	s_nop 0
	v_permlane16_swap_b32_e32 v226, v228
	v_permlane16_swap_b32_e32 v227, v229
	s_nop 1
	v_lshlrev_b32_e32 v135, 16, v226
	v_and_b32_e32 v136, 0xffff0000, v226
	v_lshlrev_b32_e32 v137, 16, v227
	v_and_b32_e32 v138, 0xffff0000, v227
	v_fma_f32 v26, v135, s50, v26
	v_fma_f32 v27, v136, s50, v27
	v_fma_f32 v28, v137, s50, v28
	v_fma_f32 v29, v138, s50, v29
	global_store_dwordx4 v207, v[26:29], s[42:43]
	v_lshlrev_b32_e32 v135, 16, v228
	v_and_b32_e32 v136, 0xffff0000, v228
	v_lshlrev_b32_e32 v137, 16, v229
	v_and_b32_e32 v138, 0xffff0000, v229
	v_fma_f32 v30, v135, s50, v30
	v_fma_f32 v31, v136, s50, v31
	v_fma_f32 v32, v137, s50, v32
	v_fma_f32 v33, v138, s50, v33
	global_store_dwordx4 v207, v[30:33], s[42:43] offset:64
	global_load_dwordx4 v[222:225], v202, s[40:41]
	global_load_dwordx4 v[226:229], v203, s[40:41]
	s_waitcnt vmcnt(7)
	s_nop 0
	v_permlane16_swap_b32_e32 v214, v216
	v_permlane16_swap_b32_e32 v215, v217
	s_nop 1
	v_lshlrev_b32_e32 v135, 16, v214
	v_and_b32_e32 v136, 0xffff0000, v214
	v_lshlrev_b32_e32 v137, 16, v215
	v_and_b32_e32 v138, 0xffff0000, v215
	v_fma_f32 v34, v135, s50, v34
	v_fma_f32 v35, v136, s50, v35
	v_fma_f32 v36, v137, s50, v36
	v_fma_f32 v37, v138, s50, v37
	global_store_dwordx4 v208, v[34:37], s[42:43]
	v_lshlrev_b32_e32 v135, 16, v216
	v_and_b32_e32 v136, 0xffff0000, v216
	v_lshlrev_b32_e32 v137, 16, v217
	v_and_b32_e32 v138, 0xffff0000, v217
	v_fma_f32 v38, v135, s50, v38
	v_fma_f32 v39, v136, s50, v39
	v_fma_f32 v40, v137, s50, v40
	v_fma_f32 v41, v138, s50, v41
	global_store_dwordx4 v208, v[38:41], s[42:43] offset:64
	s_waitcnt vmcnt(8)
	s_nop 0
	v_permlane16_swap_b32_e32 v218, v220
	v_permlane16_swap_b32_e32 v219, v221
	s_nop 1
	v_lshlrev_b32_e32 v135, 16, v218
	v_and_b32_e32 v136, 0xffff0000, v218
	v_lshlrev_b32_e32 v137, 16, v219
	v_and_b32_e32 v138, 0xffff0000, v219
	v_fma_f32 v42, v135, s50, v42
	v_fma_f32 v43, v136, s50, v43
	v_fma_f32 v44, v137, s50, v44
	v_fma_f32 v45, v138, s50, v45
	global_store_dwordx4 v209, v[42:45], s[42:43]
	v_lshlrev_b32_e32 v135, 16, v220
	v_and_b32_e32 v136, 0xffff0000, v220
	v_lshlrev_b32_e32 v137, 16, v221
	v_and_b32_e32 v138, 0xffff0000, v221
	v_fma_f32 v46, v135, s50, v46
	v_fma_f32 v47, v136, s50, v47
	v_fma_f32 v48, v137, s50, v48
	v_fma_f32 v49, v138, s50, v49
	global_store_dwordx4 v209, v[46:49], s[42:43] offset:64
	s_mov_b64 s[98:99], exec
	s_mov_b64 exec, s[48:49]
	global_load_dwordx4 v[230:233], v212, s[40:41]
	s_mov_b64 exec, s[98:99]
	s_waitcnt vmcnt(6)
	s_nop 0
	v_permlane16_swap_b32_e32 v222, v224
	v_permlane16_swap_b32_e32 v223, v225
	s_nop 1
	v_lshlrev_b32_e32 v135, 16, v222
	v_and_b32_e32 v136, 0xffff0000, v222
	v_lshlrev_b32_e32 v137, 16, v223
	v_and_b32_e32 v138, 0xffff0000, v223
	v_fma_f32 v50, v135, s50, v50
	v_fma_f32 v51, v136, s50, v51
	v_fma_f32 v52, v137, s50, v52
	v_fma_f32 v53, v138, s50, v53
	global_store_dwordx4 v210, v[50:53], s[42:43]
	v_lshlrev_b32_e32 v135, 16, v224
	v_and_b32_e32 v136, 0xffff0000, v224
	v_lshlrev_b32_e32 v137, 16, v225
	v_and_b32_e32 v138, 0xffff0000, v225
	v_fma_f32 v54, v135, s50, v54
	v_fma_f32 v55, v136, s50, v55
	v_fma_f32 v56, v137, s50, v56
	v_fma_f32 v57, v138, s50, v57
	global_store_dwordx4 v210, v[54:57], s[42:43] offset:64
	s_waitcnt vmcnt(7)
	s_nop 0
	v_permlane16_swap_b32_e32 v226, v228
	v_permlane16_swap_b32_e32 v227, v229
	s_nop 1
	v_lshlrev_b32_e32 v135, 16, v226
	v_and_b32_e32 v136, 0xffff0000, v226
	v_lshlrev_b32_e32 v137, 16, v227
	v_and_b32_e32 v138, 0xffff0000, v227
	v_fma_f32 v58, v135, s50, v58
	v_fma_f32 v59, v136, s50, v59
	v_fma_f32 v60, v137, s50, v60
	v_fma_f32 v61, v138, s50, v61
	global_store_dwordx4 v211, v[58:61], s[42:43]
	v_lshlrev_b32_e32 v135, 16, v228
	v_and_b32_e32 v136, 0xffff0000, v228
	v_lshlrev_b32_e32 v137, 16, v229
	v_and_b32_e32 v138, 0xffff0000, v229
	v_fma_f32 v62, v135, s50, v62
	v_fma_f32 v63, v136, s50, v63
	v_fma_f32 v64, v137, s50, v64
	v_fma_f32 v65, v138, s50, v65
	global_store_dwordx4 v211, v[62:65], s[42:43] offset:64
	s_waitcnt vmcnt(4)
	s_nop 0
	v_permlane16_swap_b32_e32 v230, v232
	v_permlane16_swap_b32_e32 v231, v233
	s_nop 1
	s_mov_b64 exec, s[48:49]
	v_lshlrev_b32_e32 v135, 16, v230
	v_and_b32_e32 v136, 0xffff0000, v230
	v_lshlrev_b32_e32 v137, 16, v231
	v_and_b32_e32 v138, 0xffff0000, v231
	v_fma_f32 v66, v135, s50, v66
	v_fma_f32 v67, v136, s50, v67
	v_fma_f32 v68, v137, s50, v68
	v_fma_f32 v69, v138, s50, v69
	global_store_dwordx4 v213, v[66:69], s[42:43]
	v_lshlrev_b32_e32 v135, 16, v232
	v_and_b32_e32 v136, 0xffff0000, v232
	v_lshlrev_b32_e32 v137, 16, v233
	v_and_b32_e32 v138, 0xffff0000, v233
	v_fma_f32 v70, v135, s50, v70
	v_fma_f32 v71, v136, s50, v71
	v_fma_f32 v72, v137, s50, v72
	v_fma_f32 v73, v138, s50, v73
	global_store_dwordx4 v213, v[70:73], s[42:43] offset:64
	s_mov_b64 exec, s[98:99]
	s_add_u32 s0, s0, s96
	s_branch .Lg4_task

.LBB0_326:
	v_add_u32_e32 v0, s2, v34
	s_movk_i32 s0, 0x4400
	v_cmp_gt_i32_e32 vcc, s0, v0
	v_ashrrev_i32_e32 v35, 31, v34
	v_lshlrev_b64 v[36:37], 12, v[34:35]
	v_cndmask_b32_e32 v54, v34, v0, vcc
	v_ashrrev_i32_e32 v55, 31, v54
	v_lshlrev_b64 v[38:39], 12, v[54:55]
	v_lshl_add_u64 v[48:49], v[50:51], 0, v[36:37]
	v_cmp_ne_u32_e32 vcc, v34, v54
	v_lshlrev_b64 v[34:35], 11, v[34:35]
	s_waitcnt lgkmcnt(0)
	v_lshl_add_u64 v[42:43], v[50:51], 0, v[38:39]
	v_lshl_add_u64 v[56:57], v[52:53], 0, v[34:35]
	global_load_dwordx4 v[34:37], v[48:49], off offset:3072
	global_load_dwordx4 v[38:41], v[48:49], off offset:2048
	s_waitcnt vmcnt(0)
	v_mov_b32_e32 v45, v34
	s_waitcnt vmcnt(0)
	v_mov_b32_e32 v44, v38
	v_mov_b32_e32 v46, v39
	v_mov_b32_e32 v47, v35
	v_pk_add_f32 v[44:45], v[44:45], v[46:47]
	v_mov_b32_e32 v46, v40
	v_mov_b32_e32 v47, v36
	v_pk_add_f32 v[44:45], v[44:45], v[46:47]
	v_mov_b32_e32 v46, v41
	v_mov_b32_e32 v47, v37
	v_pk_add_f32 v[62:63], v[44:45], v[46:47]
	global_load_dwordx4 v[44:47], v[48:49], off offset:1024
	global_load_dwordx4 v[58:61], v[48:49], off
	s_waitcnt vmcnt(1)
	v_mov_b32_e32 v49, v44
	s_waitcnt vmcnt(0)
	v_mov_b32_e32 v48, v58
	v_mov_b32_e32 v64, v59
	v_mov_b32_e32 v65, v45
	v_pk_add_f32 v[48:49], v[48:49], v[64:65]
	v_mov_b32_e32 v64, v60
	v_mov_b32_e32 v65, v46
	v_pk_add_f32 v[48:49], v[48:49], v[64:65]
	v_mov_b32_e32 v64, v61
	v_mov_b32_e32 v65, v47
	v_pk_add_f32 v[48:49], v[48:49], v[64:65]
	s_nop 0
	v_add_f32_e32 v48, 0, v48
	v_add_f32_e32 v48, v48, v49
	v_add_f32_e32 v48, v48, v62
	v_add_f32_e32 v48, v48, v63
	s_nop 1
	v_add_f32_dpp v48, v48, v48 quad_perm:[1,0,3,2] row_mask:0xf bank_mask:0xf bound_ctrl:1
	s_nop 1
	v_add_f32_dpp v48, v48, v48 quad_perm:[2,3,0,1] row_mask:0xf bank_mask:0xf bound_ctrl:1
	s_nop 1
	v_add_f32_dpp v48, v48, v48 row_half_mirror row_mask:0xf bank_mask:0xf bound_ctrl:1
	s_nop 1
	v_add_f32_dpp v48, v48, v48 row_mirror row_mask:0xf bank_mask:0xf bound_ctrl:1
	v_mov_b32_e32 v49, v48
	v_mov_b32_e32 v255, v48
	s_nop 1
	v_permlane16_swap_b32_e32 v49, v255
	s_nop 1
	v_add_f32_e32 v48, v49, v255
	v_mov_b32_e32 v49, v48
	v_mov_b32_e32 v255, v48
	s_nop 1
	v_permlane32_swap_b32_e32 v49, v255
	s_nop 1
	v_add_f32_e32 v48, v49, v255
	v_mul_f32_e32 v48, 0x3a800000, v48
	v_pk_add_f32 v[58:59], v[58:59], v[48:49] op_sel_hi:[1,0] neg_lo:[0,1] neg_hi:[0,1]
	v_pk_add_f32 v[44:45], v[44:45], v[48:49] op_sel_hi:[1,0] neg_lo:[0,1] neg_hi:[0,1]
	v_mov_b32_e32 v64, v59
	v_mov_b32_e32 v65, v45
	v_pk_add_f32 v[60:61], v[60:61], v[48:49] op_sel_hi:[1,0] neg_lo:[0,1] neg_hi:[0,1]
	v_pk_add_f32 v[46:47], v[46:47], v[48:49] op_sel_hi:[1,0] neg_lo:[0,1] neg_hi:[0,1]
	v_mov_b32_e32 v62, v58
	v_mov_b32_e32 v63, v44
	v_pk_mul_f32 v[64:65], v[64:65], v[64:65]
	v_pk_add_f32 v[38:39], v[38:39], v[48:49] op_sel_hi:[1,0] neg_lo:[0,1] neg_hi:[0,1]
	v_pk_fma_f32 v[62:63], v[62:63], v[62:63], v[64:65]
	v_mov_b32_e32 v64, v60
	v_mov_b32_e32 v65, v46
	v_pk_fma_f32 v[62:63], v[64:65], v[64:65], v[62:63]
	v_mov_b32_e32 v64, v61
	v_mov_b32_e32 v65, v47
	v_pk_add_f32 v[34:35], v[34:35], v[48:49] op_sel_hi:[1,0] neg_lo:[0,1] neg_hi:[0,1]
	v_pk_fma_f32 v[62:63], v[64:65], v[64:65], v[62:63]
	v_mov_b32_e32 v64, v35
	v_mov_b32_e32 v65, v39
	v_pk_add_f32 v[40:41], v[40:41], v[48:49] op_sel_hi:[1,0] neg_lo:[0,1] neg_hi:[0,1]
	v_pk_add_f32 v[36:37], v[36:37], v[48:49] op_sel_hi:[1,0] neg_lo:[0,1] neg_hi:[0,1]
	v_mov_b32_e32 v48, v34
	v_mov_b32_e32 v49, v38
	v_pk_mul_f32 v[64:65], v[64:65], v[64:65]
	v_add_f32_e32 v62, v62, v63
	v_pk_fma_f32 v[48:49], v[48:49], v[48:49], v[64:65]
	v_mov_b32_e32 v64, v36
	v_mov_b32_e32 v65, v40
	v_pk_fma_f32 v[48:49], v[64:65], v[64:65], v[48:49]
	v_mov_b32_e32 v64, v37
	v_mov_b32_e32 v65, v41
	v_pk_fma_f32 v[48:49], v[64:65], v[64:65], v[48:49]
	s_nop 0
	v_add_f32_e32 v49, v49, v62
	v_add_f32_e32 v48, v48, v49
	s_nop 1
	v_add_f32_dpp v48, v48, v48 quad_perm:[1,0,3,2] row_mask:0xf bank_mask:0xf bound_ctrl:1
	s_nop 1
	v_add_f32_dpp v48, v48, v48 quad_perm:[2,3,0,1] row_mask:0xf bank_mask:0xf bound_ctrl:1
	s_nop 1
	v_add_f32_dpp v48, v48, v48 row_half_mirror row_mask:0xf bank_mask:0xf bound_ctrl:1
	s_nop 1
	v_add_f32_dpp v48, v48, v48 row_mirror row_mask:0xf bank_mask:0xf bound_ctrl:1
	v_mov_b32_e32 v49, v48
	v_mov_b32_e32 v255, v48
	s_nop 1
	v_permlane16_swap_b32_e32 v49, v255
	s_nop 1
	v_add_f32_e32 v48, v49, v255
	v_mov_b32_e32 v49, v48
	v_mov_b32_e32 v255, v48
	s_nop 1
	v_permlane32_swap_b32_e32 v49, v255
	s_nop 1
	v_add_f32_e32 v48, v49, v255
	v_fmamk_f32 v48, v48, 0x3a800000, v122
	v_cmp_gt_f32_e64 s[0:1], s84, v48
	v_mul_f32_e32 v49, 0x4b800000, v48
	s_nop 0
	v_cndmask_b32_e64 v48, v48, v49, s[0:1]
	v_rsq_f32_e32 v48, v48
	s_nop 0
	v_mul_f32_e32 v49, 0x45800000, v48
	v_cndmask_b32_e64 v48, v48, v49, s[0:1]
	v_pk_mul_f32 v[38:39], v[38:39], v[48:49] op_sel_hi:[1,0]
	v_pk_mul_f32 v[40:41], v[40:41], v[48:49] op_sel_hi:[1,0]
	v_pk_mul_f32 v[34:35], v[34:35], v[48:49] op_sel_hi:[1,0]
	v_pk_mul_f32 v[36:37], v[36:37], v[48:49] op_sel_hi:[1,0]
	v_pk_fma_f32 v[38:39], v[18:19], v[38:39], v[26:27]
	v_pk_fma_f32 v[40:41], v[20:21], v[40:41], v[28:29]
	v_pk_fma_f32 v[34:35], v[22:23], v[34:35], v[30:31]
	v_pk_fma_f32 v[36:37], v[24:25], v[36:37], v[32:33]
	v_cvt_pk_bf16_f32 v62, v38, v39
	v_cvt_pk_bf16_f32 v63, v40, v41
	v_cvt_pk_bf16_f32 v64, v34, v35
	v_cvt_pk_bf16_f32 v65, v36, v37
	global_load_dwordx4 v[38:41], v[42:43], off
	global_load_dwordx4 v[34:37], v[42:43], off offset:1024
	v_pk_mul_f32 v[58:59], v[58:59], v[48:49] op_sel_hi:[1,0]
	v_pk_mul_f32 v[60:61], v[60:61], v[48:49] op_sel_hi:[1,0]
	v_pk_mul_f32 v[44:45], v[44:45], v[48:49] op_sel_hi:[1,0]
	v_pk_mul_f32 v[46:47], v[46:47], v[48:49] op_sel_hi:[1,0]
	v_pk_fma_f32 v[58:59], v[2:3], v[58:59], v[10:11]
	v_pk_fma_f32 v[60:61], v[4:5], v[60:61], v[12:13]
	v_pk_fma_f32 v[44:45], v[6:7], v[44:45], v[14:15]
	v_pk_fma_f32 v[46:47], v[8:9], v[46:47], v[16:17]
	v_cvt_pk_bf16_f32 v58, v58, v59
	v_cvt_pk_bf16_f32 v59, v60, v61
	v_cvt_pk_bf16_f32 v60, v44, v45
	v_cvt_pk_bf16_f32 v61, v46, v47
	s_waitcnt vmcnt(1)
	v_mov_b32_e32 v44, v38
	s_waitcnt vmcnt(0)
	v_mov_b32_e32 v45, v34
	v_mov_b32_e32 v46, v39
	v_mov_b32_e32 v47, v35
	v_pk_add_f32 v[44:45], v[44:45], v[46:47]
	v_mov_b32_e32 v46, v40
	v_mov_b32_e32 v47, v36
	v_pk_add_f32 v[44:45], v[44:45], v[46:47]
	v_mov_b32_e32 v46, v41
	v_mov_b32_e32 v47, v37
	v_pk_add_f32 v[44:45], v[44:45], v[46:47]
	s_nop 0
	v_add_f32_e32 v44, 0, v44
	v_add_f32_e32 v72, v44, v45
	global_load_dwordx4 v[46:49], v[42:43], off offset:2048
	s_nop 0
	global_load_dwordx4 v[42:45], v[42:43], off offset:3072
	s_nop 0
	global_store_dwordx2 v[56:57], v[58:59], off
	global_store_dwordx2 v[56:57], v[60:61], off offset:512
	global_store_dwordx2 v[56:57], v[62:63], off offset:1024
	global_store_dwordx2 v[56:57], v[64:65], off offset:1536
	s_waitcnt vmcnt(5)
	v_mov_b32_e32 v68, v46
	s_waitcnt vmcnt(4)
	v_mov_b32_e32 v69, v42
	v_mov_b32_e32 v70, v47
	v_mov_b32_e32 v71, v43
	v_pk_add_f32 v[68:69], v[68:69], v[70:71]
	v_mov_b32_e32 v70, v48
	v_mov_b32_e32 v71, v44
	v_pk_add_f32 v[68:69], v[68:69], v[70:71]
	v_mov_b32_e32 v70, v49
	v_mov_b32_e32 v71, v45
	v_pk_add_f32 v[68:69], v[68:69], v[70:71]
	s_nop 0
	v_add_f32_e32 v68, v72, v68
	v_add_f32_e32 v56, v68, v69
	s_nop 1
	v_add_f32_dpp v56, v56, v56 quad_perm:[1,0,3,2] row_mask:0xf bank_mask:0xf bound_ctrl:1
	s_nop 1
	v_add_f32_dpp v56, v56, v56 quad_perm:[2,3,0,1] row_mask:0xf bank_mask:0xf bound_ctrl:1
	s_nop 1
	v_add_f32_dpp v56, v56, v56 row_half_mirror row_mask:0xf bank_mask:0xf bound_ctrl:1
	s_nop 1
	v_add_f32_dpp v56, v56, v56 row_mirror row_mask:0xf bank_mask:0xf bound_ctrl:1
	v_mov_b32_e32 v57, v56
	v_mov_b32_e32 v255, v56
	s_nop 1
	v_permlane16_swap_b32_e32 v57, v255
	s_nop 1
	v_add_f32_e32 v56, v57, v255
	v_mov_b32_e32 v57, v56
	v_mov_b32_e32 v255, v56
	s_nop 1
	v_permlane32_swap_b32_e32 v57, v255
	s_nop 1
	v_add_f32_e32 v56, v57, v255
	v_mul_f32_e32 v64, 0x3a800000, v56
	v_pk_add_f32 v[62:63], v[38:39], v[64:65] op_sel_hi:[1,0] neg_lo:[0,1] neg_hi:[0,1]
	v_pk_add_f32 v[58:59], v[34:35], v[64:65] op_sel_hi:[1,0] neg_lo:[0,1] neg_hi:[0,1]
	v_pk_add_f32 v[60:61], v[40:41], v[64:65] op_sel_hi:[1,0] neg_lo:[0,1] neg_hi:[0,1]
	v_pk_mul_f32 v[68:69], v[62:63], v[62:63]
	v_pk_add_f32 v[56:57], v[36:37], v[64:65] op_sel_hi:[1,0] neg_lo:[0,1] neg_hi:[0,1]
	v_pk_mul_f32 v[72:73], v[58:59], v[58:59]
	v_pk_add_f32 v[40:41], v[46:47], v[64:65] op_sel_hi:[1,0] neg_lo:[0,1] neg_hi:[0,1]
	v_pk_mul_f32 v[70:71], v[60:61], v[60:61]
	v_pk_mul_f32 v[74:75], v[56:57], v[56:57]
	v_pk_add_f32 v[38:39], v[48:49], v[64:65] op_sel_hi:[1,0] neg_lo:[0,1] neg_hi:[0,1]
	v_pk_mul_f32 v[46:47], v[40:41], v[40:41]
	v_pk_add_f32 v[36:37], v[42:43], v[64:65] op_sel_hi:[1,0] neg_lo:[0,1] neg_hi:[0,1]
	v_pk_add_f32 v[34:35], v[44:45], v[64:65] op_sel_hi:[1,0] neg_lo:[0,1] neg_hi:[0,1]
	v_add_f32_e32 v64, v72, v73
	v_add_f32_e32 v65, v68, v69
	v_pk_mul_f32 v[48:49], v[38:39], v[38:39]
	v_pk_mul_f32 v[42:43], v[36:37], v[36:37]
	v_add_f32_e32 v64, v74, v64
	v_add_f32_e32 v65, v70, v65
	v_add_f32_e32 v46, v46, v47
	v_pk_mul_f32 v[44:45], v[34:35], v[34:35]
	v_add_f32_e32 v64, v75, v64
	v_add_f32_e32 v65, v71, v65
	v_add_f32_e32 v46, v48, v46
	v_add_f32_e32 v42, v42, v43
	v_add_f32_e32 v64, v65, v64
	v_add_f32_e32 v46, v49, v46
	v_add_f32_e32 v42, v44, v42
	v_add_f32_e32 v46, v46, v64
	v_add_f32_e32 v42, v45, v42
	v_add_f32_e32 v42, v42, v46
	s_nop 1
	v_add_f32_dpp v42, v42, v42 quad_perm:[1,0,3,2] row_mask:0xf bank_mask:0xf bound_ctrl:1
	s_nop 1
	v_add_f32_dpp v42, v42, v42 quad_perm:[2,3,0,1] row_mask:0xf bank_mask:0xf bound_ctrl:1
	s_nop 1
	v_add_f32_dpp v42, v42, v42 row_half_mirror row_mask:0xf bank_mask:0xf bound_ctrl:1
	s_nop 1
	v_add_f32_dpp v42, v42, v42 row_mirror row_mask:0xf bank_mask:0xf bound_ctrl:1
	ds_bpermute_b32 v43, v66, v42
	s_waitcnt lgkmcnt(0)
	v_add_f32_e32 v42, v42, v43
	ds_bpermute_b32 v43, v67, v42
	s_and_saveexec_b64 s[0:1], vcc
	s_cbranch_execz .LBB0_325
	s_waitcnt lgkmcnt(0)
	v_add_f32_e32 v42, v42, v43
	v_fmamk_f32 v42, v42, 0x3a800000, v122
	v_mul_f32_e32 v43, 0x4b800000, v42
	v_cmp_gt_f32_e32 vcc, s84, v42
	s_nop 1
	v_cndmask_b32_e32 v42, v42, v43, vcc
	v_rsq_f32_e32 v44, v42
	v_lshlrev_b64 v[42:43], 11, v[54:55]
	v_lshl_add_u64 v[42:43], v[52:53], 0, v[42:43]
	v_mul_f32_e32 v45, 0x45800000, v44
	v_cndmask_b32_e32 v44, v44, v45, vcc
	v_pk_mul_f32 v[46:47], v[62:63], v[44:45] op_sel_hi:[1,0]
	v_pk_mul_f32 v[48:49], v[60:61], v[44:45] op_sel_hi:[1,0]
	v_pk_fma_f32 v[46:47], v[2:3], v[46:47], v[10:11]
	v_pk_fma_f32 v[48:49], v[4:5], v[48:49], v[12:13]
	v_cvt_pk_bf16_f32 v46, v46, v47
	v_cvt_pk_bf16_f32 v47, v48, v49
	global_store_dwordx2 v[42:43], v[46:47], off
	v_pk_mul_f32 v[46:47], v[58:59], v[44:45] op_sel_hi:[1,0]
	v_pk_mul_f32 v[48:49], v[56:57], v[44:45] op_sel_hi:[1,0]
	v_pk_mul_f32 v[40:41], v[40:41], v[44:45] op_sel_hi:[1,0]
	v_pk_mul_f32 v[38:39], v[38:39], v[44:45] op_sel_hi:[1,0]
	v_pk_mul_f32 v[36:37], v[36:37], v[44:45] op_sel_hi:[1,0]
	v_pk_mul_f32 v[34:35], v[34:35], v[44:45] op_sel_hi:[1,0]
	v_pk_fma_f32 v[46:47], v[6:7], v[46:47], v[14:15]
	v_pk_fma_f32 v[48:49], v[8:9], v[48:49], v[16:17]
	v_pk_fma_f32 v[40:41], v[18:19], v[40:41], v[26:27]
	v_pk_fma_f32 v[38:39], v[20:21], v[38:39], v[28:29]
	v_pk_fma_f32 v[36:37], v[22:23], v[36:37], v[30:31]
	v_pk_fma_f32 v[34:35], v[24:25], v[34:35], v[32:33]
	v_cvt_pk_bf16_f32 v46, v46, v47
	v_cvt_pk_bf16_f32 v47, v48, v49
	v_cvt_pk_bf16_f32 v40, v40, v41
	v_cvt_pk_bf16_f32 v41, v38, v39
	v_cvt_pk_bf16_f32 v36, v36, v37
	v_cvt_pk_bf16_f32 v37, v34, v35
	global_store_dwordx2 v[42:43], v[46:47], off offset:512
	global_store_dwordx2 v[42:43], v[40:41], off offset:1024
	global_store_dwordx2 v[42:43], v[36:37], off offset:1536
	s_branch .LBB0_325

.LBB0_330:
	s_andn2_b64 vcc, exec, s[0:1]
	s_cbranch_vccnz .LBB0_342
	v_and_b32_e32 v135, 63, v144
	v_lshrrev_b32_e32 v136, 6, v144
	v_lshlrev_b32_e32 v0, 10, v136
	s_nop 0
	v_readfirstlane_b32 s44, v0
	v_lshrrev_b32_e32 v137, 3, v135
	v_lshl_add_u32 v137, v136, 3, v137
	v_lshrrev_b32_e32 v138, 1, v137
	v_xor_b32_e32 v138, v138, v135
	v_and_b32_e32 v138, 7, v138
	v_lshlrev_b32_e32 v138, 4, v138
	s_movk_i32 s1, 0x2000
	s_movk_i32 s2, 0x800
	v_add_u32_e32 v139, 0, v137
	v_mul_lo_u32 v114, v139, s1
	v_add_u32_e32 v114, v114, v138
	v_mul_lo_u32 v119, v139, s2
	v_add_u32_e32 v119, v119, v138
	v_add_u32_e32 v139, 32, v137
	v_mul_lo_u32 v115, v139, s1
	v_add_u32_e32 v115, v115, v138
	v_mul_lo_u32 v120, v139, s2
	v_add_u32_e32 v120, v120, v138
	v_add_u32_e32 v139, 64, v137
	v_mul_lo_u32 v116, v139, s1
	v_add_u32_e32 v116, v116, v138
	v_mul_lo_u32 v121, v139, s2
	v_add_u32_e32 v121, v121, v138
	v_add_u32_e32 v139, 96, v137
	v_mul_lo_u32 v117, v139, s1
	v_add_u32_e32 v117, v117, v138
	v_mul_lo_u32 v126, v139, s2
	v_add_u32_e32 v126, v126, v138
	v_add_u32_e32 v139, 128, v137
	v_mul_lo_u32 v118, v139, s1
	v_add_u32_e32 v118, v118, v138
	v_and_b32_e32 v139, 15, v135
	v_lshrrev_b32_e32 v140, 4, v135
	v_lshrrev_b32_e32 v141, 1, v136
	v_and_b32_e32 v142, 1, v136
	v_bfe_u32 v143, v135, 1, 3
	v_add_u32_e32 v138, 0, v140
	v_xor_b32_e32 v138, v138, v143
	v_lshlrev_b32_e32 v138, 4, v138
	v_lshl_add_u32 v133, v139, 7, v138
	v_lshl_add_u32 v127, v141, 13, v133
	v_lshl_add_u32 v129, v142, 13, v133
	v_add_u32_e32 v129, 0x4000, v129
	v_add_u32_e32 v133, 0x8000, v133
	v_lshl_add_u32 v131, v141, 12, v129
	v_mov_b32_e32 v0, v131
	v_xor_b32_e32 v137, 1, v141
	v_lshl_add_u32 v131, v137, 12, v129
	v_mov_b32_e32 v129, v0
	v_add_u32_e32 v138, 4, v140
	v_xor_b32_e32 v138, v138, v143
	v_lshlrev_b32_e32 v138, 4, v138
	v_lshl_add_u32 v134, v139, 7, v138
	v_lshl_add_u32 v128, v141, 13, v134
	v_lshl_add_u32 v130, v142, 13, v134
	v_add_u32_e32 v130, 0x4000, v130
	v_add_u32_e32 v134, 0x8000, v134
	v_lshl_add_u32 v132, v141, 12, v130
	v_mov_b32_e32 v0, v132
	v_xor_b32_e32 v137, 1, v141
	v_lshl_add_u32 v132, v137, 12, v130
	v_mov_b32_e32 v130, v0
	v_lshl_add_u32 v135, v141, 6, v139
	v_lshlrev_b32_e32 v136, 2, v140
	v_lshl_add_u32 v136, v142, 6, v136
	v_lshl_add_u32 v138, v137, 5, v136
	v_lshl_add_u32 v136, v141, 5, v136
	v_add_u32_e32 v0, 0, v135
	v_lshlrev_b32_e32 v137, 11, v0
	v_lshl_add_u32 v196, v136, 1, v137
	v_lshl_add_u32 v197, v138, 1, v137
	v_lshlrev_b32_e32 v137, 12, v0
	v_lshl_add_u32 v204, v136, 2, v137
	v_lshl_add_u32 v205, v138, 2, v137
	v_add_u32_e32 v0, 16, v135
	v_lshlrev_b32_e32 v137, 11, v0
	v_lshl_add_u32 v198, v136, 1, v137
	v_lshl_add_u32 v199, v138, 1, v137
	v_lshlrev_b32_e32 v137, 12, v0
	v_lshl_add_u32 v206, v136, 2, v137
	v_lshl_add_u32 v207, v138, 2, v137
	v_add_u32_e32 v0, 32, v135
	v_lshlrev_b32_e32 v137, 11, v0
	v_lshl_add_u32 v200, v136, 1, v137
	v_lshl_add_u32 v201, v138, 1, v137
	v_lshlrev_b32_e32 v137, 12, v0
	v_lshl_add_u32 v208, v136, 2, v137
	v_lshl_add_u32 v209, v138, 2, v137
	v_add_u32_e32 v0, 48, v135
	v_lshlrev_b32_e32 v137, 11, v0
	v_lshl_add_u32 v202, v136, 1, v137
	v_lshl_add_u32 v203, v138, 1, v137
	v_lshlrev_b32_e32 v137, 12, v0
	v_lshl_add_u32 v210, v136, 2, v137
	v_lshl_add_u32 v211, v138, 2, v137
	v_add_u32_e32 v0, 128, v139
	v_lshlrev_b32_e32 v137, 11, v0
	v_lshl_add_u32 v212, v136, 1, v137
	v_lshlrev_b32_e32 v137, 12, v0
	v_lshl_add_u32 v213, v136, 2, v137
	v_and_b32_e32 v137, 1, v140
	v_lshlrev_b32_e32 v137, 4, v137
	v_lshrrev_b32_e32 v0, 1, v140
	v_lshl_add_u32 v137, v0, 3, v137
	v_lshlrev_b32_e32 v0, 2, v140
	v_sub_u32_e32 v137, v137, v0
	v_lshlrev_b32_e32 v137, 1, v137
	v_add_u32_e32 v196, v196, v137
	v_add_u32_e32 v197, v197, v137
	v_add_u32_e32 v198, v198, v137
	v_add_u32_e32 v199, v199, v137
	v_add_u32_e32 v200, v200, v137
	v_add_u32_e32 v201, v201, v137
	v_add_u32_e32 v202, v202, v137
	v_add_u32_e32 v203, v203, v137
	v_add_u32_e32 v212, v212, v137
	v_cmp_gt_u32_e32 vcc, 8, v139
	s_nop 3
	s_mov_b64 s[48:49], vcc
	s_mov_b32 s50, 0x3fb504f3
	s_mov_b32 s0, s91

.Lg2_last_join:
	s_setprio 0
	s_waitcnt lgkmcnt(9)
	v_mfma_f32_16x16x32_bf16 v[2:5], v[164:167], v[74:77], v[2:5]
	v_mfma_f32_16x16x32_bf16 v[6:9], v[168:171], v[74:77], v[6:9]
	v_mfma_f32_16x16x32_bf16 v[10:13], v[172:175], v[74:77], v[10:13]
	v_mfma_f32_16x16x32_bf16 v[14:17], v[176:179], v[74:77], v[14:17]
	v_mfma_f32_16x16x32_bf16 v[18:21], v[164:167], v[78:81], v[18:21]
	v_mfma_f32_16x16x32_bf16 v[22:25], v[168:171], v[78:81], v[22:25]
	v_mfma_f32_16x16x32_bf16 v[26:29], v[172:175], v[78:81], v[26:29]
	v_mfma_f32_16x16x32_bf16 v[30:33], v[176:179], v[78:81], v[30:33]
	v_mfma_f32_16x16x32_bf16 v[34:37], v[164:167], v[82:85], v[34:37]
	v_mfma_f32_16x16x32_bf16 v[38:41], v[168:171], v[82:85], v[38:41]
	v_mfma_f32_16x16x32_bf16 v[42:45], v[172:175], v[82:85], v[42:45]
	v_mfma_f32_16x16x32_bf16 v[46:49], v[176:179], v[82:85], v[46:49]
	v_mfma_f32_16x16x32_bf16 v[50:53], v[164:167], v[86:89], v[50:53]
	v_mfma_f32_16x16x32_bf16 v[54:57], v[168:171], v[86:89], v[54:57]
	v_mfma_f32_16x16x32_bf16 v[58:61], v[172:175], v[86:89], v[58:61]
	v_mfma_f32_16x16x32_bf16 v[62:65], v[176:179], v[86:89], v[62:65]
	v_mfma_f32_16x16x32_bf16 v[66:69], v[164:167], v[106:109], v[66:69]
	v_mfma_f32_16x16x32_bf16 v[70:73], v[168:171], v[106:109], v[70:73]
	s_waitcnt lgkmcnt(0)
	v_mfma_f32_16x16x32_bf16 v[2:5], v[180:183], v[90:93], v[2:5]
	v_mfma_f32_16x16x32_bf16 v[6:9], v[184:187], v[90:93], v[6:9]
	v_mfma_f32_16x16x32_bf16 v[10:13], v[188:191], v[90:93], v[10:13]
	v_mfma_f32_16x16x32_bf16 v[14:17], v[192:195], v[90:93], v[14:17]
	v_mfma_f32_16x16x32_bf16 v[18:21], v[180:183], v[94:97], v[18:21]
	v_mfma_f32_16x16x32_bf16 v[22:25], v[184:187], v[94:97], v[22:25]
	v_mfma_f32_16x16x32_bf16 v[26:29], v[188:191], v[94:97], v[26:29]
	v_mfma_f32_16x16x32_bf16 v[30:33], v[192:195], v[94:97], v[30:33]
	v_mfma_f32_16x16x32_bf16 v[34:37], v[180:183], v[98:101], v[34:37]
	v_mfma_f32_16x16x32_bf16 v[38:41], v[184:187], v[98:101], v[38:41]
	v_mfma_f32_16x16x32_bf16 v[42:45], v[188:191], v[98:101], v[42:45]
	v_mfma_f32_16x16x32_bf16 v[46:49], v[192:195], v[98:101], v[46:49]
	v_mfma_f32_16x16x32_bf16 v[50:53], v[180:183], v[102:105], v[50:53]
	v_mfma_f32_16x16x32_bf16 v[54:57], v[184:187], v[102:105], v[54:57]
	v_mfma_f32_16x16x32_bf16 v[58:61], v[188:191], v[102:105], v[58:61]
	v_mfma_f32_16x16x32_bf16 v[62:65], v[192:195], v[102:105], v[62:65]
	v_mfma_f32_16x16x32_bf16 v[66:69], v[180:183], v[110:113], v[66:69]
	v_mfma_f32_16x16x32_bf16 v[70:73], v[184:187], v[110:113], v[70:73]
	s_add_u32 s45, s45, 1
	s_cmpk_lt_u32 s45, 8
	s_cbranch_scc1 .Lg2_kloop
	s_nop 7
	s_nop 7
	global_load_dwordx4 v[214:217], v196, s[40:41]
	global_load_dwordx4 v[218:221], v197, s[40:41]
	global_load_dwordx4 v[222:225], v198, s[40:41]
	global_load_dwordx4 v[226:229], v199, s[40:41]
	s_waitcnt vmcnt(3)
	s_nop 0
	v_permlane16_swap_b32_e32 v214, v216
	v_permlane16_swap_b32_e32 v215, v217
	s_nop 1
	v_lshlrev_b32_e32 v135, 16, v214
	v_and_b32_e32 v136, 0xffff0000, v214
	v_lshlrev_b32_e32 v137, 16, v215
	v_and_b32_e32 v138, 0xffff0000, v215
	v_fma_f32 v2, v135, s50, v2
	v_fma_f32 v3, v136, s50, v3
	v_fma_f32 v4, v137, s50, v4
	v_fma_f32 v5, v138, s50, v5
	global_store_dwordx4 v204, v[2:5], s[42:43]
	v_lshlrev_b32_e32 v135, 16, v216
	v_and_b32_e32 v136, 0xffff0000, v216
	v_lshlrev_b32_e32 v137, 16, v217
	v_and_b32_e32 v138, 0xffff0000, v217
	v_fma_f32 v6, v135, s50, v6
	v_fma_f32 v7, v136, s50, v7
	v_fma_f32 v8, v137, s50, v8
	v_fma_f32 v9, v138, s50, v9
	global_store_dwordx4 v204, v[6:9], s[42:43] offset:64
	s_waitcnt vmcnt(4)
	s_nop 0
	v_permlane16_swap_b32_e32 v218, v220
	v_permlane16_swap_b32_e32 v219, v221
	s_nop 1
	v_lshlrev_b32_e32 v135, 16, v218
	v_and_b32_e32 v136, 0xffff0000, v218
	v_lshlrev_b32_e32 v137, 16, v219
	v_and_b32_e32 v138, 0xffff0000, v219
	v_fma_f32 v10, v135, s50, v10
	v_fma_f32 v11, v136, s50, v11
	v_fma_f32 v12, v137, s50, v12
	v_fma_f32 v13, v138, s50, v13
	global_store_dwordx4 v205, v[10:13], s[42:43]
	v_lshlrev_b32_e32 v135, 16, v220
	v_and_b32_e32 v136, 0xffff0000, v220
	v_lshlrev_b32_e32 v137, 16, v221
	v_and_b32_e32 v138, 0xffff0000, v221
	v_fma_f32 v14, v135, s50, v14
	v_fma_f32 v15, v136, s50, v15
	v_fma_f32 v16, v137, s50, v16
	v_fma_f32 v17, v138, s50, v17
	global_store_dwordx4 v205, v[14:17], s[42:43] offset:64
	global_load_dwordx4 v[214:217], v200, s[40:41]
	global_load_dwordx4 v[218:221], v201, s[40:41]
	s_waitcnt vmcnt(7)
	s_nop 0
	v_permlane16_swap_b32_e32 v222, v224
	v_permlane16_swap_b32_e32 v223, v225
	s_nop 1
	v_lshlrev_b32_e32 v135, 16, v222
	v_and_b32_e32 v136, 0xffff0000, v222
	v_lshlrev_b32_e32 v137, 16, v223
	v_and_b32_e32 v138, 0xffff0000, v223
	v_fma_f32 v18, v135, s50, v18
	v_fma_f32 v19, v136, s50, v19
	v_fma_f32 v20, v137, s50, v20
	v_fma_f32 v21, v138, s50, v21
	global_store_dwordx4 v206, v[18:21], s[42:43]
	v_lshlrev_b32_e32 v135, 16, v224
	v_and_b32_e32 v136, 0xffff0000, v224
	v_lshlrev_b32_e32 v137, 16, v225
	v_and_b32_e32 v138, 0xffff0000, v225
	v_fma_f32 v22, v135, s50, v22
	v_fma_f32 v23, v136, s50, v23
	v_fma_f32 v24, v137, s50, v24
	v_fma_f32 v25, v138, s50, v25
	global_store_dwordx4 v206, v[22:25], s[42:43] offset:64
	s_waitcnt vmcnt(8)
	s_nop 0
	v_permlane16_swap_b32_e32 v226, v228
	v_permlane16_swap_b32_e32 v227, v229
	s_nop 1
	v_lshlrev_b32_e32 v135, 16, v226
	v_and_b32_e32 v136, 0xffff0000, v226
	v_lshlrev_b32_e32 v137, 16, v227
	v_and_b32_e32 v138, 0xffff0000, v227
	v_fma_f32 v26, v135, s50, v26
	v_fma_f32 v27, v136, s50, v27
	v_fma_f32 v28, v137, s50, v28
	v_fma_f32 v29, v138, s50, v29
	global_store_dwordx4 v207, v[26:29], s[42:43]
	v_lshlrev_b32_e32 v135, 16, v228
	v_and_b32_e32 v136, 0xffff0000, v228
	v_lshlrev_b32_e32 v137, 16, v229
	v_and_b32_e32 v138, 0xffff0000, v229
	v_fma_f32 v30, v135, s50, v30
	v_fma_f32 v31, v136, s50, v31
	v_fma_f32 v32, v137, s50, v32
	v_fma_f32 v33, v138, s50, v33
	global_store_dwordx4 v207, v[30:33], s[42:43] offset:64
	global_load_dwordx4 v[222:225], v202, s[40:41]
	global_load_dwordx4 v[226:229], v203, s[40:41]
	s_waitcnt vmcnt(7)
	s_nop 0
	v_permlane16_swap_b32_e32 v214, v216
	v_permlane16_swap_b32_e32 v215, v217
	s_nop 1
	v_lshlrev_b32_e32 v135, 16, v214
	v_and_b32_e32 v136, 0xffff0000, v214
	v_lshlrev_b32_e32 v137, 16, v215
	v_and_b32_e32 v138, 0xffff0000, v215
	v_fma_f32 v34, v135, s50, v34
	v_fma_f32 v35, v136, s50, v35
	v_fma_f32 v36, v137, s50, v36
	v_fma_f32 v37, v138, s50, v37
	global_store_dwordx4 v208, v[34:37], s[42:43]
	v_lshlrev_b32_e32 v135, 16, v216
	v_and_b32_e32 v136, 0xffff0000, v216
	v_lshlrev_b32_e32 v137, 16, v217
	v_and_b32_e32 v138, 0xffff0000, v217
	v_fma_f32 v38, v135, s50, v38
	v_fma_f32 v39, v136, s50, v39
	v_fma_f32 v40, v137, s50, v40
	v_fma_f32 v41, v138, s50, v41
	global_store_dwordx4 v208, v[38:41], s[42:43] offset:64
	s_waitcnt vmcnt(8)
	s_nop 0
	v_permlane16_swap_b32_e32 v218, v220
	v_permlane16_swap_b32_e32 v219, v221
	s_nop 1
	v_lshlrev_b32_e32 v135, 16, v218
	v_and_b32_e32 v136, 0xffff0000, v218
	v_lshlrev_b32_e32 v137, 16, v219
	v_and_b32_e32 v138, 0xffff0000, v219
	v_fma_f32 v42, v135, s50, v42
	v_fma_f32 v43, v136, s50, v43
	v_fma_f32 v44, v137, s50, v44
	v_fma_f32 v45, v138, s50, v45
	global_store_dwordx4 v209, v[42:45], s[42:43]
	v_lshlrev_b32_e32 v135, 16, v220
	v_and_b32_e32 v136, 0xffff0000, v220
	v_lshlrev_b32_e32 v137, 16, v221
	v_and_b32_e32 v138, 0xffff0000, v221
	v_fma_f32 v46, v135, s50, v46
	v_fma_f32 v47, v136, s50, v47
	v_fma_f32 v48, v137, s50, v48
	v_fma_f32 v49, v138, s50, v49
	global_store_dwordx4 v209, v[46:49], s[42:43] offset:64
	s_mov_b64 s[98:99], exec
	s_mov_b64 exec, s[48:49]
	global_load_dwordx4 v[230:233], v212, s[40:41]
	s_mov_b64 exec, s[98:99]
	s_waitcnt vmcnt(6)
	s_nop 0
	v_permlane16_swap_b32_e32 v222, v224
	v_permlane16_swap_b32_e32 v223, v225
	s_nop 1
	v_lshlrev_b32_e32 v135, 16, v222
	v_and_b32_e32 v136, 0xffff0000, v222
	v_lshlrev_b32_e32 v137, 16, v223
	v_and_b32_e32 v138, 0xffff0000, v223
	v_fma_f32 v50, v135, s50, v50
	v_fma_f32 v51, v136, s50, v51
	v_fma_f32 v52, v137, s50, v52
	v_fma_f32 v53, v138, s50, v53
	global_store_dwordx4 v210, v[50:53], s[42:43]
	v_lshlrev_b32_e32 v135, 16, v224
	v_and_b32_e32 v136, 0xffff0000, v224
	v_lshlrev_b32_e32 v137, 16, v225
	v_and_b32_e32 v138, 0xffff0000, v225
	v_fma_f32 v54, v135, s50, v54
	v_fma_f32 v55, v136, s50, v55
	v_fma_f32 v56, v137, s50, v56
	v_fma_f32 v57, v138, s50, v57
	global_store_dwordx4 v210, v[54:57], s[42:43] offset:64
	s_waitcnt vmcnt(7)
	s_nop 0
	v_permlane16_swap_b32_e32 v226, v228
	v_permlane16_swap_b32_e32 v227, v229
	s_nop 1
	v_lshlrev_b32_e32 v135, 16, v226
	v_and_b32_e32 v136, 0xffff0000, v226
	v_lshlrev_b32_e32 v137, 16, v227
	v_and_b32_e32 v138, 0xffff0000, v227
	v_fma_f32 v58, v135, s50, v58
	v_fma_f32 v59, v136, s50, v59
	v_fma_f32 v60, v137, s50, v60
	v_fma_f32 v61, v138, s50, v61
	global_store_dwordx4 v211, v[58:61], s[42:43]
	v_lshlrev_b32_e32 v135, 16, v228
	v_and_b32_e32 v136, 0xffff0000, v228
	v_lshlrev_b32_e32 v137, 16, v229
	v_and_b32_e32 v138, 0xffff0000, v229
	v_fma_f32 v62, v135, s50, v62
	v_fma_f32 v63, v136, s50, v63
	v_fma_f32 v64, v137, s50, v64
	v_fma_f32 v65, v138, s50, v65
	global_store_dwordx4 v211, v[62:65], s[42:43] offset:64
	s_waitcnt vmcnt(4)
	s_nop 0
	v_permlane16_swap_b32_e32 v230, v232
	v_permlane16_swap_b32_e32 v231, v233
	s_nop 1
	s_mov_b64 exec, s[48:49]
	v_lshlrev_b32_e32 v135, 16, v230
	v_and_b32_e32 v136, 0xffff0000, v230
	v_lshlrev_b32_e32 v137, 16, v231
	v_and_b32_e32 v138, 0xffff0000, v231
	v_fma_f32 v66, v135, s50, v66
	v_fma_f32 v67, v136, s50, v67
	v_fma_f32 v68, v137, s50, v68
	v_fma_f32 v69, v138, s50, v69
	global_store_dwordx4 v213, v[66:69], s[42:43]
	v_lshlrev_b32_e32 v135, 16, v232
	v_and_b32_e32 v136, 0xffff0000, v232
	v_lshlrev_b32_e32 v137, 16, v233
	v_and_b32_e32 v138, 0xffff0000, v233
	v_fma_f32 v70, v135, s50, v70
	v_fma_f32 v71, v136, s50, v71
	v_fma_f32 v72, v137, s50, v72
	v_fma_f32 v73, v138, s50, v73
	global_store_dwordx4 v213, v[70:73], s[42:43] offset:64
	s_mov_b64 exec, s[98:99]
	s_add_u32 s0, s0, s96
	s_branch .Lg2_task

.LBB0_350:
	v_add_u32_e32 v34, s2, v18
	s_movk_i32 s0, 0x4400
	v_cmp_gt_i32_e32 vcc, s0, v34
	v_mov_b32_e32 v9, v1
	v_ashrrev_i32_e32 v19, 31, v18
	v_cndmask_b32_e32 v20, v18, v34, vcc
	v_ashrrev_i32_e32 v21, 31, v20
	v_lshlrev_b64 v[10:11], 13, v[20:21]
	v_lshl_add_u64 v[12:13], s[30:31], 0, v[10:11]
	v_lshl_add_u64 v[10:11], v[12:13], 0, v[0:1]
	v_add_co_u32_e32 v16, vcc, 0x1000, v10
	s_mov_b64 s[0:1], 0x1200
	s_nop 0
	v_addc_co_u32_e32 v17, vcc, 0, v11, vcc
	v_lshl_add_u64 v[12:13], v[12:13], 0, v[8:9]
	v_cmp_ne_u32_e64 s[38:39], v18, v20
	v_lshlrev_b64 v[18:19], 13, v[18:19]
	v_lshl_add_u64 v[14:15], v[10:11], 0, s[0:1]
	global_load_dword v41, v[10:11], off offset:1536
	global_load_dword v42, v[16:17], off offset:512
	global_load_dword v40, v[10:11], off offset:1792
	global_load_dword v39, v[14:15], off offset:256
	global_load_dword v38, v[10:11], off offset:2048
	global_load_dword v37, v[14:15], off offset:512
	global_load_dword v36, v[10:11], off offset:2304
	s_waitcnt lgkmcnt(0)
	global_load_dword v35, v[14:15], off offset:768
	v_add_co_u32_e32 v16, vcc, s93, v12
	v_lshl_add_u64 v[20:21], s[30:31], 0, v[18:19]
	s_nop 0
	v_addc_co_u32_e32 v17, vcc, 0, v13, vcc
	v_lshl_add_u64 v[18:19], v[20:21], 0, v[8:9]
	v_add_co_u32_e32 v22, vcc, s93, v18
	v_lshl_add_u64 v[20:21], v[20:21], 0, v[0:1]
	s_nop 0
	v_addc_co_u32_e32 v23, vcc, 0, v19, vcc
	v_lshl_add_u64 v[26:27], v[20:21], 0, s[0:1]
	global_load_dwordx2 v[14:15], v[12:13], off offset:2560
	s_mov_b32 s4, 0x3c800000
	global_load_dwordx2 v[16:17], v[16:17], off offset:3088
	s_nop 0
	global_load_dwordx2 v[22:23], v[22:23], off offset:3088
	s_nop 0
	global_load_dwordx2 v[24:25], v[18:19], off offset:2560
	global_load_dword v9, v[26:27], off offset:768
	global_load_dword v30, v[20:21], off offset:2304
	global_load_dword v31, v[26:27], off offset:512
	global_load_dword v43, v[20:21], off offset:2048
	global_load_dword v46, v[26:27], off offset:256
	global_load_dword v47, v[20:21], off offset:1792
	v_add_co_u32_e32 v26, vcc, s93, v20
	s_brev_b32 s5, 60
	s_nop 0
	v_addc_co_u32_e32 v27, vcc, 0, v21, vcc
	global_load_dword v28, v[26:27], off offset:512
	s_nop 0
	global_load_dword v27, v[20:21], off offset:1536
	s_waitcnt vmcnt(0)
	v_lshlrev_b32_e32 v48, 16, v28
	s_waitcnt vmcnt(0)
	v_lshlrev_b32_e32 v26, 16, v27
	v_and_b32_e32 v27, 0xffff0000, v27
	v_and_b32_e32 v49, 0xffff0000, v28
	v_pk_mul_f32 v[28:29], v[26:27], v[26:27]
	s_nop 0
	v_add_f32_e32 v28, v28, v29
	s_nop 1
	v_add_f32_dpp v28, v28, v28 quad_perm:[1,0,3,2] row_mask:0xf bank_mask:0xf bound_ctrl:1
	s_nop 1
	v_add_f32_dpp v28, v28, v28 quad_perm:[2,3,0,1] row_mask:0xf bank_mask:0xf bound_ctrl:1
	s_nop 1
	v_add_f32_dpp v28, v28, v28 row_half_mirror row_mask:0xf bank_mask:0xf bound_ctrl:1
	s_nop 1
	v_add_f32_dpp v28, v28, v28 row_mirror row_mask:0xf bank_mask:0xf bound_ctrl:1
	v_mov_b32_e32 v29, v28
	v_mov_b32_e32 v255, v28
	s_nop 1
	v_permlane16_swap_b32_e32 v29, v255
	s_nop 1
	v_add_f32_e32 v28, v29, v255
	v_mov_b32_e32 v29, v28
	v_mov_b32_e32 v255, v28
	s_nop 1
	v_permlane32_swap_b32_e32 v29, v255
	s_nop 1
	v_add_f32_e32 v28, v29, v255
	v_fmamk_f32 v28, v28, 0x3c000000, v123
	v_cmp_gt_f32_e32 vcc, s84, v28
	v_mul_f32_e32 v29, 0x4b800000, v28
	s_nop 0
	v_cndmask_b32_e32 v28, v28, v29, vcc
	v_rsq_f32_e32 v28, v28
	s_nop 0
	v_mul_f32_e32 v29, 0x45800000, v28
	v_cndmask_b32_e32 v28, v28, v29, vcc
	v_mul_f32_e32 v29, 0xbfb8aa3b, v48
	v_pk_mul_f32 v[26:27], v[28:29], v[26:27] op_sel_hi:[0,1]
	v_mul_f32_e32 v28, 0xbfb8aa3b, v49
	v_exp_f32_e32 v44, v29
	v_exp_f32_e32 v45, v28
	v_pk_mul_f32 v[26:27], v[6:7], v[26:27]
	v_pk_add_f32 v[28:29], v[44:45], 1.0 op_sel_hi:[1,0]
	s_nop 0
	v_div_scale_f32 v44, s[0:1], v29, v29, v49
	v_rcp_f32_e32 v45, v44
	s_nop 0
	v_fma_f32 v50, -v44, v45, 1.0
	v_fmac_f32_e32 v45, v50, v45
	v_div_scale_f32 v50, vcc, v49, v29, v49
	v_mul_f32_e32 v51, v50, v45
	v_fma_f32 v52, -v44, v51, v50
	v_fmac_f32_e32 v51, v52, v45
	v_fma_f32 v44, -v44, v51, v50
	v_div_fmas_f32 v44, v44, v45, v51
	v_div_fixup_f32 v29, v44, v29, v49
	v_div_scale_f32 v44, s[0:1], v28, v28, v48
	v_rcp_f32_e32 v45, v44
	s_nop 0
	v_fma_f32 v49, -v44, v45, 1.0
	v_fmac_f32_e32 v45, v49, v45
	v_div_scale_f32 v49, vcc, v48, v28, v48
	v_mul_f32_e32 v50, v49, v45
	v_fma_f32 v51, -v44, v50, v49
	v_fmac_f32_e32 v50, v51, v45
	v_fma_f32 v44, -v44, v50, v49
	v_div_fmas_f32 v44, v44, v45, v50
	v_div_fixup_f32 v28, v44, v28, v48
	v_pk_mul_f32 v[26:27], v[28:29], v[26:27]
	s_nop 0
	v_cvt_pk_bf16_f32 v26, v26, v27
	global_store_dword v[20:21], v26, off offset:1536
	v_lshlrev_b32_e32 v26, 16, v47
	v_and_b32_e32 v27, 0xffff0000, v47
	v_lshlrev_b32_e32 v47, 16, v46
	v_and_b32_e32 v46, 0xffff0000, v46
	v_mul_f32_e32 v44, 0xbfb8aa3b, v47
	v_mul_f32_e32 v45, 0xbfb8aa3b, v46
	v_exp_f32_e32 v44, v44
	v_exp_f32_e32 v45, v45
	v_pk_mul_f32 v[28:29], v[26:27], v[26:27]
	v_pk_add_f32 v[44:45], v[44:45], 1.0 op_sel_hi:[1,0]
	s_nop 0
	v_div_scale_f32 v48, s[0:1], v45, v45, v46
	v_rcp_f32_e32 v49, v48
	s_nop 0
	v_fma_f32 v50, -v48, v49, 1.0
	v_fmac_f32_e32 v49, v50, v49
	v_div_scale_f32 v50, vcc, v46, v45, v46
	v_mul_f32_e32 v51, v50, v49
	v_fma_f32 v52, -v48, v51, v50
	v_fmac_f32_e32 v51, v52, v49
	v_fma_f32 v48, -v48, v51, v50
	v_div_fmas_f32 v48, v48, v49, v51
	v_div_fixup_f32 v45, v48, v45, v46
	v_div_scale_f32 v46, s[0:1], v44, v44, v47
	v_rcp_f32_e32 v48, v46
	s_mov_b32 s0, s5
	v_fma_f32 v49, -v46, v48, 1.0
	v_fmac_f32_e32 v48, v49, v48
	v_div_scale_f32 v49, vcc, v47, v44, v47
	v_mul_f32_e32 v50, v49, v48
	v_fma_f32 v51, -v46, v50, v49
	v_fmac_f32_e32 v50, v51, v48
	v_fma_f32 v46, -v46, v50, v49
	v_div_fmas_f32 v46, v46, v48, v50
	v_div_fixup_f32 v44, v46, v44, v47
	v_lshlrev_b32_e32 v46, 16, v43
	v_and_b32_e32 v47, 0xffff0000, v43
	v_pk_mul_f32 v[48:49], v[46:47], v[46:47]
	v_mov_b32_e32 v51, v28
	v_mov_b32_e32 v50, v48
	v_mov_b32_e32 v28, v49
	v_pk_add_f32 v[28:29], v[50:51], v[28:29]
	v_mov_b32_e32 v49, v1
	v_mov_b32_e32 v48, v1
	v_lshlrev_b32_e32 v43, 16, v31
	v_mov_b32_dpp v49, v29 quad_perm:[1,0,3,2] row_mask:0xf bank_mask:0xf
	v_mov_b32_dpp v48, v28 quad_perm:[1,0,3,2] row_mask:0xf bank_mask:0xf
	v_pk_add_f32 v[28:29], v[28:29], v[48:49]
	v_mov_b32_e32 v49, v1
	v_mov_b32_e32 v48, v1
	v_and_b32_e32 v31, 0xffff0000, v31
	v_mov_b32_dpp v49, v29 quad_perm:[2,3,0,1] row_mask:0xf bank_mask:0xf
	v_mov_b32_dpp v48, v28 quad_perm:[2,3,0,1] row_mask:0xf bank_mask:0xf
	v_pk_add_f32 v[28:29], v[28:29], v[48:49]
	v_mov_b32_e32 v49, v1
	v_mov_b32_e32 v48, v1
	s_nop 0
	v_mov_b32_dpp v49, v29 row_half_mirror row_mask:0xf bank_mask:0xf
	v_mov_b32_dpp v48, v28 row_half_mirror row_mask:0xf bank_mask:0xf
	v_pk_add_f32 v[28:29], v[28:29], v[48:49]
	v_mov_b32_e32 v49, v1
	v_mov_b32_e32 v48, v1
	s_nop 0
	v_mov_b32_dpp v49, v29 row_mirror row_mask:0xf bank_mask:0xf
	v_mov_b32_dpp v48, v28 row_mirror row_mask:0xf bank_mask:0xf
	v_pk_add_f32 v[28:29], v[28:29], v[48:49]
	ds_bpermute_b32 v49, v32, v29
	ds_bpermute_b32 v48, v32, v28
	s_waitcnt lgkmcnt(0)
	v_pk_add_f32 v[28:29], v[28:29], v[48:49]
	ds_bpermute_b32 v49, v33, v29
	ds_bpermute_b32 v48, v33, v28
	s_waitcnt lgkmcnt(0)
	v_pk_add_f32 v[28:29], v[28:29], v[48:49]
	v_mov_b32_e32 v48, v123
	v_pk_fma_f32 v[28:29], v[28:29], s[0:1], v[48:49] op_sel_hi:[1,0,0]
	s_nop 0
	v_mul_f32_e32 v48, 0x4b800000, v29
	v_cmp_gt_f32_e64 s[0:1], s84, v29
	v_cmp_gt_f32_e32 vcc, s84, v28
	s_nop 0
	v_cndmask_b32_e64 v29, v29, v48, s[0:1]
	v_rsq_f32_e32 v29, v29
	s_nop 0
	v_mul_f32_e32 v48, 0x45800000, v29
	v_cndmask_b32_e64 v48, v29, v48, s[0:1]
	v_pk_mul_f32 v[26:27], v[48:49], v[26:27] op_sel_hi:[0,1]
	v_pk_mul_f32 v[26:27], v[6:7], v[26:27]
	v_mul_f32_e32 v29, 0xbfb8aa3b, v31
	v_pk_mul_f32 v[26:27], v[44:45], v[26:27]
	v_exp_f32_e32 v29, v29
	v_cvt_pk_bf16_f32 v26, v26, v27
	global_store_dword v[20:21], v26, off offset:1792
	v_mul_f32_e32 v26, 0x4b800000, v28
	v_cndmask_b32_e32 v26, v28, v26, vcc
	v_rsq_f32_e32 v26, v26
	s_nop 0
	v_mul_f32_e32 v27, 0x45800000, v26
	v_cndmask_b32_e32 v26, v26, v27, vcc
	v_mul_f32_e32 v27, 0xbfb8aa3b, v43
	v_exp_f32_e32 v28, v27
	v_pk_mul_f32 v[26:27], v[26:27], v[46:47] op_sel_hi:[0,1]
	v_pk_mul_f32 v[26:27], v[6:7], v[26:27]
	v_pk_add_f32 v[28:29], v[28:29], 1.0 op_sel_hi:[1,0]
	s_nop 0
	v_div_scale_f32 v44, s[0:1], v29, v29, v31
	v_rcp_f32_e32 v45, v44
	s_nop 0
	v_fma_f32 v46, -v44, v45, 1.0
	v_fmac_f32_e32 v45, v46, v45
	v_div_scale_f32 v46, vcc, v31, v29, v31
	v_mul_f32_e32 v47, v46, v45
	v_fma_f32 v48, -v44, v47, v46
	v_fmac_f32_e32 v47, v48, v45
	v_fma_f32 v44, -v44, v47, v46
	v_div_fmas_f32 v44, v44, v45, v47
	v_div_fixup_f32 v29, v44, v29, v31
	v_div_scale_f32 v31, s[0:1], v28, v28, v43
	v_rcp_f32_e32 v44, v31
	s_nop 0
	v_fma_f32 v45, -v31, v44, 1.0
	v_fmac_f32_e32 v44, v45, v44
	v_div_scale_f32 v45, vcc, v43, v28, v43
	v_mul_f32_e32 v46, v45, v44
	v_fma_f32 v47, -v31, v46, v45
	v_fmac_f32_e32 v46, v47, v44
	v_fma_f32 v31, -v31, v46, v45
	v_div_fmas_f32 v31, v31, v44, v46
	v_div_fixup_f32 v28, v31, v28, v43
	v_lshlrev_b32_e32 v43, 16, v9
	v_and_b32_e32 v9, 0xffff0000, v9
	v_pk_mul_f32 v[26:27], v[28:29], v[26:27]
	v_mul_f32_e32 v28, 0xbfb8aa3b, v43
	v_mul_f32_e32 v29, 0xbfb8aa3b, v9
	v_exp_f32_e32 v28, v28
	v_exp_f32_e32 v29, v29
	v_cvt_pk_bf16_f32 v26, v26, v27
	global_store_dword v[20:21], v26, off offset:2048
	v_lshlrev_b32_e32 v26, 16, v30
	v_pk_add_f32 v[28:29], v[28:29], 1.0 op_sel_hi:[1,0]
	v_and_b32_e32 v27, 0xffff0000, v30
	v_div_scale_f32 v44, s[0:1], v29, v29, v9
	v_rcp_f32_e32 v45, v44
	v_pk_mul_f32 v[30:31], v[26:27], v[26:27]
	v_fma_f32 v46, -v44, v45, 1.0
	v_fmac_f32_e32 v45, v46, v45
	v_div_scale_f32 v46, vcc, v9, v29, v9
	v_mul_f32_e32 v47, v46, v45
	v_fma_f32 v48, -v44, v47, v46
	v_fmac_f32_e32 v47, v48, v45
	v_fma_f32 v44, -v44, v47, v46
	v_div_fmas_f32 v44, v44, v45, v47
	v_div_fixup_f32 v29, v44, v29, v9
	v_div_scale_f32 v9, s[0:1], v28, v28, v43
	v_rcp_f32_e32 v44, v9
	s_nop 0
	v_fma_f32 v45, -v9, v44, 1.0
	v_fmac_f32_e32 v44, v45, v44
	v_div_scale_f32 v45, vcc, v43, v28, v43
	v_mul_f32_e32 v46, v45, v44
	v_fma_f32 v47, -v9, v46, v45
	v_fmac_f32_e32 v46, v47, v44
	v_fma_f32 v9, -v9, v46, v45
	v_div_fmas_f32 v9, v9, v44, v46
	v_div_fixup_f32 v28, v9, v28, v43
	v_lshlrev_b32_e32 v9, 16, v22
	v_mul_f32_e32 v9, 0xbfb8aa3b, v9
	v_exp_f32_e32 v46, v9
	v_and_b32_e32 v9, 0xffff0000, v22
	v_mul_f32_e32 v9, 0xbfb8aa3b, v9
	v_exp_f32_e32 v47, v9
	v_lshlrev_b32_e32 v9, 16, v23
	v_mul_f32_e32 v9, 0xbfb8aa3b, v9
	v_exp_f32_e32 v22, v9
	v_and_b32_e32 v9, 0xffff0000, v23
	v_mul_f32_e32 v9, 0xbfb8aa3b, v9
	v_exp_f32_e32 v23, v9
	v_pk_add_f32 v[46:47], v[46:47], 1.0 op_sel_hi:[1,0]
	v_lshlrev_b32_e32 v44, 16, v24
	v_and_b32_e32 v45, 0xffff0000, v24
	v_pk_add_f32 v[22:23], v[22:23], 1.0 op_sel_hi:[1,0]
	v_lshlrev_b32_e32 v24, 16, v25
	v_div_scale_f32 v9, s[0:1], v23, v23, 1.0
	v_rcp_f32_e32 v43, v9
	v_and_b32_e32 v25, 0xffff0000, v25
	v_fma_f32 v48, -v9, v43, 1.0
	v_fmac_f32_e32 v43, v48, v43
	v_div_scale_f32 v48, vcc, 1.0, v23, 1.0
	v_mul_f32_e32 v49, v48, v43
	v_fma_f32 v50, -v9, v49, v48
	v_fmac_f32_e32 v49, v50, v43
	v_fma_f32 v9, -v9, v49, v48
	v_div_fmas_f32 v9, v9, v43, v49
	v_div_fixup_f32 v23, v9, v23, 1.0
	v_div_scale_f32 v9, s[0:1], v22, v22, 1.0
	v_rcp_f32_e32 v43, v9
	s_nop 0
	v_fma_f32 v48, -v9, v43, 1.0
	v_fmac_f32_e32 v43, v48, v43
	v_div_scale_f32 v48, vcc, 1.0, v22, 1.0
	v_mul_f32_e32 v49, v48, v43
	v_fma_f32 v50, -v9, v49, v48
	v_fmac_f32_e32 v49, v50, v43
	v_fma_f32 v9, -v9, v49, v48
	v_div_fmas_f32 v9, v9, v43, v49
	v_div_fixup_f32 v22, v9, v22, 1.0
	v_div_scale_f32 v9, s[0:1], v47, v47, 1.0
	v_rcp_f32_e32 v43, v9
	v_pk_mul_f32 v[48:49], v[22:23], v[24:25]
	v_fma_f32 v50, -v9, v43, 1.0
	v_fmac_f32_e32 v43, v50, v43
	v_div_scale_f32 v50, vcc, 1.0, v47, 1.0
	v_mul_f32_e32 v51, v50, v43
	v_fma_f32 v52, -v9, v51, v50
	v_fmac_f32_e32 v51, v52, v43
	v_fma_f32 v9, -v9, v51, v50
	v_div_fmas_f32 v9, v9, v43, v51
	v_div_fixup_f32 v47, v9, v47, 1.0
	v_div_scale_f32 v9, s[0:1], v46, v46, 1.0
	v_rcp_f32_e32 v43, v9
	s_nop 0
	v_fma_f32 v50, -v9, v43, 1.0
	v_fmac_f32_e32 v43, v50, v43
	v_div_scale_f32 v50, vcc, 1.0, v46, 1.0
	v_mul_f32_e32 v51, v50, v43
	v_fma_f32 v52, -v9, v51, v50
	v_fmac_f32_e32 v51, v52, v43
	v_fma_f32 v9, -v9, v51, v50
	v_div_fmas_f32 v9, v9, v43, v51
	v_div_fixup_f32 v46, v9, v46, 1.0
	v_pk_mul_f32 v[50:51], v[46:47], v[44:45]
	s_nop 0
	v_add_f32_e32 v9, v50, v51
	v_add_f32_e32 v9, v9, v48
	v_add_f32_e32 v9, v49, v9
	s_nop 1
	v_add_f32_dpp v9, v9, v9 quad_perm:[1,0,3,2] row_mask:0xf bank_mask:0xf bound_ctrl:1
	s_nop 1
	v_add_f32_dpp v9, v9, v9 quad_perm:[2,3,0,1] row_mask:0xf bank_mask:0xf bound_ctrl:1
	s_nop 1
	v_add_f32_dpp v9, v9, v9 row_half_mirror row_mask:0xf bank_mask:0xf bound_ctrl:1
	s_nop 1
	v_add_f32_dpp v9, v9, v9 row_mirror row_mask:0xf bank_mask:0xf bound_ctrl:1
	v_mul_f32_e32 v48, 0x3c800000, v9
	v_pk_fma_f32 v[44:45], v[46:47], v[44:45], v[48:49] op_sel_hi:[1,1,0] neg_lo:[0,0,1] neg_hi:[0,0,1]
	v_pk_fma_f32 v[22:23], v[22:23], v[24:25], v[48:49] op_sel_hi:[1,1,0] neg_lo:[0,0,1] neg_hi:[0,0,1]
	v_pk_mul_f32 v[24:25], v[44:45], v[44:45]
	v_mov_b32_e32 v49, v30
	v_mov_b32_e32 v48, v24
	v_mov_b32_e32 v30, v25
	v_pk_mul_f32 v[46:47], v[22:23], v[22:23]
	v_pk_add_f32 v[24:25], v[48:49], v[30:31]
	v_mov_b32_e32 v31, v1
	v_mov_b32_e32 v30, v46
	s_nop 0
	v_mov_b32_dpp v31, v25 quad_perm:[1,0,3,2] row_mask:0xf bank_mask:0xf
	v_pk_add_f32 v[24:25], v[30:31], v[24:25]
	v_mov_b32_e32 v31, v1
	v_mov_b32_e32 v30, v47
	s_nop 0
	v_mov_b32_dpp v31, v25 quad_perm:[2,3,0,1] row_mask:0xf bank_mask:0xf
	v_pk_add_f32 v[24:25], v[30:31], v[24:25]
	v_mov_b32_e32 v31, v1
	v_mov_b32_e32 v30, v1
	s_nop 0
	v_mov_b32_dpp v31, v25 row_half_mirror row_mask:0xf bank_mask:0xf
	v_mov_b32_dpp v30, v24 quad_perm:[1,0,3,2] row_mask:0xf bank_mask:0xf
	v_pk_add_f32 v[24:25], v[24:25], v[30:31]
	v_mov_b32_e32 v31, v1
	v_mov_b32_e32 v30, v1
	s_nop 0
	v_mov_b32_dpp v31, v25 row_mirror row_mask:0xf bank_mask:0xf
	v_mov_b32_dpp v30, v24 quad_perm:[2,3,0,1] row_mask:0xf bank_mask:0xf
	v_pk_add_f32 v[24:25], v[24:25], v[30:31]
	ds_bpermute_b32 v31, v32, v25
	v_mov_b32_e32 v30, v1
	s_nop 1
	v_mov_b32_dpp v30, v24 row_half_mirror row_mask:0xf bank_mask:0xf
	s_waitcnt lgkmcnt(0)
	v_pk_add_f32 v[24:25], v[24:25], v[30:31]
	ds_bpermute_b32 v31, v33, v25
	v_mov_b32_e32 v30, v1
	s_nop 1
	v_mov_b32_dpp v30, v24 row_mirror row_mask:0xf bank_mask:0xf
	s_waitcnt lgkmcnt(0)
	v_pk_add_f32 v[24:25], v[24:25], v[30:31]
	s_nop 0
	v_pk_fma_f32 v[24:25], v[24:25], s[4:5], v[122:123]
	s_nop 0
	v_mul_f32_e32 v9, 0x4b800000, v25
	v_cmp_gt_f32_e64 s[0:1], s84, v25
	v_cmp_gt_f32_e32 vcc, s84, v24
	s_nop 0
	v_cndmask_b32_e64 v9, v25, v9, s[0:1]
	v_rsq_f32_e32 v9, v9
	s_nop 0
	v_mul_f32_e32 v25, 0x45800000, v9
	v_cndmask_b32_e64 v30, v9, v25, s[0:1]
	v_pk_mul_f32 v[26:27], v[30:31], v[26:27] op_sel_hi:[0,1]
	v_pk_mul_f32 v[26:27], v[6:7], v[26:27]
	s_nop 0
	v_pk_mul_f32 v[26:27], v[28:29], v[26:27]
	s_nop 0
	v_cvt_pk_bf16_f32 v9, v26, v27
	global_store_dword v[20:21], v9, off offset:2304
	v_mul_f32_e32 v9, 0x4b800000, v24
	v_cndmask_b32_e32 v9, v24, v9, vcc
	v_rsq_f32_e32 v9, v9
	s_nop 0
	v_mul_f32_e32 v20, 0x45800000, v9
	v_cndmask_b32_e32 v20, v9, v20, vcc
	v_pk_mul_f32 v[24:25], v[44:45], v[20:21] op_sel_hi:[1,0]
	v_pk_mul_f32 v[20:21], v[22:23], v[20:21] op_sel_hi:[1,0]
	v_pk_mul_f32 v[24:25], v[2:3], v[24:25]
	v_pk_mul_f32 v[20:21], v[4:5], v[20:21]
	v_cvt_pk_bf16_f32 v24, v24, v25
	v_cvt_pk_bf16_f32 v25, v20, v21
	global_store_dwordx2 v[18:19], v[24:25], off offset:2560
	s_and_saveexec_b64 s[44:45], s[38:39]
	s_cbranch_execz .LBB0_349
	v_lshlrev_b32_e32 v18, 16, v41
	v_and_b32_e32 v19, 0xffff0000, v41
	v_pk_mul_f32 v[20:21], v[18:19], v[18:19]
	v_lshlrev_b32_e32 v9, 16, v42
	v_add_f32_e32 v20, v20, v21
	v_and_b32_e32 v24, 0xffff0000, v42
	v_and_b32_e32 v30, 0xffff0000, v37
	v_add_f32_dpp v20, v20, v20 quad_perm:[1,0,3,2] row_mask:0xf bank_mask:0xf bound_ctrl:1
	s_nop 1
	v_add_f32_dpp v20, v20, v20 quad_perm:[2,3,0,1] row_mask:0xf bank_mask:0xf bound_ctrl:1
	s_nop 1
	v_add_f32_dpp v20, v20, v20 row_half_mirror row_mask:0xf bank_mask:0xf bound_ctrl:1
	s_nop 1
	v_add_f32_dpp v20, v20, v20 row_mirror row_mask:0xf bank_mask:0xf bound_ctrl:1
	v_mov_b32_e32 v21, v20
	v_mov_b32_e32 v255, v20
	s_nop 1
	v_permlane16_swap_b32_e32 v21, v255
	s_nop 1
	v_add_f32_e32 v20, v21, v255
	v_mov_b32_e32 v21, v20
	v_mov_b32_e32 v255, v20
	s_nop 1
	v_permlane32_swap_b32_e32 v21, v255
	s_nop 1
	v_add_f32_e32 v20, v21, v255
	v_fmamk_f32 v20, v20, 0x3c000000, v123
	v_cmp_gt_f32_e32 vcc, s84, v20
	v_mul_f32_e32 v21, 0x4b800000, v20
	s_nop 0
	v_cndmask_b32_e32 v20, v20, v21, vcc
	v_rsq_f32_e32 v20, v20
	s_nop 0
	v_mul_f32_e32 v21, 0x45800000, v20
	v_cndmask_b32_e32 v20, v20, v21, vcc
	v_mul_f32_e32 v21, 0xbfb8aa3b, v9
	v_pk_mul_f32 v[18:19], v[20:21], v[18:19] op_sel_hi:[0,1]
	v_mul_f32_e32 v20, 0xbfb8aa3b, v24
	v_exp_f32_e32 v22, v21
	v_exp_f32_e32 v23, v20
	v_pk_mul_f32 v[18:19], v[6:7], v[18:19]
	v_pk_add_f32 v[20:21], v[22:23], 1.0 op_sel_hi:[1,0]
	s_nop 0
	v_div_scale_f32 v22, s[0:1], v21, v21, v24
	v_rcp_f32_e32 v23, v22
	s_nop 0
	v_fma_f32 v25, -v22, v23, 1.0
	v_fmac_f32_e32 v23, v25, v23
	v_div_scale_f32 v25, vcc, v24, v21, v24
	v_mul_f32_e32 v26, v25, v23
	v_fma_f32 v27, -v22, v26, v25
	v_fmac_f32_e32 v26, v27, v23
	v_fma_f32 v22, -v22, v26, v25
	v_div_fmas_f32 v22, v22, v23, v26
	v_div_fixup_f32 v21, v22, v21, v24
	v_div_scale_f32 v22, s[0:1], v20, v20, v9
	v_rcp_f32_e32 v23, v22
	s_nop 0
	v_fma_f32 v24, -v22, v23, 1.0
	v_fmac_f32_e32 v23, v24, v23
	v_div_scale_f32 v24, vcc, v9, v20, v9
	v_mul_f32_e32 v25, v24, v23
	v_fma_f32 v26, -v22, v25, v24
	v_fmac_f32_e32 v25, v26, v23
	v_fma_f32 v22, -v22, v25, v24
	v_div_fmas_f32 v22, v22, v23, v25
	v_div_fixup_f32 v20, v22, v20, v9
	v_pk_mul_f32 v[18:19], v[20:21], v[18:19]
	v_and_b32_e32 v24, 0xffff0000, v39
	v_cvt_pk_bf16_f32 v9, v18, v19
	global_store_dword v[10:11], v9, off offset:1536
	v_lshlrev_b32_e32 v9, 16, v39
	v_mul_f32_e32 v22, 0xbfb8aa3b, v9
	v_mul_f32_e32 v23, 0xbfb8aa3b, v24
	v_exp_f32_e32 v22, v22
	v_exp_f32_e32 v23, v23
	v_lshlrev_b32_e32 v18, 16, v40
	v_and_b32_e32 v19, 0xffff0000, v40
	v_pk_mul_f32 v[20:21], v[18:19], v[18:19]
	v_pk_add_f32 v[22:23], v[22:23], 1.0 op_sel_hi:[1,0]
	s_nop 0
	v_div_scale_f32 v25, s[0:1], v23, v23, v24
	v_rcp_f32_e32 v26, v25
	s_nop 0
	v_fma_f32 v27, -v25, v26, 1.0
	v_fmac_f32_e32 v26, v27, v26
	v_div_scale_f32 v27, vcc, v24, v23, v24
	v_mul_f32_e32 v28, v27, v26
	v_fma_f32 v29, -v25, v28, v27
	v_fmac_f32_e32 v28, v29, v26
	v_fma_f32 v25, -v25, v28, v27
	v_div_fmas_f32 v25, v25, v26, v28
	v_div_fixup_f32 v23, v25, v23, v24
	v_div_scale_f32 v24, s[0:1], v22, v22, v9
	v_rcp_f32_e32 v25, v24
	v_mov_b32_e32 v29, v20
	s_mov_b32 s0, s5
	v_fma_f32 v26, -v24, v25, 1.0
	v_fmac_f32_e32 v25, v26, v25
	v_div_scale_f32 v26, vcc, v9, v22, v9
	v_mul_f32_e32 v27, v26, v25
	v_fma_f32 v28, -v24, v27, v26
	v_fmac_f32_e32 v27, v28, v25
	v_fma_f32 v24, -v24, v27, v26
	v_div_fmas_f32 v24, v24, v25, v27
	v_div_fixup_f32 v22, v24, v22, v9
	v_lshlrev_b32_e32 v24, 16, v38
	v_and_b32_e32 v25, 0xffff0000, v38
	v_pk_mul_f32 v[26:27], v[24:25], v[24:25]
	v_lshlrev_b32_e32 v9, 16, v37
	v_mov_b32_e32 v28, v26
	v_mov_b32_e32 v20, v27
	v_pk_add_f32 v[20:21], v[28:29], v[20:21]
	v_mov_b32_e32 v27, v1
	v_mov_b32_e32 v26, v1
	s_nop 0
	v_mov_b32_dpp v27, v21 quad_perm:[1,0,3,2] row_mask:0xf bank_mask:0xf
	v_mov_b32_dpp v26, v20 quad_perm:[1,0,3,2] row_mask:0xf bank_mask:0xf
	v_pk_add_f32 v[20:21], v[20:21], v[26:27]
	v_mov_b32_e32 v27, v1
	v_mov_b32_e32 v26, v1
	s_nop 0
	v_mov_b32_dpp v27, v21 quad_perm:[2,3,0,1] row_mask:0xf bank_mask:0xf
	v_mov_b32_dpp v26, v20 quad_perm:[2,3,0,1] row_mask:0xf bank_mask:0xf
	v_pk_add_f32 v[20:21], v[20:21], v[26:27]
	v_mov_b32_e32 v27, v1
	v_mov_b32_e32 v26, v1
	s_nop 0
	v_mov_b32_dpp v27, v21 row_half_mirror row_mask:0xf bank_mask:0xf
	v_mov_b32_dpp v26, v20 row_half_mirror row_mask:0xf bank_mask:0xf
	v_pk_add_f32 v[20:21], v[20:21], v[26:27]
	v_mov_b32_e32 v27, v1
	v_mov_b32_e32 v26, v1
	s_nop 0
	v_mov_b32_dpp v27, v21 row_mirror row_mask:0xf bank_mask:0xf
	v_mov_b32_dpp v26, v20 row_mirror row_mask:0xf bank_mask:0xf
	v_pk_add_f32 v[20:21], v[20:21], v[26:27]
	ds_bpermute_b32 v27, v32, v21
	ds_bpermute_b32 v26, v32, v20
	s_waitcnt lgkmcnt(0)
	v_pk_add_f32 v[20:21], v[20:21], v[26:27]
	ds_bpermute_b32 v27, v33, v21
	ds_bpermute_b32 v26, v33, v20
	s_waitcnt lgkmcnt(0)
	v_pk_add_f32 v[20:21], v[20:21], v[26:27]
	v_mov_b32_e32 v26, v123
	v_pk_fma_f32 v[20:21], v[20:21], s[0:1], v[26:27] op_sel_hi:[1,0,0]
	s_nop 0
	v_mul_f32_e32 v26, 0x4b800000, v21
	v_cmp_gt_f32_e64 s[0:1], s84, v21
	v_cmp_gt_f32_e32 vcc, s84, v20
	s_nop 0
	v_cndmask_b32_e64 v21, v21, v26, s[0:1]
	v_rsq_f32_e32 v21, v21
	s_nop 0
	v_mul_f32_e32 v26, 0x45800000, v21
	v_cndmask_b32_e64 v26, v21, v26, s[0:1]
	v_pk_mul_f32 v[18:19], v[26:27], v[18:19] op_sel_hi:[0,1]
	v_pk_mul_f32 v[18:19], v[6:7], v[18:19]
	v_mul_f32_e32 v21, 0xbfb8aa3b, v30
	v_pk_mul_f32 v[18:19], v[22:23], v[18:19]
	v_exp_f32_e32 v21, v21
	v_cvt_pk_bf16_f32 v18, v18, v19
	global_store_dword v[10:11], v18, off offset:1792
	v_mul_f32_e32 v18, 0x4b800000, v20
	v_cndmask_b32_e32 v18, v20, v18, vcc
	v_rsq_f32_e32 v18, v18
	s_nop 0
	v_mul_f32_e32 v19, 0x45800000, v18
	v_cndmask_b32_e32 v18, v18, v19, vcc
	v_mul_f32_e32 v19, 0xbfb8aa3b, v9
	v_exp_f32_e32 v20, v19
	v_pk_mul_f32 v[18:19], v[18:19], v[24:25] op_sel_hi:[0,1]
	v_pk_mul_f32 v[18:19], v[6:7], v[18:19]
	v_pk_add_f32 v[20:21], v[20:21], 1.0 op_sel_hi:[1,0]
	s_nop 0
	v_div_scale_f32 v22, s[0:1], v21, v21, v30
	v_rcp_f32_e32 v23, v22
	s_nop 0
	v_fma_f32 v24, -v22, v23, 1.0
	v_fmac_f32_e32 v23, v24, v23
	v_div_scale_f32 v24, vcc, v30, v21, v30
	v_mul_f32_e32 v25, v24, v23
	v_fma_f32 v26, -v22, v25, v24
	v_fmac_f32_e32 v25, v26, v23
	v_fma_f32 v22, -v22, v25, v24
	v_div_fmas_f32 v22, v22, v23, v25
	v_div_fixup_f32 v21, v22, v21, v30
	v_div_scale_f32 v22, s[0:1], v20, v20, v9
	v_rcp_f32_e32 v23, v22
	s_nop 0
	v_fma_f32 v24, -v22, v23, 1.0
	v_fmac_f32_e32 v23, v24, v23
	v_div_scale_f32 v24, vcc, v9, v20, v9
	v_mul_f32_e32 v25, v24, v23
	v_fma_f32 v26, -v22, v25, v24
	v_fmac_f32_e32 v25, v26, v23
	v_fma_f32 v22, -v22, v25, v24
	v_div_fmas_f32 v22, v22, v23, v25
	v_div_fixup_f32 v20, v22, v20, v9
	v_pk_mul_f32 v[18:19], v[20:21], v[18:19]
	v_and_b32_e32 v24, 0xffff0000, v35
	v_cvt_pk_bf16_f32 v9, v18, v19
	global_store_dword v[10:11], v9, off offset:2048
	v_lshlrev_b32_e32 v9, 16, v35
	v_mul_f32_e32 v20, 0xbfb8aa3b, v9
	v_mul_f32_e32 v21, 0xbfb8aa3b, v24
	v_exp_f32_e32 v20, v20
	v_exp_f32_e32 v21, v21
	v_lshlrev_b32_e32 v18, 16, v36
	v_and_b32_e32 v19, 0xffff0000, v36
	v_pk_mul_f32 v[22:23], v[18:19], v[18:19]
	v_pk_add_f32 v[20:21], v[20:21], 1.0 op_sel_hi:[1,0]
	s_nop 0
	v_div_scale_f32 v25, s[0:1], v21, v21, v24
	v_rcp_f32_e32 v26, v25
	s_nop 0
	v_fma_f32 v27, -v25, v26, 1.0
	v_fmac_f32_e32 v26, v27, v26
	v_div_scale_f32 v27, vcc, v24, v21, v24
	v_mul_f32_e32 v28, v27, v26
	v_fma_f32 v29, -v25, v28, v27
	v_fmac_f32_e32 v28, v29, v26
	v_fma_f32 v25, -v25, v28, v27
	v_div_fmas_f32 v25, v25, v26, v28
	v_div_fixup_f32 v21, v25, v21, v24
	v_div_scale_f32 v24, s[0:1], v20, v20, v9
	v_rcp_f32_e32 v25, v24
	s_nop 0
	v_fma_f32 v26, -v24, v25, 1.0
	v_fmac_f32_e32 v25, v26, v25
	v_div_scale_f32 v26, vcc, v9, v20, v9
	v_mul_f32_e32 v27, v26, v25
	v_fma_f32 v28, -v24, v27, v26
	v_fmac_f32_e32 v27, v28, v25
	v_fma_f32 v24, -v24, v27, v26
	v_div_fmas_f32 v24, v24, v25, v27
	v_div_fixup_f32 v20, v24, v20, v9
	v_lshlrev_b32_e32 v9, 16, v16
	v_mul_f32_e32 v9, 0xbfb8aa3b, v9
	v_exp_f32_e32 v26, v9
	v_and_b32_e32 v9, 0xffff0000, v16
	v_mul_f32_e32 v9, 0xbfb8aa3b, v9
	v_exp_f32_e32 v27, v9
	v_lshlrev_b32_e32 v9, 16, v17
	v_mul_f32_e32 v9, 0xbfb8aa3b, v9
	v_exp_f32_e32 v16, v9
	v_and_b32_e32 v9, 0xffff0000, v17
	v_mul_f32_e32 v9, 0xbfb8aa3b, v9
	v_exp_f32_e32 v17, v9
	v_pk_add_f32 v[26:27], v[26:27], 1.0 op_sel_hi:[1,0]
	v_lshlrev_b32_e32 v24, 16, v14
	v_and_b32_e32 v25, 0xffff0000, v14
	v_pk_add_f32 v[16:17], v[16:17], 1.0 op_sel_hi:[1,0]
	v_lshlrev_b32_e32 v14, 16, v15
	v_div_scale_f32 v9, s[0:1], v17, v17, 1.0
	v_rcp_f32_e32 v28, v9
	v_and_b32_e32 v15, 0xffff0000, v15
	v_fma_f32 v29, -v9, v28, 1.0
	v_fmac_f32_e32 v28, v29, v28
	v_div_scale_f32 v29, vcc, 1.0, v17, 1.0
	v_mul_f32_e32 v30, v29, v28
	v_fma_f32 v31, -v9, v30, v29
	v_fmac_f32_e32 v30, v31, v28
	v_fma_f32 v9, -v9, v30, v29
	v_div_fmas_f32 v9, v9, v28, v30
	v_div_fixup_f32 v17, v9, v17, 1.0
	v_div_scale_f32 v9, s[0:1], v16, v16, 1.0
	v_rcp_f32_e32 v28, v9
	s_nop 0
	v_fma_f32 v29, -v9, v28, 1.0
	v_fmac_f32_e32 v28, v29, v28
	v_div_scale_f32 v29, vcc, 1.0, v16, 1.0
	v_mul_f32_e32 v30, v29, v28
	v_fma_f32 v31, -v9, v30, v29
	v_fmac_f32_e32 v30, v31, v28
	v_fma_f32 v9, -v9, v30, v29
	v_div_fmas_f32 v9, v9, v28, v30
	v_div_fixup_f32 v16, v9, v16, 1.0
	v_div_scale_f32 v9, s[0:1], v27, v27, 1.0
	v_rcp_f32_e32 v30, v9
	v_pk_mul_f32 v[28:29], v[16:17], v[14:15]
	v_fma_f32 v31, -v9, v30, 1.0
	v_fmac_f32_e32 v30, v31, v30
	v_div_scale_f32 v31, vcc, 1.0, v27, 1.0
	v_mul_f32_e32 v35, v31, v30
	v_fma_f32 v36, -v9, v35, v31
	v_fmac_f32_e32 v35, v36, v30
	v_fma_f32 v9, -v9, v35, v31
	v_div_fmas_f32 v9, v9, v30, v35
	v_div_fixup_f32 v27, v9, v27, 1.0
	v_div_scale_f32 v9, s[0:1], v26, v26, 1.0
	v_rcp_f32_e32 v30, v9
	s_nop 0
	v_fma_f32 v31, -v9, v30, 1.0
	v_fmac_f32_e32 v30, v31, v30
	v_div_scale_f32 v31, vcc, 1.0, v26, 1.0
	v_mul_f32_e32 v35, v31, v30
	v_fma_f32 v36, -v9, v35, v31
	v_fmac_f32_e32 v35, v36, v30
	v_fma_f32 v9, -v9, v35, v31
	v_div_fmas_f32 v9, v9, v30, v35
	v_div_fixup_f32 v26, v9, v26, 1.0
	v_pk_mul_f32 v[30:31], v[26:27], v[24:25]
	s_nop 0
	v_add_f32_e32 v9, v30, v31
	v_add_f32_e32 v9, v9, v28
	v_add_f32_e32 v9, v29, v9
	s_nop 1
	v_add_f32_dpp v9, v9, v9 quad_perm:[1,0,3,2] row_mask:0xf bank_mask:0xf bound_ctrl:1
	s_nop 1
	v_add_f32_dpp v9, v9, v9 quad_perm:[2,3,0,1] row_mask:0xf bank_mask:0xf bound_ctrl:1
	s_nop 1
	v_add_f32_dpp v9, v9, v9 row_half_mirror row_mask:0xf bank_mask:0xf bound_ctrl:1
	s_nop 1
	v_add_f32_dpp v9, v9, v9 row_mirror row_mask:0xf bank_mask:0xf bound_ctrl:1
	v_mul_f32_e32 v28, 0x3c800000, v9
	v_pk_fma_f32 v[24:25], v[26:27], v[24:25], v[28:29] op_sel_hi:[1,1,0] neg_lo:[0,0,1] neg_hi:[0,0,1]
	v_pk_fma_f32 v[14:15], v[16:17], v[14:15], v[28:29] op_sel_hi:[1,1,0] neg_lo:[0,0,1] neg_hi:[0,0,1]
	v_pk_mul_f32 v[16:17], v[24:25], v[24:25]
	v_mov_b32_e32 v29, v22
	v_mov_b32_e32 v28, v16
	v_mov_b32_e32 v22, v17
	v_pk_mul_f32 v[26:27], v[14:15], v[14:15]
	v_pk_add_f32 v[16:17], v[28:29], v[22:23]
	v_mov_b32_e32 v23, v1
	v_mov_b32_e32 v22, v26
	s_nop 0
	v_mov_b32_dpp v23, v17 quad_perm:[1,0,3,2] row_mask:0xf bank_mask:0xf
	v_pk_add_f32 v[16:17], v[22:23], v[16:17]
	v_mov_b32_e32 v23, v1
	v_mov_b32_e32 v22, v27
	s_nop 0
	v_mov_b32_dpp v23, v17 quad_perm:[2,3,0,1] row_mask:0xf bank_mask:0xf
	v_pk_add_f32 v[16:17], v[22:23], v[16:17]
	v_mov_b32_e32 v23, v1
	v_mov_b32_e32 v22, v1
	s_nop 0
	v_mov_b32_dpp v23, v17 row_half_mirror row_mask:0xf bank_mask:0xf
	v_mov_b32_dpp v22, v16 quad_perm:[1,0,3,2] row_mask:0xf bank_mask:0xf
	v_pk_add_f32 v[16:17], v[16:17], v[22:23]
	v_mov_b32_e32 v23, v1
	v_mov_b32_e32 v22, v1
	s_nop 0
	v_mov_b32_dpp v23, v17 row_mirror row_mask:0xf bank_mask:0xf
	v_mov_b32_dpp v22, v16 quad_perm:[2,3,0,1] row_mask:0xf bank_mask:0xf
	v_pk_add_f32 v[16:17], v[16:17], v[22:23]
	ds_bpermute_b32 v23, v32, v17
	v_mov_b32_e32 v22, v1
	s_nop 1
	v_mov_b32_dpp v22, v16 row_half_mirror row_mask:0xf bank_mask:0xf
	s_waitcnt lgkmcnt(0)
	v_pk_add_f32 v[16:17], v[16:17], v[22:23]
	ds_bpermute_b32 v23, v33, v17
	v_mov_b32_e32 v22, v1
	s_nop 1
	v_mov_b32_dpp v22, v16 row_mirror row_mask:0xf bank_mask:0xf
	s_waitcnt lgkmcnt(0)
	v_pk_add_f32 v[16:17], v[16:17], v[22:23]
	s_nop 0
	v_pk_fma_f32 v[16:17], v[16:17], s[4:5], v[122:123]
	s_nop 0
	v_mul_f32_e32 v9, 0x4b800000, v17
	v_cmp_gt_f32_e64 s[0:1], s84, v17
	v_cmp_gt_f32_e32 vcc, s84, v16
	s_nop 0
	v_cndmask_b32_e64 v9, v17, v9, s[0:1]
	v_rsq_f32_e32 v9, v9
	s_nop 0
	v_mul_f32_e32 v17, 0x45800000, v9
	v_cndmask_b32_e64 v22, v9, v17, s[0:1]
	v_pk_mul_f32 v[18:19], v[22:23], v[18:19] op_sel_hi:[0,1]
	v_pk_mul_f32 v[18:19], v[6:7], v[18:19]
	s_nop 0
	v_pk_mul_f32 v[18:19], v[20:21], v[18:19]
	s_nop 0
	v_cvt_pk_bf16_f32 v9, v18, v19
	global_store_dword v[10:11], v9, off offset:2304
	v_mul_f32_e32 v9, 0x4b800000, v16
	v_cndmask_b32_e32 v9, v16, v9, vcc
	v_rsq_f32_e32 v9, v9
	s_nop 0
	v_mul_f32_e32 v10, 0x45800000, v9
	v_cndmask_b32_e32 v10, v9, v10, vcc
	v_pk_mul_f32 v[16:17], v[24:25], v[10:11] op_sel_hi:[1,0]
	v_pk_mul_f32 v[10:11], v[14:15], v[10:11] op_sel_hi:[1,0]
	v_pk_mul_f32 v[16:17], v[2:3], v[16:17]
	v_pk_mul_f32 v[10:11], v[4:5], v[10:11]
	v_cvt_pk_bf16_f32 v16, v16, v17
	v_cvt_pk_bf16_f32 v17, v10, v11
	global_store_dwordx2 v[12:13], v[16:17], off offset:2560
	s_branch .LBB0_349

.LBB0_587:
	s_cmpk_lg_i32 s44, 0x1600
	s_cselect_b32 s38, s49, 0x580
	v_or_b32_e32 v0, s38, v23
	v_lshlrev_b64 v[68:69], 1, v[0:1]
	v_lshl_add_u64 v[70:71], v[8:9], 0, v[68:69]
	s_waitcnt vmcnt(7)
	v_and_b32_e32 v77, 0xffff0000, v88
	v_lshlrev_b32_e32 v76, 16, v88
	global_load_dword v88, v[70:71], off offset:1536
	v_lshl_add_u64 v[70:71], v[10:11], 0, v[68:69]
	v_lshlrev_b64 v[64:65], 2, v[0:1]
	global_load_dword v0, v[70:71], off
	v_lshl_add_u64 v[70:71], v[12:13], 0, v[68:69]
	global_load_dword v25, v[70:71], off
	v_lshl_add_u64 v[70:71], v[14:15], 0, v[68:69]
	global_load_dword v27, v[70:71], off
	v_lshl_add_u64 v[70:71], v[16:17], 0, v[68:69]
	global_load_dword v29, v[70:71], off
	v_lshl_add_u64 v[70:71], v[18:19], 0, v[68:69]
	global_load_dword v31, v[70:71], off
	v_lshl_add_u64 v[70:71], v[20:21], 0, v[68:69]
	v_lshl_add_u64 v[68:69], v[38:39], 0, v[68:69]
	v_lshl_add_u64 v[74:75], v[56:57], 0, s[44:45]
	global_load_dword v33, v[70:71], off
	global_load_dword v35, v[68:69], off
	v_add_co_u32_e32 v70, vcc, s93, v74
	global_load_dwordx2 v[68:69], v[74:75], off
	s_nop 0
	v_addc_co_u32_e32 v71, vcc, 0, v75, vcc
	v_add_co_u32_e32 v72, vcc, s95, v74
	global_load_dwordx2 v[70:71], v[70:71], off offset:2048
	s_nop 0
	v_addc_co_u32_e32 v73, vcc, 0, v75, vcc
	global_load_dwordx2 v[72:73], v[72:73], off
	v_add_co_u32_e32 v74, vcc, s86, v74
	v_lshl_add_u64 v[66:67], v[2:3], 0, v[64:65]
	s_nop 0
	v_addc_co_u32_e32 v75, vcc, 0, v75, vcc
	global_load_dwordx2 v[74:75], v[74:75], off offset:2048
	v_lshl_add_u64 v[62:63], v[4:5], 0, v[64:65]
	v_lshl_add_u64 v[64:65], v[6:7], 0, v[64:65]
	global_load_dwordx2 v[62:63], v[62:63], off
	s_cmp_lt_u32 s48, 8
	global_load_dwordx2 v[64:65], v[64:65], off
	s_cselect_b64 s[46:47], -1, 0
	global_load_dwordx2 v[66:67], v[66:67], off
	s_cmp_lt_u32 s48, 4
	s_cselect_b64 s[38:39], -1, 0
	s_cmp_gt_u32 s48, 7
	s_waitcnt vmcnt(6)
	v_pk_fma_f32 v[82:83], v[82:83], v[68:69], 0 op_sel_hi:[1,1,0]
	s_waitcnt vmcnt(5)
	v_pk_fma_f32 v[82:83], v[80:81], v[70:71], v[82:83]
	s_waitcnt vmcnt(4)
	v_pk_fma_f32 v[82:83], v[78:79], v[72:73], v[82:83]
	s_waitcnt vmcnt(3)
	v_pk_fma_f32 v[82:83], v[74:75], v[76:77], v[82:83]
	s_nop 0
	v_mul_f32_e32 v37, 0xbfb8aa3b, v82
	v_exp_f32_e32 v84, v37
	v_mul_f32_e32 v37, 0xbfb8aa3b, v83
	v_exp_f32_e32 v85, v37
	s_nop 0
	v_pk_add_f32 v[84:85], v[84:85], 1.0 op_sel_hi:[1,0]
	s_nop 0
	v_div_scale_f32 v37, s[40:41], v85, v85, v83
	v_rcp_f32_e32 v94, v37
	s_nop 0
	v_fma_f32 v95, -v37, v94, 1.0
	v_fmac_f32_e32 v94, v95, v94
	v_div_scale_f32 v95, vcc, v83, v85, v83
	v_mul_f32_e32 v96, v95, v94
	v_fma_f32 v97, -v37, v96, v95
	v_fmac_f32_e32 v96, v97, v94
	v_fma_f32 v37, -v37, v96, v95
	v_div_fmas_f32 v37, v37, v94, v96
	v_div_fixup_f32 v85, v37, v85, v83
	v_div_scale_f32 v37, s[40:41], v84, v84, v82
	v_rcp_f32_e32 v83, v37
	s_nop 0
	v_fma_f32 v94, -v37, v83, 1.0
	v_fmac_f32_e32 v83, v94, v83
	v_div_scale_f32 v94, vcc, v82, v84, v82
	v_mul_f32_e32 v95, v94, v83
	v_fma_f32 v96, -v37, v95, v94
	v_fmac_f32_e32 v95, v96, v83
	v_fma_f32 v37, -v37, v95, v94
	v_div_fmas_f32 v37, v37, v83, v95
	v_div_fixup_f32 v84, v37, v84, v82
	s_cbranch_scc1 .LBB0_589
	v_pk_mul_f32 v[82:83], v[84:85], v[84:85]
	s_nop 0
	v_add_f32_e32 v37, v82, v83
	v_and_b32_e32 v82, 64, v150
	v_add_u32_e32 v82, 64, v82
	v_add_f32_dpp v37, v37, v37 quad_perm:[1,0,3,2] row_mask:0xf bank_mask:0xf bound_ctrl:1
	v_cmp_lt_i32_e32 vcc, v151, v82
	s_nop 0
	v_add_f32_dpp v37, v37, v37 quad_perm:[2,3,0,1] row_mask:0xf bank_mask:0xf bound_ctrl:1
	v_cndmask_b32_e32 v83, v150, v151, vcc
	v_lshlrev_b32_e32 v83, 2, v83
	v_add_f32_dpp v37, v37, v37 row_half_mirror row_mask:0xf bank_mask:0xf bound_ctrl:1
	s_nop 1
	v_add_f32_dpp v37, v37, v37 row_mirror row_mask:0xf bank_mask:0xf bound_ctrl:1
	v_mov_b32_e32 v83, v37
	v_mov_b32_e32 v255, v37
	s_nop 1
	v_permlane16_swap_b32_e32 v83, v255
	s_nop 1
	v_add_f32_e32 v37, v83, v255
	v_xor_b32_e32 v83, 32, v150
	v_cmp_lt_i32_e32 vcc, v83, v82
	s_nop 1
	v_cndmask_b32_e32 v82, v150, v83, vcc
	v_lshlrev_b32_e32 v82, 2, v82
	v_mov_b32_e32 v82, v37
	v_mov_b32_e32 v255, v37
	s_nop 1
	v_permlane32_swap_b32_e32 v82, v255
	s_nop 1
	v_add_f32_e32 v37, v82, v255
	v_add_f32_e32 v37, 0x358637bd, v37
	v_mul_f32_e32 v82, 0x4b800000, v37
	v_cmp_gt_f32_e32 vcc, s84, v37
	s_nop 1
	v_cndmask_b32_e32 v37, v37, v82, vcc
	v_rsq_f32_e32 v37, v37
	s_nop 0
	v_mul_f32_e32 v82, 0x45800000, v37
	v_cndmask_b32_e32 v37, v37, v82, vcc
	v_mul_f32_e32 v82, 0x3db504f3, v37
	v_cndmask_b32_e64 v82, v37, v82, s[38:39]
	v_pk_mul_f32 v[84:85], v[84:85], v[82:83] op_sel_hi:[1,0]
.LBB0_589:
	v_pk_fma_f32 v[80:81], v[80:81], v[68:69], 0 op_sel_hi:[1,1,0]
	v_and_b32_e32 v83, 0xffff0000, v93
	v_pk_fma_f32 v[80:81], v[78:79], v[70:71], v[80:81]
	v_lshlrev_b32_e32 v82, 16, v93
	v_pk_fma_f32 v[80:81], v[72:73], v[76:77], v[80:81]
	v_cvt_pk_bf16_f32 v37, v84, v85
	v_lshl_add_u64 v[84:85], v[58:59], 0, v[40:41]
	v_pk_fma_f32 v[80:81], v[74:75], v[82:83], v[80:81]
	global_store_dword v[84:85], v37, off
	v_mul_f32_e32 v37, 0xbfb8aa3b, v80
	v_exp_f32_e32 v84, v37
	v_mul_f32_e32 v37, 0xbfb8aa3b, v81
	v_exp_f32_e32 v85, v37
	s_nop 0
	v_pk_add_f32 v[84:85], v[84:85], 1.0 op_sel_hi:[1,0]
	s_nop 0
	v_div_scale_f32 v37, s[40:41], v85, v85, v81
	v_rcp_f32_e32 v93, v37
	s_nop 0
	v_fma_f32 v94, -v37, v93, 1.0
	v_fmac_f32_e32 v93, v94, v93
	v_div_scale_f32 v94, vcc, v81, v85, v81
	v_mul_f32_e32 v95, v94, v93
	v_fma_f32 v96, -v37, v95, v94
	v_fmac_f32_e32 v95, v96, v93
	v_fma_f32 v37, -v37, v95, v94
	v_div_fmas_f32 v37, v37, v93, v95
	v_div_fixup_f32 v85, v37, v85, v81
	v_div_scale_f32 v37, s[40:41], v84, v84, v80
	v_rcp_f32_e32 v81, v37
	s_nop 0
	v_fma_f32 v93, -v37, v81, 1.0
	v_fmac_f32_e32 v81, v93, v81
	v_div_scale_f32 v93, vcc, v80, v84, v80
	v_mul_f32_e32 v94, v93, v81
	v_fma_f32 v95, -v37, v94, v93
	v_fmac_f32_e32 v94, v95, v81
	v_fma_f32 v37, -v37, v94, v93
	v_div_fmas_f32 v37, v37, v81, v94
	v_div_fixup_f32 v84, v37, v84, v80
	v_cndmask_b32_e64 v37, 0, 1, s[46:47]
	v_cmp_ne_u32_e64 s[40:41], 1, v37
	s_andn2_b64 vcc, exec, s[46:47]
	s_cbranch_vccnz .LBB0_591
	v_pk_mul_f32 v[80:81], v[84:85], v[84:85]
	s_nop 0
	v_add_f32_e32 v37, v80, v81
	v_and_b32_e32 v80, 64, v150
	v_add_u32_e32 v80, 64, v80
	v_add_f32_dpp v37, v37, v37 quad_perm:[1,0,3,2] row_mask:0xf bank_mask:0xf bound_ctrl:1
	v_cmp_lt_i32_e32 vcc, v151, v80
	s_nop 0
	v_add_f32_dpp v37, v37, v37 quad_perm:[2,3,0,1] row_mask:0xf bank_mask:0xf bound_ctrl:1
	v_cndmask_b32_e32 v81, v150, v151, vcc
	v_lshlrev_b32_e32 v81, 2, v81
	v_add_f32_dpp v37, v37, v37 row_half_mirror row_mask:0xf bank_mask:0xf bound_ctrl:1
	s_nop 1
	v_add_f32_dpp v37, v37, v37 row_mirror row_mask:0xf bank_mask:0xf bound_ctrl:1
	v_mov_b32_e32 v81, v37
	v_mov_b32_e32 v255, v37
	s_nop 1
	v_permlane16_swap_b32_e32 v81, v255
	s_nop 1
	v_add_f32_e32 v37, v81, v255
	v_xor_b32_e32 v81, 32, v150
	v_cmp_lt_i32_e32 vcc, v81, v80
	s_nop 1
	v_cndmask_b32_e32 v80, v150, v81, vcc
	v_lshlrev_b32_e32 v80, 2, v80
	v_mov_b32_e32 v80, v37
	v_mov_b32_e32 v255, v37
	s_nop 1
	v_permlane32_swap_b32_e32 v80, v255
	s_nop 1
	v_add_f32_e32 v37, v80, v255
	v_add_f32_e32 v37, 0x358637bd, v37
	v_mul_f32_e32 v80, 0x4b800000, v37
	v_cmp_gt_f32_e32 vcc, s84, v37
	s_nop 1
	v_cndmask_b32_e32 v37, v37, v80, vcc
	v_rsq_f32_e32 v37, v37
	s_nop 0
	v_mul_f32_e32 v80, 0x45800000, v37
	v_cndmask_b32_e32 v37, v37, v80, vcc
	v_mul_f32_e32 v80, 0x3db504f3, v37
	v_cndmask_b32_e64 v80, v37, v80, s[38:39]
	v_pk_mul_f32 v[84:85], v[84:85], v[80:81] op_sel_hi:[1,0]
.LBB0_591:
	v_pk_fma_f32 v[78:79], v[78:79], v[68:69], 0 op_sel_hi:[1,1,0]
	v_and_b32_e32 v81, 0xffff0000, v92
	v_pk_fma_f32 v[78:79], v[70:71], v[76:77], v[78:79]
	v_lshlrev_b32_e32 v80, 16, v92
	v_pk_fma_f32 v[78:79], v[72:73], v[82:83], v[78:79]
	v_cvt_pk_bf16_f32 v37, v84, v85
	v_lshl_add_u64 v[84:85], v[58:59], 0, v[42:43]
	v_pk_fma_f32 v[78:79], v[74:75], v[80:81], v[78:79]
	global_store_dword v[84:85], v37, off
	v_mul_f32_e32 v37, 0xbfb8aa3b, v78
	v_exp_f32_e32 v84, v37
	v_mul_f32_e32 v37, 0xbfb8aa3b, v79
	v_exp_f32_e32 v85, v37
	s_nop 0
	v_pk_add_f32 v[84:85], v[84:85], 1.0 op_sel_hi:[1,0]
	s_nop 0
	v_div_scale_f32 v37, s[46:47], v85, v85, v79
	v_rcp_f32_e32 v92, v37
	s_nop 0
	v_fma_f32 v93, -v37, v92, 1.0
	v_fmac_f32_e32 v92, v93, v92
	v_div_scale_f32 v93, vcc, v79, v85, v79
	v_mul_f32_e32 v94, v93, v92
	v_fma_f32 v95, -v37, v94, v93
	v_fmac_f32_e32 v94, v95, v92
	v_fma_f32 v37, -v37, v94, v93
	v_div_fmas_f32 v37, v37, v92, v94
	v_div_fixup_f32 v85, v37, v85, v79
	v_div_scale_f32 v37, s[46:47], v84, v84, v78
	v_rcp_f32_e32 v79, v37
	s_nop 0
	v_fma_f32 v92, -v37, v79, 1.0
	v_fmac_f32_e32 v79, v92, v79
	v_div_scale_f32 v92, vcc, v78, v84, v78
	v_mul_f32_e32 v93, v92, v79
	v_fma_f32 v94, -v37, v93, v92
	v_fmac_f32_e32 v93, v94, v79
	v_fma_f32 v37, -v37, v93, v92
	v_div_fmas_f32 v37, v37, v79, v93
	v_div_fixup_f32 v84, v37, v84, v78
	s_and_b64 vcc, exec, s[40:41]
	s_cbranch_vccnz .LBB0_593
	v_pk_mul_f32 v[78:79], v[84:85], v[84:85]
	s_nop 0
	v_add_f32_e32 v37, v78, v79
	v_and_b32_e32 v78, 64, v150
	v_add_u32_e32 v78, 64, v78
	v_add_f32_dpp v37, v37, v37 quad_perm:[1,0,3,2] row_mask:0xf bank_mask:0xf bound_ctrl:1
	v_cmp_lt_i32_e32 vcc, v151, v78
	s_nop 0
	v_add_f32_dpp v37, v37, v37 quad_perm:[2,3,0,1] row_mask:0xf bank_mask:0xf bound_ctrl:1
	v_cndmask_b32_e32 v79, v150, v151, vcc
	v_lshlrev_b32_e32 v79, 2, v79
	v_add_f32_dpp v37, v37, v37 row_half_mirror row_mask:0xf bank_mask:0xf bound_ctrl:1
	s_nop 1
	v_add_f32_dpp v37, v37, v37 row_mirror row_mask:0xf bank_mask:0xf bound_ctrl:1
	v_mov_b32_e32 v79, v37
	v_mov_b32_e32 v255, v37
	s_nop 1
	v_permlane16_swap_b32_e32 v79, v255
	s_nop 1
	v_add_f32_e32 v37, v79, v255
	v_xor_b32_e32 v79, 32, v150
	v_cmp_lt_i32_e32 vcc, v79, v78
	s_nop 1
	v_cndmask_b32_e32 v78, v150, v79, vcc
	v_lshlrev_b32_e32 v78, 2, v78
	v_mov_b32_e32 v78, v37
	v_mov_b32_e32 v255, v37
	s_nop 1
	v_permlane32_swap_b32_e32 v78, v255
	s_nop 1
	v_add_f32_e32 v37, v78, v255
	v_add_f32_e32 v37, 0x358637bd, v37
	v_mul_f32_e32 v78, 0x4b800000, v37
	v_cmp_gt_f32_e32 vcc, s84, v37
	s_nop 1
	v_cndmask_b32_e32 v37, v37, v78, vcc
	v_rsq_f32_e32 v37, v37
	s_nop 0
	v_mul_f32_e32 v78, 0x45800000, v37
	v_cndmask_b32_e32 v37, v37, v78, vcc
	v_mul_f32_e32 v78, 0x3db504f3, v37
	v_cndmask_b32_e64 v78, v37, v78, s[38:39]
	v_pk_mul_f32 v[84:85], v[84:85], v[78:79] op_sel_hi:[1,0]
.LBB0_593:
	v_pk_fma_f32 v[76:77], v[68:69], v[76:77], 0 op_sel_hi:[1,1,0]
	v_and_b32_e32 v79, 0xffff0000, v91
	v_pk_fma_f32 v[76:77], v[70:71], v[82:83], v[76:77]
	v_lshlrev_b32_e32 v78, 16, v91
	v_pk_fma_f32 v[76:77], v[72:73], v[80:81], v[76:77]
	v_cvt_pk_bf16_f32 v37, v84, v85
	v_lshl_add_u64 v[84:85], v[58:59], 0, v[44:45]
	v_pk_fma_f32 v[76:77], v[74:75], v[78:79], v[76:77]
	global_store_dword v[84:85], v37, off
	v_mul_f32_e32 v37, 0xbfb8aa3b, v76
	v_exp_f32_e32 v84, v37
	v_mul_f32_e32 v37, 0xbfb8aa3b, v77
	v_exp_f32_e32 v85, v37
	s_nop 0
	v_pk_add_f32 v[84:85], v[84:85], 1.0 op_sel_hi:[1,0]
	s_nop 0
	v_div_scale_f32 v37, s[46:47], v85, v85, v77
	v_rcp_f32_e32 v91, v37
	s_nop 0
	v_fma_f32 v92, -v37, v91, 1.0
	v_fmac_f32_e32 v91, v92, v91
	v_div_scale_f32 v92, vcc, v77, v85, v77
	v_mul_f32_e32 v93, v92, v91
	v_fma_f32 v94, -v37, v93, v92
	v_fmac_f32_e32 v93, v94, v91
	v_fma_f32 v37, -v37, v93, v92
	v_div_fmas_f32 v37, v37, v91, v93
	v_div_fixup_f32 v85, v37, v85, v77
	v_div_scale_f32 v37, s[46:47], v84, v84, v76
	v_rcp_f32_e32 v77, v37
	s_nop 0
	v_fma_f32 v91, -v37, v77, 1.0
	v_fmac_f32_e32 v77, v91, v77
	v_div_scale_f32 v91, vcc, v76, v84, v76
	v_mul_f32_e32 v92, v91, v77
	v_fma_f32 v93, -v37, v92, v91
	v_fmac_f32_e32 v92, v93, v77
	v_fma_f32 v37, -v37, v92, v91
	v_div_fmas_f32 v37, v37, v77, v92
	v_div_fixup_f32 v84, v37, v84, v76
	s_and_b64 vcc, exec, s[40:41]
	s_cbranch_vccnz .LBB0_595
	v_pk_mul_f32 v[76:77], v[84:85], v[84:85]
	s_nop 0
	v_add_f32_e32 v37, v76, v77
	v_and_b32_e32 v76, 64, v150
	v_add_u32_e32 v76, 64, v76
	v_add_f32_dpp v37, v37, v37 quad_perm:[1,0,3,2] row_mask:0xf bank_mask:0xf bound_ctrl:1
	v_cmp_lt_i32_e32 vcc, v151, v76
	s_nop 0
	v_add_f32_dpp v37, v37, v37 quad_perm:[2,3,0,1] row_mask:0xf bank_mask:0xf bound_ctrl:1
	v_cndmask_b32_e32 v77, v150, v151, vcc
	v_lshlrev_b32_e32 v77, 2, v77
	v_add_f32_dpp v37, v37, v37 row_half_mirror row_mask:0xf bank_mask:0xf bound_ctrl:1
	s_nop 1
	v_add_f32_dpp v37, v37, v37 row_mirror row_mask:0xf bank_mask:0xf bound_ctrl:1
	v_mov_b32_e32 v77, v37
	v_mov_b32_e32 v255, v37
	s_nop 1
	v_permlane16_swap_b32_e32 v77, v255
	s_nop 1
	v_add_f32_e32 v37, v77, v255
	v_xor_b32_e32 v77, 32, v150
	v_cmp_lt_i32_e32 vcc, v77, v76
	s_nop 1
	v_cndmask_b32_e32 v76, v150, v77, vcc
	v_lshlrev_b32_e32 v76, 2, v76
	v_mov_b32_e32 v76, v37
	v_mov_b32_e32 v255, v37
	s_nop 1
	v_permlane32_swap_b32_e32 v76, v255
	s_nop 1
	v_add_f32_e32 v37, v76, v255
	v_add_f32_e32 v37, 0x358637bd, v37
	v_mul_f32_e32 v76, 0x4b800000, v37
	v_cmp_gt_f32_e32 vcc, s84, v37
	s_nop 1
	v_cndmask_b32_e32 v37, v37, v76, vcc
	v_rsq_f32_e32 v37, v37
	s_nop 0
	v_mul_f32_e32 v76, 0x45800000, v37
	v_cndmask_b32_e32 v37, v37, v76, vcc
	v_mul_f32_e32 v76, 0x3db504f3, v37
	v_cndmask_b32_e64 v76, v37, v76, s[38:39]
	v_pk_mul_f32 v[84:85], v[84:85], v[76:77] op_sel_hi:[1,0]
.LBB0_595:
	v_pk_fma_f32 v[82:83], v[68:69], v[82:83], 0 op_sel_hi:[1,1,0]
	v_and_b32_e32 v77, 0xffff0000, v90
	v_pk_fma_f32 v[82:83], v[70:71], v[80:81], v[82:83]
	v_lshlrev_b32_e32 v76, 16, v90
	v_pk_fma_f32 v[82:83], v[72:73], v[78:79], v[82:83]
	v_cvt_pk_bf16_f32 v37, v84, v85
	v_lshl_add_u64 v[84:85], v[58:59], 0, v[46:47]
	v_pk_fma_f32 v[82:83], v[74:75], v[76:77], v[82:83]
	global_store_dword v[84:85], v37, off
	v_mul_f32_e32 v37, 0xbfb8aa3b, v82
	v_exp_f32_e32 v84, v37
	v_mul_f32_e32 v37, 0xbfb8aa3b, v83
	v_exp_f32_e32 v85, v37
	s_nop 0
	v_pk_add_f32 v[84:85], v[84:85], 1.0 op_sel_hi:[1,0]
	s_nop 0
	v_div_scale_f32 v37, s[46:47], v85, v85, v83
	v_rcp_f32_e32 v90, v37
	s_nop 0
	v_fma_f32 v91, -v37, v90, 1.0
	v_fmac_f32_e32 v90, v91, v90
	v_div_scale_f32 v91, vcc, v83, v85, v83
	v_mul_f32_e32 v92, v91, v90
	v_fma_f32 v93, -v37, v92, v91
	v_fmac_f32_e32 v92, v93, v90
	v_fma_f32 v37, -v37, v92, v91
	v_div_fmas_f32 v37, v37, v90, v92
	v_div_fixup_f32 v85, v37, v85, v83
	v_div_scale_f32 v37, s[46:47], v84, v84, v82
	v_rcp_f32_e32 v83, v37
	s_nop 0
	v_fma_f32 v90, -v37, v83, 1.0
	v_fmac_f32_e32 v83, v90, v83
	v_div_scale_f32 v90, vcc, v82, v84, v82
	v_mul_f32_e32 v91, v90, v83
	v_fma_f32 v92, -v37, v91, v90
	v_fmac_f32_e32 v91, v92, v83
	v_fma_f32 v37, -v37, v91, v90
	v_div_fmas_f32 v37, v37, v83, v91
	v_div_fixup_f32 v84, v37, v84, v82
	s_and_b64 vcc, exec, s[40:41]
	s_cbranch_vccnz .LBB0_597
	v_pk_mul_f32 v[82:83], v[84:85], v[84:85]
	s_nop 0
	v_add_f32_e32 v37, v82, v83
	v_and_b32_e32 v82, 64, v150
	v_add_u32_e32 v82, 64, v82
	v_add_f32_dpp v37, v37, v37 quad_perm:[1,0,3,2] row_mask:0xf bank_mask:0xf bound_ctrl:1
	v_cmp_lt_i32_e32 vcc, v151, v82
	s_nop 0
	v_add_f32_dpp v37, v37, v37 quad_perm:[2,3,0,1] row_mask:0xf bank_mask:0xf bound_ctrl:1
	v_cndmask_b32_e32 v83, v150, v151, vcc
	v_lshlrev_b32_e32 v83, 2, v83
	v_add_f32_dpp v37, v37, v37 row_half_mirror row_mask:0xf bank_mask:0xf bound_ctrl:1
	s_nop 1
	v_add_f32_dpp v37, v37, v37 row_mirror row_mask:0xf bank_mask:0xf bound_ctrl:1
	v_mov_b32_e32 v83, v37
	v_mov_b32_e32 v255, v37
	s_nop 1
	v_permlane16_swap_b32_e32 v83, v255
	s_nop 1
	v_add_f32_e32 v37, v83, v255
	v_xor_b32_e32 v83, 32, v150
	v_cmp_lt_i32_e32 vcc, v83, v82
	s_nop 1
	v_cndmask_b32_e32 v82, v150, v83, vcc
	v_lshlrev_b32_e32 v82, 2, v82
	v_mov_b32_e32 v82, v37
	v_mov_b32_e32 v255, v37
	s_nop 1
	v_permlane32_swap_b32_e32 v82, v255
	s_nop 1
	v_add_f32_e32 v37, v82, v255
	v_add_f32_e32 v37, 0x358637bd, v37
	v_mul_f32_e32 v82, 0x4b800000, v37
	v_cmp_gt_f32_e32 vcc, s84, v37
	s_nop 1
	v_cndmask_b32_e32 v37, v37, v82, vcc
	v_rsq_f32_e32 v37, v37
	s_nop 0
	v_mul_f32_e32 v82, 0x45800000, v37
	v_cndmask_b32_e32 v37, v37, v82, vcc
	v_mul_f32_e32 v82, 0x3db504f3, v37
	v_cndmask_b32_e64 v82, v37, v82, s[38:39]
	v_pk_mul_f32 v[84:85], v[84:85], v[82:83] op_sel_hi:[1,0]
.LBB0_597:
	v_pk_fma_f32 v[80:81], v[68:69], v[80:81], 0 op_sel_hi:[1,1,0]
	v_and_b32_e32 v83, 0xffff0000, v87
	v_pk_fma_f32 v[80:81], v[70:71], v[78:79], v[80:81]
	v_lshlrev_b32_e32 v82, 16, v87
	v_pk_fma_f32 v[80:81], v[72:73], v[76:77], v[80:81]
	v_cvt_pk_bf16_f32 v37, v84, v85
	v_lshl_add_u64 v[84:85], v[58:59], 0, v[48:49]
	v_pk_fma_f32 v[80:81], v[74:75], v[82:83], v[80:81]
	global_store_dword v[84:85], v37, off
	v_mul_f32_e32 v37, 0xbfb8aa3b, v80
	v_exp_f32_e32 v84, v37
	v_mul_f32_e32 v37, 0xbfb8aa3b, v81
	v_exp_f32_e32 v85, v37
	s_nop 0
	v_pk_add_f32 v[84:85], v[84:85], 1.0 op_sel_hi:[1,0]
	s_nop 0
	v_div_scale_f32 v37, s[46:47], v85, v85, v81
	v_rcp_f32_e32 v87, v37
	s_nop 0
	v_fma_f32 v90, -v37, v87, 1.0
	v_fmac_f32_e32 v87, v90, v87
	v_div_scale_f32 v90, vcc, v81, v85, v81
	v_mul_f32_e32 v91, v90, v87
	v_fma_f32 v92, -v37, v91, v90
	v_fmac_f32_e32 v91, v92, v87
	v_fma_f32 v37, -v37, v91, v90
	v_div_fmas_f32 v37, v37, v87, v91
	v_div_fixup_f32 v81, v37, v85, v81
	v_div_scale_f32 v37, s[46:47], v84, v84, v80
	v_rcp_f32_e32 v85, v37
	s_nop 0
	v_fma_f32 v87, -v37, v85, 1.0
	v_fmac_f32_e32 v85, v87, v85
	v_div_scale_f32 v87, vcc, v80, v84, v80
	v_mul_f32_e32 v90, v87, v85
	v_fma_f32 v91, -v37, v90, v87
	v_fmac_f32_e32 v90, v91, v85
	v_fma_f32 v37, -v37, v90, v87
	v_div_fmas_f32 v37, v37, v85, v90
	v_div_fixup_f32 v80, v37, v84, v80
	s_and_b64 vcc, exec, s[40:41]
	s_cbranch_vccnz .LBB0_599
	v_pk_mul_f32 v[84:85], v[80:81], v[80:81]
	s_nop 0
	v_add_f32_e32 v37, v84, v85
	v_and_b32_e32 v84, 64, v150
	v_add_u32_e32 v84, 64, v84
	v_add_f32_dpp v37, v37, v37 quad_perm:[1,0,3,2] row_mask:0xf bank_mask:0xf bound_ctrl:1
	v_cmp_lt_i32_e32 vcc, v151, v84
	s_nop 0
	v_add_f32_dpp v37, v37, v37 quad_perm:[2,3,0,1] row_mask:0xf bank_mask:0xf bound_ctrl:1
	v_cndmask_b32_e32 v85, v150, v151, vcc
	v_lshlrev_b32_e32 v85, 2, v85
	v_add_f32_dpp v37, v37, v37 row_half_mirror row_mask:0xf bank_mask:0xf bound_ctrl:1
	s_nop 1
	v_add_f32_dpp v37, v37, v37 row_mirror row_mask:0xf bank_mask:0xf bound_ctrl:1
	v_mov_b32_e32 v85, v37
	v_mov_b32_e32 v255, v37
	s_nop 1
	v_permlane16_swap_b32_e32 v85, v255
	s_nop 1
	v_add_f32_e32 v37, v85, v255
	v_xor_b32_e32 v85, 32, v150
	v_cmp_lt_i32_e32 vcc, v85, v84
	s_nop 1
	v_cndmask_b32_e32 v84, v150, v85, vcc
	v_lshlrev_b32_e32 v84, 2, v84
	v_mov_b32_e32 v84, v37
	v_mov_b32_e32 v255, v37
	s_nop 1
	v_permlane32_swap_b32_e32 v84, v255
	s_nop 1
	v_add_f32_e32 v37, v84, v255
	v_add_f32_e32 v37, 0x358637bd, v37
	v_mul_f32_e32 v84, 0x4b800000, v37
	v_cmp_gt_f32_e32 vcc, s84, v37
	s_nop 1
	v_cndmask_b32_e32 v37, v37, v84, vcc
	v_rsq_f32_e32 v37, v37
	s_nop 0
	v_mul_f32_e32 v84, 0x45800000, v37
	v_cndmask_b32_e32 v37, v37, v84, vcc
	v_mul_f32_e32 v84, 0x3db504f3, v37
	v_cndmask_b32_e64 v84, v37, v84, s[38:39]
	v_pk_mul_f32 v[80:81], v[80:81], v[84:85] op_sel_hi:[1,0]
.LBB0_599:
	v_pk_fma_f32 v[78:79], v[68:69], v[78:79], 0 op_sel_hi:[1,1,0]
	v_cvt_pk_bf16_f32 v37, v80, v81
	v_lshl_add_u64 v[80:81], v[58:59], 0, v[50:51]
	v_pk_fma_f32 v[78:79], v[70:71], v[76:77], v[78:79]
	v_and_b32_e32 v85, 0xffff0000, v86
	v_lshlrev_b32_e32 v84, 16, v86
	global_store_dword v[80:81], v37, off
	v_lshl_add_u64 v[80:81], v[60:61], 0, s[44:45]
	v_pk_fma_f32 v[78:79], v[72:73], v[82:83], v[78:79]
	v_add_co_u32_e32 v86, vcc, 0x4a2c000, v80
	v_pk_fma_f32 v[78:79], v[74:75], v[84:85], v[78:79]
	s_nop 0
	v_addc_co_u32_e32 v87, vcc, 0, v81, vcc
	v_mul_f32_e32 v37, 0xbfb8aa3b, v78
	global_store_dwordx2 v[86:87], v[82:83], off offset:256
	v_exp_f32_e32 v86, v37
	v_mul_f32_e32 v37, 0xbfb8aa3b, v79
	v_exp_f32_e32 v87, v37
	s_nop 0
	v_pk_add_f32 v[86:87], v[86:87], 1.0 op_sel_hi:[1,0]
	s_nop 0
	v_div_scale_f32 v37, s[46:47], v87, v87, v79
	v_rcp_f32_e32 v90, v37
	s_nop 0
	v_fma_f32 v91, -v37, v90, 1.0
	v_fmac_f32_e32 v90, v91, v90
	v_div_scale_f32 v91, vcc, v79, v87, v79
	v_mul_f32_e32 v92, v91, v90
	v_fma_f32 v93, -v37, v92, v91
	v_fmac_f32_e32 v92, v93, v90
	v_fma_f32 v37, -v37, v92, v91
	v_div_fmas_f32 v37, v37, v90, v92
	v_div_fixup_f32 v87, v37, v87, v79
	v_div_scale_f32 v37, s[46:47], v86, v86, v78
	v_rcp_f32_e32 v79, v37
	s_nop 0
	v_fma_f32 v90, -v37, v79, 1.0
	v_fmac_f32_e32 v79, v90, v79
	v_div_scale_f32 v90, vcc, v78, v86, v78
	v_mul_f32_e32 v91, v90, v79
	v_fma_f32 v92, -v37, v91, v90
	v_fmac_f32_e32 v91, v92, v79
	v_fma_f32 v37, -v37, v91, v90
	v_div_fmas_f32 v37, v37, v79, v91
	v_div_fixup_f32 v86, v37, v86, v78
	s_and_b64 vcc, exec, s[40:41]
	s_cbranch_vccnz .LBB0_601
	v_pk_mul_f32 v[78:79], v[86:87], v[86:87]
	s_nop 0
	v_add_f32_e32 v37, v78, v79
	v_and_b32_e32 v78, 64, v150
	v_add_u32_e32 v78, 64, v78
	v_add_f32_dpp v37, v37, v37 quad_perm:[1,0,3,2] row_mask:0xf bank_mask:0xf bound_ctrl:1
	v_cmp_lt_i32_e32 vcc, v151, v78
	s_nop 0
	v_add_f32_dpp v37, v37, v37 quad_perm:[2,3,0,1] row_mask:0xf bank_mask:0xf bound_ctrl:1
	v_cndmask_b32_e32 v79, v150, v151, vcc
	v_lshlrev_b32_e32 v79, 2, v79
	v_add_f32_dpp v37, v37, v37 row_half_mirror row_mask:0xf bank_mask:0xf bound_ctrl:1
	s_nop 1
	v_add_f32_dpp v37, v37, v37 row_mirror row_mask:0xf bank_mask:0xf bound_ctrl:1
	v_mov_b32_e32 v79, v37
	v_mov_b32_e32 v255, v37
	s_nop 1
	v_permlane16_swap_b32_e32 v79, v255
	s_nop 1
	v_add_f32_e32 v37, v79, v255
	v_xor_b32_e32 v79, 32, v150
	v_cmp_lt_i32_e32 vcc, v79, v78
	s_nop 1
	v_cndmask_b32_e32 v78, v150, v79, vcc
	v_lshlrev_b32_e32 v78, 2, v78
	v_mov_b32_e32 v78, v37
	v_mov_b32_e32 v255, v37
	s_nop 1
	v_permlane32_swap_b32_e32 v78, v255
	s_nop 1
	v_add_f32_e32 v37, v78, v255
	v_add_f32_e32 v37, 0x358637bd, v37
	v_mul_f32_e32 v78, 0x4b800000, v37
	v_cmp_gt_f32_e32 vcc, s84, v37
	s_nop 1
	v_cndmask_b32_e32 v37, v37, v78, vcc
	v_rsq_f32_e32 v37, v37
	s_nop 0
	v_mul_f32_e32 v78, 0x45800000, v37
	v_cndmask_b32_e32 v37, v37, v78, vcc
	v_mul_f32_e32 v78, 0x3db504f3, v37
	v_cndmask_b32_e64 v78, v37, v78, s[38:39]
	v_pk_mul_f32 v[86:87], v[86:87], v[78:79] op_sel_hi:[1,0]
.LBB0_601:
	v_pk_fma_f32 v[68:69], v[68:69], v[76:77], 0 op_sel_hi:[1,1,0]
	v_and_b32_e32 v79, 0xffff0000, v89
	v_pk_fma_f32 v[68:69], v[70:71], v[82:83], v[68:69]
	v_lshlrev_b32_e32 v78, 16, v89
	v_pk_fma_f32 v[68:69], v[72:73], v[84:85], v[68:69]
	v_cvt_pk_bf16_f32 v37, v86, v87
	v_lshl_add_u64 v[86:87], v[58:59], 0, v[52:53]
	v_pk_fma_f32 v[68:69], v[74:75], v[78:79], v[68:69]
	global_store_dword v[86:87], v37, off
	v_mul_f32_e32 v37, 0xbfb8aa3b, v68
	v_exp_f32_e32 v70, v37
	v_mul_f32_e32 v37, 0xbfb8aa3b, v69
	v_exp_f32_e32 v71, v37
	v_add_co_u32_e32 v86, vcc, 0x4a2d000, v80
	v_pk_add_f32 v[70:71], v[70:71], 1.0 op_sel_hi:[1,0]
	s_nop 0
	v_div_scale_f32 v37, s[46:47], v71, v71, v69
	v_rcp_f32_e32 v72, v37
	v_addc_co_u32_e32 v87, vcc, 0, v81, vcc
	global_store_dwordx2 v[86:87], v[84:85], off offset:2304
	v_fma_f32 v73, -v37, v72, 1.0
	v_fmac_f32_e32 v72, v73, v72
	v_div_scale_f32 v73, vcc, v69, v71, v69
	v_mul_f32_e32 v74, v73, v72
	v_fma_f32 v75, -v37, v74, v73
	v_fmac_f32_e32 v74, v75, v72
	v_fma_f32 v37, -v37, v74, v73
	v_div_fmas_f32 v37, v37, v72, v74
	v_div_fixup_f32 v69, v37, v71, v69
	v_div_scale_f32 v37, s[46:47], v70, v70, v68
	v_rcp_f32_e32 v71, v37
	s_nop 0
	v_fma_f32 v72, -v37, v71, 1.0
	v_fmac_f32_e32 v71, v72, v71
	v_div_scale_f32 v72, vcc, v68, v70, v68
	v_mul_f32_e32 v73, v72, v71
	v_fma_f32 v74, -v37, v73, v72
	v_fmac_f32_e32 v73, v74, v71
	v_fma_f32 v37, -v37, v73, v72
	v_div_fmas_f32 v37, v37, v71, v73
	v_div_fixup_f32 v68, v37, v70, v68
	s_and_b64 vcc, exec, s[40:41]
	s_cbranch_vccnz .LBB0_586
	v_pk_mul_f32 v[70:71], v[68:69], v[68:69]
	s_nop 0
	v_add_f32_e32 v37, v70, v71
	v_and_b32_e32 v70, 64, v150
	v_add_u32_e32 v70, 64, v70
	v_add_f32_dpp v37, v37, v37 quad_perm:[1,0,3,2] row_mask:0xf bank_mask:0xf bound_ctrl:1
	v_cmp_lt_i32_e32 vcc, v151, v70
	s_nop 0
	v_add_f32_dpp v37, v37, v37 quad_perm:[2,3,0,1] row_mask:0xf bank_mask:0xf bound_ctrl:1
	v_cndmask_b32_e32 v71, v150, v151, vcc
	v_lshlrev_b32_e32 v71, 2, v71
	v_add_f32_dpp v37, v37, v37 row_half_mirror row_mask:0xf bank_mask:0xf bound_ctrl:1
	s_nop 1
	v_add_f32_dpp v37, v37, v37 row_mirror row_mask:0xf bank_mask:0xf bound_ctrl:1
	v_mov_b32_e32 v71, v37
	v_mov_b32_e32 v255, v37
	s_nop 1
	v_permlane16_swap_b32_e32 v71, v255
	s_nop 1
	v_add_f32_e32 v37, v71, v255
	v_xor_b32_e32 v71, 32, v150
	v_cmp_lt_i32_e32 vcc, v71, v70
	s_nop 1
	v_cndmask_b32_e32 v70, v150, v71, vcc
	v_lshlrev_b32_e32 v70, 2, v70
	v_mov_b32_e32 v70, v37
	v_mov_b32_e32 v255, v37
	s_nop 1
	v_permlane32_swap_b32_e32 v70, v255
	s_nop 1
	v_add_f32_e32 v37, v70, v255
	v_add_f32_e32 v37, 0x358637bd, v37
	v_mul_f32_e32 v70, 0x4b800000, v37
	v_cmp_gt_f32_e32 vcc, s84, v37
	s_nop 1
	v_cndmask_b32_e32 v37, v37, v70, vcc
	v_rsq_f32_e32 v37, v37
	s_nop 0
	v_mul_f32_e32 v70, 0x45800000, v37
	v_cndmask_b32_e32 v37, v37, v70, vcc
	v_mul_f32_e32 v70, 0x3db504f3, v37
	v_cndmask_b32_e64 v70, v37, v70, s[38:39]
	v_pk_mul_f32 v[68:69], v[68:69], v[70:71] op_sel_hi:[1,0]
	s_branch .LBB0_586

.LBB0_634:
	s_or_b64 exec, exec, s[46:47]
	v_lshlrev_b64 v[64:65], 1, v[0:1]
	v_lshl_add_u64 v[66:67], v[2:3], 0, v[64:65]
	s_waitcnt vmcnt(15)
	v_and_b32_e32 v79, 0xffff0000, v25
	v_lshlrev_b32_e32 v78, 16, v25
	global_load_dword v25, v[66:67], off offset:1536
	v_lshl_add_u64 v[66:67], v[4:5], 0, v[64:65]
	global_load_dword v0, v[66:67], off offset:1536
	v_lshl_add_u64 v[66:67], v[6:7], 0, v[64:65]
	global_load_dword v87, v[66:67], off offset:1536
	v_lshl_add_u64 v[66:67], v[8:9], 0, v[64:65]
	global_load_dword v88, v[66:67], off offset:1536
	v_lshl_add_u64 v[66:67], v[10:11], 0, v[64:65]
	global_load_dword v89, v[66:67], off offset:1536
	v_lshl_add_u64 v[66:67], v[12:13], 0, v[64:65]
	global_load_dword v91, v[66:67], off offset:1536
	v_lshl_add_u64 v[66:67], v[14:15], 0, v[64:65]
	global_load_dword v93, v[66:67], off offset:1536
	v_lshl_add_u64 v[66:67], v[16:17], 0, v[64:65]
	global_load_dword v95, v[66:67], off offset:1536
	v_lshl_add_u64 v[66:67], v[18:19], 0, v[64:65]
	global_load_dword v97, v[66:67], off offset:1536
	v_lshl_add_u64 v[66:67], v[20:21], 0, v[64:65]
	global_load_dword v99, v[66:67], off offset:1536
	v_lshl_add_u64 v[66:67], v[40:41], 0, v[64:65]
	global_load_dword v90, v[66:67], off offset:1536
	v_lshl_add_u64 v[66:67], v[42:43], 0, v[64:65]
	global_load_dword v92, v[66:67], off offset:1536
	v_lshl_add_u64 v[66:67], v[44:45], 0, v[64:65]
	global_load_dword v94, v[66:67], off offset:1536
	v_lshl_add_u64 v[66:67], v[46:47], 0, v[64:65]
	global_load_dword v96, v[66:67], off offset:1536
	v_lshl_add_u64 v[66:67], v[48:49], 0, v[64:65]
	v_lshl_add_u64 v[64:65], v[50:51], 0, v[64:65]
	v_lshl_add_u64 v[70:71], s[52:53], 0, v[38:39]
	global_load_dword v98, v[66:67], off offset:1536
	global_load_dword v100, v[64:65], off offset:1536
	v_add_co_u32_e32 v66, vcc, s93, v70
	global_load_dwordx2 v[64:65], v[70:71], off
	s_nop 0
	v_addc_co_u32_e32 v67, vcc, 0, v71, vcc
	v_add_co_u32_e32 v68, vcc, s95, v70
	global_load_dwordx2 v[66:67], v[66:67], off offset:2048
	s_nop 0
	v_addc_co_u32_e32 v69, vcc, 0, v71, vcc
	global_load_dwordx2 v[68:69], v[68:69], off
	v_add_co_u32_e32 v70, vcc, s86, v70
	s_cmp_lt_u32 s81, 8
	s_nop 0
	v_addc_co_u32_e32 v71, vcc, 0, v71, vcc
	global_load_dwordx2 v[70:71], v[70:71], off offset:2048
	s_cselect_b64 s[74:75], -1, 0
	s_cmp_lt_u32 s81, 4
	s_cselect_b64 s[46:47], -1, 0
	s_cmp_gt_u32 s81, 7
	s_waitcnt vmcnt(3)
	v_pk_fma_f32 v[72:73], v[72:73], v[64:65], 0 op_sel_hi:[1,1,0]
	s_waitcnt vmcnt(2)
	v_pk_fma_f32 v[72:73], v[76:77], v[66:67], v[72:73]
	s_waitcnt vmcnt(1)
	v_pk_fma_f32 v[72:73], v[74:75], v[68:69], v[72:73]
	s_waitcnt vmcnt(0)
	v_pk_fma_f32 v[72:73], v[70:71], v[78:79], v[72:73]
	s_nop 0
	v_mul_f32_e32 v83, 0xbfb8aa3b, v72
	v_exp_f32_e32 v84, v83
	v_mul_f32_e32 v83, 0xbfb8aa3b, v73
	v_exp_f32_e32 v85, v83
	s_nop 0
	v_pk_add_f32 v[84:85], v[84:85], 1.0 op_sel_hi:[1,0]
	s_nop 0
	v_div_scale_f32 v83, s[48:49], v85, v85, v73
	v_rcp_f32_e32 v112, v83
	s_nop 0
	v_fma_f32 v113, -v83, v112, 1.0
	v_fmac_f32_e32 v112, v113, v112
	v_div_scale_f32 v113, vcc, v73, v85, v73
	v_mul_f32_e32 v114, v113, v112
	v_fma_f32 v115, -v83, v114, v113
	v_fmac_f32_e32 v114, v115, v112
	v_fma_f32 v83, -v83, v114, v113
	v_div_fmas_f32 v83, v83, v112, v114
	v_div_fixup_f32 v73, v83, v85, v73
	v_div_scale_f32 v83, s[48:49], v84, v84, v72
	v_rcp_f32_e32 v85, v83
	s_nop 0
	v_fma_f32 v112, -v83, v85, 1.0
	v_fmac_f32_e32 v85, v112, v85
	v_div_scale_f32 v112, vcc, v72, v84, v72
	v_mul_f32_e32 v113, v112, v85
	v_fma_f32 v114, -v83, v113, v112
	v_fmac_f32_e32 v113, v114, v85
	v_fma_f32 v83, -v83, v113, v112
	v_div_fmas_f32 v83, v83, v85, v113
	v_div_fixup_f32 v72, v83, v84, v72
	s_cbranch_scc1 .LBB0_636
	v_pk_mul_f32 v[84:85], v[72:73], v[72:73]
	s_nop 0
	v_add_f32_e32 v83, v84, v85
	v_and_b32_e32 v84, 64, v150
	v_add_u32_e32 v84, 64, v84
	v_add_f32_dpp v83, v83, v83 quad_perm:[1,0,3,2] row_mask:0xf bank_mask:0xf bound_ctrl:1
	v_cmp_lt_i32_e32 vcc, v151, v84
	s_nop 0
	v_add_f32_dpp v83, v83, v83 quad_perm:[2,3,0,1] row_mask:0xf bank_mask:0xf bound_ctrl:1
	v_cndmask_b32_e32 v85, v150, v151, vcc
	v_lshlrev_b32_e32 v85, 2, v85
	v_add_f32_dpp v83, v83, v83 row_half_mirror row_mask:0xf bank_mask:0xf bound_ctrl:1
	s_nop 1
	v_add_f32_dpp v83, v83, v83 row_mirror row_mask:0xf bank_mask:0xf bound_ctrl:1
	v_mov_b32_e32 v85, v83
	v_mov_b32_e32 v255, v83
	s_nop 1
	v_permlane16_swap_b32_e32 v85, v255
	s_nop 1
	v_add_f32_e32 v83, v85, v255
	v_xor_b32_e32 v85, 32, v150
	v_cmp_lt_i32_e32 vcc, v85, v84
	s_nop 1
	v_cndmask_b32_e32 v84, v150, v85, vcc
	v_lshlrev_b32_e32 v84, 2, v84
	v_mov_b32_e32 v84, v83
	v_mov_b32_e32 v255, v83
	s_nop 1
	v_permlane32_swap_b32_e32 v84, v255
	s_nop 1
	v_add_f32_e32 v83, v84, v255
	v_add_f32_e32 v83, 0x358637bd, v83
	v_mul_f32_e32 v84, 0x4b800000, v83
	v_cmp_gt_f32_e32 vcc, s84, v83
	s_nop 1
	v_cndmask_b32_e32 v83, v83, v84, vcc
	v_rsq_f32_e32 v83, v83
	s_nop 0
	v_mul_f32_e32 v84, 0x45800000, v83
	v_cndmask_b32_e32 v83, v83, v84, vcc
	v_mul_f32_e32 v84, 0x3db504f3, v83
	v_cndmask_b32_e64 v84, v83, v84, s[46:47]
	v_pk_mul_f32 v[72:73], v[72:73], v[84:85] op_sel_hi:[1,0]
.LBB0_636:
	v_pk_fma_f32 v[76:77], v[76:77], v[64:65], 0 op_sel_hi:[1,1,0]
	v_cvt_pk_bf16_f32 v112, v72, v73
	v_lshl_add_u64 v[72:73], v[60:61], 0, s[58:59]
	v_pk_fma_f32 v[76:77], v[74:75], v[66:67], v[76:77]
	v_and_b32_e32 v85, 0xffff0000, v82
	v_lshlrev_b32_e32 v84, 16, v82
	v_add_co_u32_e32 v82, vcc, 0xc440000, v72
	v_pk_fma_f32 v[76:77], v[68:69], v[78:79], v[76:77]
	s_nop 0
	v_addc_co_u32_e32 v83, vcc, 0, v73, vcc
	v_pk_fma_f32 v[76:77], v[70:71], v[84:85], v[76:77]
	global_store_dword v[82:83], v112, off
	v_mul_f32_e32 v82, 0xbfb8aa3b, v76
	v_mul_f32_e32 v83, 0xbfb8aa3b, v77
	v_exp_f32_e32 v82, v82
	v_exp_f32_e32 v83, v83
	s_nop 0
	v_pk_add_f32 v[82:83], v[82:83], 1.0 op_sel_hi:[1,0]
	s_nop 0
	v_div_scale_f32 v112, s[48:49], v83, v83, v77
	v_rcp_f32_e32 v113, v112
	s_nop 0
	v_fma_f32 v114, -v112, v113, 1.0
	v_fmac_f32_e32 v113, v114, v113
	v_div_scale_f32 v114, vcc, v77, v83, v77
	v_mul_f32_e32 v115, v114, v113
	v_fma_f32 v116, -v112, v115, v114
	v_fmac_f32_e32 v115, v116, v113
	v_fma_f32 v112, -v112, v115, v114
	v_div_fmas_f32 v112, v112, v113, v115
	v_div_fixup_f32 v77, v112, v83, v77
	v_div_scale_f32 v83, s[48:49], v82, v82, v76
	v_rcp_f32_e32 v112, v83
	s_nop 0
	v_fma_f32 v113, -v83, v112, 1.0
	v_fmac_f32_e32 v112, v113, v112
	v_div_scale_f32 v113, vcc, v76, v82, v76
	v_mul_f32_e32 v114, v113, v112
	v_fma_f32 v115, -v83, v114, v113
	v_fmac_f32_e32 v114, v115, v112
	v_fma_f32 v83, -v83, v114, v113
	v_div_fmas_f32 v83, v83, v112, v114
	v_div_fixup_f32 v76, v83, v82, v76
	v_cndmask_b32_e64 v82, 0, 1, s[74:75]
	v_cmp_ne_u32_e64 s[48:49], 1, v82
	s_andn2_b64 vcc, exec, s[74:75]
	s_cbranch_vccnz .LBB0_638
	v_pk_mul_f32 v[82:83], v[76:77], v[76:77]
	s_nop 0
	v_add_f32_e32 v82, v82, v83
	v_and_b32_e32 v83, 64, v150
	v_add_u32_e32 v83, 64, v83
	v_add_f32_dpp v82, v82, v82 quad_perm:[1,0,3,2] row_mask:0xf bank_mask:0xf bound_ctrl:1
	v_cmp_lt_i32_e32 vcc, v151, v83
	s_nop 0
	v_add_f32_dpp v82, v82, v82 quad_perm:[2,3,0,1] row_mask:0xf bank_mask:0xf bound_ctrl:1
	v_cndmask_b32_e32 v112, v150, v151, vcc
	v_lshlrev_b32_e32 v112, 2, v112
	v_add_f32_dpp v82, v82, v82 row_half_mirror row_mask:0xf bank_mask:0xf bound_ctrl:1
	s_nop 1
	v_add_f32_dpp v82, v82, v82 row_mirror row_mask:0xf bank_mask:0xf bound_ctrl:1
	v_mov_b32_e32 v112, v82
	v_mov_b32_e32 v255, v82
	s_nop 1
	v_permlane16_swap_b32_e32 v112, v255
	s_nop 1
	v_add_f32_e32 v82, v112, v255
	v_xor_b32_e32 v112, 32, v150
	v_cmp_lt_i32_e32 vcc, v112, v83
	s_nop 1
	v_cndmask_b32_e32 v83, v150, v112, vcc
	v_lshlrev_b32_e32 v83, 2, v83
	v_mov_b32_e32 v83, v82
	v_mov_b32_e32 v255, v82
	s_nop 1
	v_permlane32_swap_b32_e32 v83, v255
	s_nop 1
	v_add_f32_e32 v82, v83, v255
	v_add_f32_e32 v82, 0x358637bd, v82
	v_mul_f32_e32 v83, 0x4b800000, v82
	v_cmp_gt_f32_e32 vcc, s84, v82
	s_nop 1
	v_cndmask_b32_e32 v82, v82, v83, vcc
	v_rsq_f32_e32 v82, v82
	s_nop 0
	v_mul_f32_e32 v83, 0x45800000, v82
	v_cndmask_b32_e32 v82, v82, v83, vcc
	v_mul_f32_e32 v83, 0x3db504f3, v82
	v_cndmask_b32_e64 v82, v82, v83, s[46:47]
	v_pk_mul_f32 v[76:77], v[76:77], v[82:83] op_sel_hi:[1,0]
.LBB0_638:
	v_pk_fma_f32 v[74:75], v[74:75], v[64:65], 0 op_sel_hi:[1,1,0]
	v_and_b32_e32 v83, 0xffff0000, v81
	v_pk_fma_f32 v[74:75], v[66:67], v[78:79], v[74:75]
	v_lshlrev_b32_e32 v82, 16, v81
	v_cvt_pk_bf16_f32 v81, v76, v77
	v_add_co_u32_e32 v76, vcc, 0xc440000, v72
	v_pk_fma_f32 v[74:75], v[68:69], v[84:85], v[74:75]
	s_nop 0
	v_addc_co_u32_e32 v77, vcc, 0, v73, vcc
	v_pk_fma_f32 v[74:75], v[70:71], v[82:83], v[74:75]
	global_store_dword v[76:77], v81, off offset:3072
	v_mul_f32_e32 v76, 0xbfb8aa3b, v74
	v_mul_f32_e32 v77, 0xbfb8aa3b, v75
	v_exp_f32_e32 v76, v76
	v_exp_f32_e32 v77, v77
	s_nop 0
	v_pk_add_f32 v[76:77], v[76:77], 1.0 op_sel_hi:[1,0]
	s_nop 0
	v_div_scale_f32 v81, s[60:61], v77, v77, v75
	v_rcp_f32_e32 v112, v81
	s_nop 0
	v_fma_f32 v113, -v81, v112, 1.0
	v_fmac_f32_e32 v112, v113, v112
	v_div_scale_f32 v113, vcc, v75, v77, v75
	v_mul_f32_e32 v114, v113, v112
	v_fma_f32 v115, -v81, v114, v113
	v_fmac_f32_e32 v114, v115, v112
	v_fma_f32 v81, -v81, v114, v113
	v_div_fmas_f32 v81, v81, v112, v114
	v_div_fixup_f32 v75, v81, v77, v75
	v_div_scale_f32 v77, s[60:61], v76, v76, v74
	v_rcp_f32_e32 v81, v77
	s_nop 0
	v_fma_f32 v112, -v77, v81, 1.0
	v_fmac_f32_e32 v81, v112, v81
	v_div_scale_f32 v112, vcc, v74, v76, v74
	v_mul_f32_e32 v113, v112, v81
	v_fma_f32 v114, -v77, v113, v112
	v_fmac_f32_e32 v113, v114, v81
	v_fma_f32 v77, -v77, v113, v112
	v_div_fmas_f32 v77, v77, v81, v113
	v_div_fixup_f32 v74, v77, v76, v74
	s_and_b64 vcc, exec, s[48:49]
	s_cbranch_vccnz .LBB0_640
	v_pk_mul_f32 v[76:77], v[74:75], v[74:75]
	s_nop 0
	v_add_f32_e32 v76, v76, v77
	v_and_b32_e32 v77, 64, v150
	v_add_u32_e32 v77, 64, v77
	v_add_f32_dpp v76, v76, v76 quad_perm:[1,0,3,2] row_mask:0xf bank_mask:0xf bound_ctrl:1
	v_cmp_lt_i32_e32 vcc, v151, v77
	s_nop 0
	v_add_f32_dpp v76, v76, v76 quad_perm:[2,3,0,1] row_mask:0xf bank_mask:0xf bound_ctrl:1
	v_cndmask_b32_e32 v81, v150, v151, vcc
	v_lshlrev_b32_e32 v81, 2, v81
	v_add_f32_dpp v76, v76, v76 row_half_mirror row_mask:0xf bank_mask:0xf bound_ctrl:1
	s_nop 1
	v_add_f32_dpp v76, v76, v76 row_mirror row_mask:0xf bank_mask:0xf bound_ctrl:1
	v_mov_b32_e32 v81, v76
	v_mov_b32_e32 v255, v76
	s_nop 1
	v_permlane16_swap_b32_e32 v81, v255
	s_nop 1
	v_add_f32_e32 v76, v81, v255
	v_xor_b32_e32 v81, 32, v150
	v_cmp_lt_i32_e32 vcc, v81, v77
	s_nop 1
	v_cndmask_b32_e32 v77, v150, v81, vcc
	v_lshlrev_b32_e32 v77, 2, v77
	v_mov_b32_e32 v77, v76
	v_mov_b32_e32 v255, v76
	s_nop 1
	v_permlane32_swap_b32_e32 v77, v255
	s_nop 1
	v_add_f32_e32 v76, v77, v255
	v_add_f32_e32 v76, 0x358637bd, v76
	v_mul_f32_e32 v77, 0x4b800000, v76
	v_cmp_gt_f32_e32 vcc, s84, v76
	s_nop 1
	v_cndmask_b32_e32 v76, v76, v77, vcc
	v_rsq_f32_e32 v76, v76
	s_nop 0
	v_mul_f32_e32 v77, 0x45800000, v76
	v_cndmask_b32_e32 v76, v76, v77, vcc
	v_mul_f32_e32 v77, 0x3db504f3, v76
	v_cndmask_b32_e64 v76, v76, v77, s[46:47]
	v_pk_mul_f32 v[74:75], v[74:75], v[76:77] op_sel_hi:[1,0]
.LBB0_640:
	s_nop 0
	v_cvt_pk_bf16_f32 v76, v74, v75
	v_add_co_u32_e32 v74, vcc, 0xc441000, v72
	v_and_b32_e32 v81, 0xffff0000, v80
	s_nop 0
	v_addc_co_u32_e32 v75, vcc, 0, v73, vcc
	global_store_dword v[74:75], v76, off offset:2048
	v_pk_fma_f32 v[74:75], v[64:65], v[78:79], 0 op_sel_hi:[1,1,0]
	v_lshlrev_b32_e32 v80, 16, v80
	v_pk_fma_f32 v[74:75], v[66:67], v[84:85], v[74:75]
	s_nop 0
	v_pk_fma_f32 v[74:75], v[68:69], v[82:83], v[74:75]
	s_nop 0
	v_pk_fma_f32 v[74:75], v[70:71], v[80:81], v[74:75]
	s_nop 0
	v_mul_f32_e32 v76, 0xbfb8aa3b, v74
	v_mul_f32_e32 v77, 0xbfb8aa3b, v75
	v_exp_f32_e32 v76, v76
	v_exp_f32_e32 v77, v77
	s_nop 0
	v_pk_add_f32 v[76:77], v[76:77], 1.0 op_sel_hi:[1,0]
	s_nop 0
	v_div_scale_f32 v78, s[60:61], v77, v77, v75
	v_rcp_f32_e32 v79, v78
	s_nop 0
	v_fma_f32 v112, -v78, v79, 1.0
	v_fmac_f32_e32 v79, v112, v79
	v_div_scale_f32 v112, vcc, v75, v77, v75
	v_mul_f32_e32 v113, v112, v79
	v_fma_f32 v114, -v78, v113, v112
	v_fmac_f32_e32 v113, v114, v79
	v_fma_f32 v78, -v78, v113, v112
	v_div_fmas_f32 v78, v78, v79, v113
	v_div_fixup_f32 v75, v78, v77, v75
	v_div_scale_f32 v77, s[60:61], v76, v76, v74
	v_rcp_f32_e32 v78, v77
	s_nop 0
	v_fma_f32 v79, -v77, v78, 1.0
	v_fmac_f32_e32 v78, v79, v78
	v_div_scale_f32 v79, vcc, v74, v76, v74
	v_mul_f32_e32 v112, v79, v78
	v_fma_f32 v113, -v77, v112, v79
	v_fmac_f32_e32 v112, v113, v78
	v_fma_f32 v77, -v77, v112, v79
	v_div_fmas_f32 v77, v77, v78, v112
	v_div_fixup_f32 v74, v77, v76, v74
	s_and_b64 vcc, exec, s[48:49]
	s_cbranch_vccnz .LBB0_642
	v_pk_mul_f32 v[76:77], v[74:75], v[74:75]
	s_nop 0
	v_add_f32_e32 v76, v76, v77
	v_and_b32_e32 v77, 64, v150
	v_add_u32_e32 v77, 64, v77
	v_add_f32_dpp v76, v76, v76 quad_perm:[1,0,3,2] row_mask:0xf bank_mask:0xf bound_ctrl:1
	v_cmp_lt_i32_e32 vcc, v151, v77
	s_nop 0
	v_add_f32_dpp v76, v76, v76 quad_perm:[2,3,0,1] row_mask:0xf bank_mask:0xf bound_ctrl:1
	v_cndmask_b32_e32 v78, v150, v151, vcc
	v_lshlrev_b32_e32 v78, 2, v78
	v_add_f32_dpp v76, v76, v76 row_half_mirror row_mask:0xf bank_mask:0xf bound_ctrl:1
	s_nop 1
	v_add_f32_dpp v76, v76, v76 row_mirror row_mask:0xf bank_mask:0xf bound_ctrl:1
	v_mov_b32_e32 v78, v76
	v_mov_b32_e32 v255, v76
	s_nop 1
	v_permlane16_swap_b32_e32 v78, v255
	s_nop 1
	v_add_f32_e32 v76, v78, v255
	v_xor_b32_e32 v78, 32, v150
	v_cmp_lt_i32_e32 vcc, v78, v77
	s_nop 1
	v_cndmask_b32_e32 v77, v150, v78, vcc
	v_lshlrev_b32_e32 v77, 2, v77
	v_mov_b32_e32 v77, v76
	v_mov_b32_e32 v255, v76
	s_nop 1
	v_permlane32_swap_b32_e32 v77, v255
	s_nop 1
	v_add_f32_e32 v76, v77, v255
	v_add_f32_e32 v76, 0x358637bd, v76
	v_mul_f32_e32 v77, 0x4b800000, v76
	v_cmp_gt_f32_e32 vcc, s84, v76
	s_nop 1
	v_cndmask_b32_e32 v76, v76, v77, vcc
	v_rsq_f32_e32 v76, v76
	s_nop 0
	v_mul_f32_e32 v77, 0x45800000, v76
	v_cndmask_b32_e32 v76, v76, v77, vcc
	v_mul_f32_e32 v77, 0x3db504f3, v76
	v_cndmask_b32_e64 v76, v76, v77, s[46:47]
	v_pk_mul_f32 v[74:75], v[74:75], v[76:77] op_sel_hi:[1,0]
.LBB0_642:
	s_nop 0
	v_cvt_pk_bf16_f32 v76, v74, v75
	v_add_co_u32_e32 v74, vcc, 0xc442000, v72
	v_and_b32_e32 v79, 0xffff0000, v111
	s_nop 0
	v_addc_co_u32_e32 v75, vcc, 0, v73, vcc
	global_store_dword v[74:75], v76, off offset:1024
	v_pk_fma_f32 v[74:75], v[64:65], v[84:85], 0 op_sel_hi:[1,1,0]
	v_lshlrev_b32_e32 v78, 16, v111
	v_pk_fma_f32 v[74:75], v[66:67], v[82:83], v[74:75]
	s_nop 0
	v_pk_fma_f32 v[74:75], v[68:69], v[80:81], v[74:75]
	s_nop 0
	v_pk_fma_f32 v[74:75], v[70:71], v[78:79], v[74:75]
	s_nop 0
	v_mul_f32_e32 v76, 0xbfb8aa3b, v74
	v_mul_f32_e32 v77, 0xbfb8aa3b, v75
	v_exp_f32_e32 v76, v76
	v_exp_f32_e32 v77, v77
	s_nop 0
	v_pk_add_f32 v[76:77], v[76:77], 1.0 op_sel_hi:[1,0]
	s_nop 0
	v_div_scale_f32 v84, s[60:61], v77, v77, v75
	v_rcp_f32_e32 v85, v84
	s_nop 0
	v_fma_f32 v111, -v84, v85, 1.0
	v_fmac_f32_e32 v85, v111, v85
	v_div_scale_f32 v111, vcc, v75, v77, v75
	v_mul_f32_e32 v112, v111, v85
	v_fma_f32 v113, -v84, v112, v111
	v_fmac_f32_e32 v112, v113, v85
	v_fma_f32 v84, -v84, v112, v111
	v_div_fmas_f32 v84, v84, v85, v112
	v_div_fixup_f32 v75, v84, v77, v75
	v_div_scale_f32 v77, s[60:61], v76, v76, v74
	v_rcp_f32_e32 v84, v77
	s_nop 0
	v_fma_f32 v85, -v77, v84, 1.0
	v_fmac_f32_e32 v84, v85, v84
	v_div_scale_f32 v85, vcc, v74, v76, v74
	v_mul_f32_e32 v111, v85, v84
	v_fma_f32 v112, -v77, v111, v85
	v_fmac_f32_e32 v111, v112, v84
	v_fma_f32 v77, -v77, v111, v85
	v_div_fmas_f32 v77, v77, v84, v111
	v_div_fixup_f32 v74, v77, v76, v74
	s_and_b64 vcc, exec, s[48:49]
	s_cbranch_vccnz .LBB0_644
	v_pk_mul_f32 v[76:77], v[74:75], v[74:75]
	s_nop 0
	v_add_f32_e32 v76, v76, v77
	v_and_b32_e32 v77, 64, v150
	v_add_u32_e32 v77, 64, v77
	v_add_f32_dpp v76, v76, v76 quad_perm:[1,0,3,2] row_mask:0xf bank_mask:0xf bound_ctrl:1
	v_cmp_lt_i32_e32 vcc, v151, v77
	s_nop 0
	v_add_f32_dpp v76, v76, v76 quad_perm:[2,3,0,1] row_mask:0xf bank_mask:0xf bound_ctrl:1
	v_cndmask_b32_e32 v84, v150, v151, vcc
	v_lshlrev_b32_e32 v84, 2, v84
	v_add_f32_dpp v76, v76, v76 row_half_mirror row_mask:0xf bank_mask:0xf bound_ctrl:1
	s_nop 1
	v_add_f32_dpp v76, v76, v76 row_mirror row_mask:0xf bank_mask:0xf bound_ctrl:1
	v_mov_b32_e32 v84, v76
	v_mov_b32_e32 v255, v76
	s_nop 1
	v_permlane16_swap_b32_e32 v84, v255
	s_nop 1
	v_add_f32_e32 v76, v84, v255
	v_xor_b32_e32 v84, 32, v150
	v_cmp_lt_i32_e32 vcc, v84, v77
	s_nop 1
	v_cndmask_b32_e32 v77, v150, v84, vcc
	v_lshlrev_b32_e32 v77, 2, v77
	v_mov_b32_e32 v77, v76
	v_mov_b32_e32 v255, v76
	s_nop 1
	v_permlane32_swap_b32_e32 v77, v255
	s_nop 1
	v_add_f32_e32 v76, v77, v255
	v_add_f32_e32 v76, 0x358637bd, v76
	v_mul_f32_e32 v77, 0x4b800000, v76
	v_cmp_gt_f32_e32 vcc, s84, v76
	s_nop 1
	v_cndmask_b32_e32 v76, v76, v77, vcc
	v_rsq_f32_e32 v76, v76
	s_nop 0
	v_mul_f32_e32 v77, 0x45800000, v76
	v_cndmask_b32_e32 v76, v76, v77, vcc
	v_mul_f32_e32 v77, 0x3db504f3, v76
	v_cndmask_b32_e64 v76, v76, v77, s[46:47]
	v_pk_mul_f32 v[74:75], v[74:75], v[76:77] op_sel_hi:[1,0]
.LBB0_644:
	s_nop 0
	v_cvt_pk_bf16_f32 v84, v74, v75
	v_add_co_u32_e32 v74, vcc, 0xc443000, v72
	v_and_b32_e32 v77, 0xffff0000, v110
	s_nop 0
	v_addc_co_u32_e32 v75, vcc, 0, v73, vcc
	global_store_dword v[74:75], v84, off
	v_pk_fma_f32 v[74:75], v[64:65], v[82:83], 0 op_sel_hi:[1,1,0]
	v_lshlrev_b32_e32 v76, 16, v110
	v_pk_fma_f32 v[74:75], v[66:67], v[80:81], v[74:75]
	s_nop 0
	v_pk_fma_f32 v[74:75], v[68:69], v[78:79], v[74:75]
	s_nop 0
	v_pk_fma_f32 v[74:75], v[70:71], v[76:77], v[74:75]
	s_nop 0
	v_mul_f32_e32 v82, 0xbfb8aa3b, v74
	v_mul_f32_e32 v83, 0xbfb8aa3b, v75
	v_exp_f32_e32 v82, v82
	v_exp_f32_e32 v83, v83
	s_nop 0
	v_pk_add_f32 v[82:83], v[82:83], 1.0 op_sel_hi:[1,0]
	s_nop 0
	v_div_scale_f32 v84, s[60:61], v83, v83, v75
	v_rcp_f32_e32 v85, v84
	s_nop 0
	v_fma_f32 v110, -v84, v85, 1.0
	v_fmac_f32_e32 v85, v110, v85
	v_div_scale_f32 v110, vcc, v75, v83, v75
	v_mul_f32_e32 v111, v110, v85
	v_fma_f32 v112, -v84, v111, v110
	v_fmac_f32_e32 v111, v112, v85
	v_fma_f32 v84, -v84, v111, v110
	v_div_fmas_f32 v84, v84, v85, v111
	v_div_fixup_f32 v83, v84, v83, v75
	v_div_scale_f32 v75, s[60:61], v82, v82, v74
	v_rcp_f32_e32 v84, v75
	s_nop 0
	v_fma_f32 v85, -v75, v84, 1.0
	v_fmac_f32_e32 v84, v85, v84
	v_div_scale_f32 v85, vcc, v74, v82, v74
	v_mul_f32_e32 v110, v85, v84
	v_fma_f32 v111, -v75, v110, v85
	v_fmac_f32_e32 v110, v111, v84
	v_fma_f32 v75, -v75, v110, v85
	v_div_fmas_f32 v75, v75, v84, v110
	v_div_fixup_f32 v82, v75, v82, v74
	s_and_b64 vcc, exec, s[48:49]
	s_cbranch_vccnz .LBB0_646
	v_pk_mul_f32 v[74:75], v[82:83], v[82:83]
	s_nop 0
	v_add_f32_e32 v74, v74, v75
	v_and_b32_e32 v75, 64, v150
	v_add_u32_e32 v75, 64, v75
	v_add_f32_dpp v74, v74, v74 quad_perm:[1,0,3,2] row_mask:0xf bank_mask:0xf bound_ctrl:1
	v_cmp_lt_i32_e32 vcc, v151, v75
	s_nop 0
	v_add_f32_dpp v74, v74, v74 quad_perm:[2,3,0,1] row_mask:0xf bank_mask:0xf bound_ctrl:1
	v_cndmask_b32_e32 v84, v150, v151, vcc
	v_lshlrev_b32_e32 v84, 2, v84
	v_add_f32_dpp v74, v74, v74 row_half_mirror row_mask:0xf bank_mask:0xf bound_ctrl:1
	s_nop 1
	v_add_f32_dpp v74, v74, v74 row_mirror row_mask:0xf bank_mask:0xf bound_ctrl:1
	v_mov_b32_e32 v84, v74
	v_mov_b32_e32 v255, v74
	s_nop 1
	v_permlane16_swap_b32_e32 v84, v255
	s_nop 1
	v_add_f32_e32 v74, v84, v255
	v_xor_b32_e32 v84, 32, v150
	v_cmp_lt_i32_e32 vcc, v84, v75
	s_nop 1
	v_cndmask_b32_e32 v75, v150, v84, vcc
	v_lshlrev_b32_e32 v75, 2, v75
	v_mov_b32_e32 v75, v74
	v_mov_b32_e32 v255, v74
	s_nop 1
	v_permlane32_swap_b32_e32 v75, v255
	s_nop 1
	v_add_f32_e32 v74, v75, v255
	v_add_f32_e32 v74, 0x358637bd, v74
	v_mul_f32_e32 v75, 0x4b800000, v74
	v_cmp_gt_f32_e32 vcc, s84, v74
	s_nop 1
	v_cndmask_b32_e32 v74, v74, v75, vcc
	v_rsq_f32_e32 v74, v74
	s_nop 0
	v_mul_f32_e32 v75, 0x45800000, v74
	v_cndmask_b32_e32 v74, v74, v75, vcc
	v_mul_f32_e32 v75, 0x3db504f3, v74
	v_cndmask_b32_e64 v74, v74, v75, s[46:47]
	v_pk_mul_f32 v[82:83], v[82:83], v[74:75] op_sel_hi:[1,0]
.LBB0_646:
	v_pk_fma_f32 v[80:81], v[64:65], v[80:81], 0 op_sel_hi:[1,1,0]
	v_and_b32_e32 v75, 0xffff0000, v109
	v_pk_fma_f32 v[80:81], v[66:67], v[78:79], v[80:81]
	v_lshlrev_b32_e32 v74, 16, v109
	v_cvt_pk_bf16_f32 v84, v82, v83
	v_add_co_u32_e32 v82, vcc, 0xc443000, v72
	v_pk_fma_f32 v[80:81], v[68:69], v[76:77], v[80:81]
	s_nop 0
	v_addc_co_u32_e32 v83, vcc, 0, v73, vcc
	v_pk_fma_f32 v[80:81], v[70:71], v[74:75], v[80:81]
	global_store_dword v[82:83], v84, off offset:3072
	v_mul_f32_e32 v82, 0xbfb8aa3b, v80
	v_mul_f32_e32 v83, 0xbfb8aa3b, v81
	v_exp_f32_e32 v82, v82
	v_exp_f32_e32 v83, v83
	s_nop 0
	v_pk_add_f32 v[82:83], v[82:83], 1.0 op_sel_hi:[1,0]
	s_nop 0
	v_div_scale_f32 v84, s[60:61], v83, v83, v81
	v_rcp_f32_e32 v85, v84
	s_nop 0
	v_fma_f32 v109, -v84, v85, 1.0
	v_fmac_f32_e32 v85, v109, v85
	v_div_scale_f32 v109, vcc, v81, v83, v81
	v_mul_f32_e32 v110, v109, v85
	v_fma_f32 v111, -v84, v110, v109
	v_fmac_f32_e32 v110, v111, v85
	v_fma_f32 v84, -v84, v110, v109
	v_div_fmas_f32 v84, v84, v85, v110
	v_div_fixup_f32 v83, v84, v83, v81
	v_div_scale_f32 v81, s[60:61], v82, v82, v80
	v_rcp_f32_e32 v84, v81
	s_nop 0
	v_fma_f32 v85, -v81, v84, 1.0
	v_fmac_f32_e32 v84, v85, v84
	v_div_scale_f32 v85, vcc, v80, v82, v80
	v_mul_f32_e32 v109, v85, v84
	v_fma_f32 v110, -v81, v109, v85
	v_fmac_f32_e32 v109, v110, v84
	v_fma_f32 v81, -v81, v109, v85
	v_div_fmas_f32 v81, v81, v84, v109
	v_div_fixup_f32 v82, v81, v82, v80
	s_and_b64 vcc, exec, s[48:49]
	s_cbranch_vccnz .LBB0_648
	v_pk_mul_f32 v[80:81], v[82:83], v[82:83]
	s_nop 0
	v_add_f32_e32 v80, v80, v81
	v_and_b32_e32 v81, 64, v150
	v_add_u32_e32 v81, 64, v81
	v_add_f32_dpp v80, v80, v80 quad_perm:[1,0,3,2] row_mask:0xf bank_mask:0xf bound_ctrl:1
	v_cmp_lt_i32_e32 vcc, v151, v81
	s_nop 0
	v_add_f32_dpp v80, v80, v80 quad_perm:[2,3,0,1] row_mask:0xf bank_mask:0xf bound_ctrl:1
	v_cndmask_b32_e32 v84, v150, v151, vcc
	v_lshlrev_b32_e32 v84, 2, v84
	v_add_f32_dpp v80, v80, v80 row_half_mirror row_mask:0xf bank_mask:0xf bound_ctrl:1
	s_nop 1
	v_add_f32_dpp v80, v80, v80 row_mirror row_mask:0xf bank_mask:0xf bound_ctrl:1
	v_mov_b32_e32 v84, v80
	v_mov_b32_e32 v255, v80
	s_nop 1
	v_permlane16_swap_b32_e32 v84, v255
	s_nop 1
	v_add_f32_e32 v80, v84, v255
	v_xor_b32_e32 v84, 32, v150
	v_cmp_lt_i32_e32 vcc, v84, v81
	s_nop 1
	v_cndmask_b32_e32 v81, v150, v84, vcc
	v_lshlrev_b32_e32 v81, 2, v81
	v_mov_b32_e32 v81, v80
	v_mov_b32_e32 v255, v80
	s_nop 1
	v_permlane32_swap_b32_e32 v81, v255
	s_nop 1
	v_add_f32_e32 v80, v81, v255
	v_add_f32_e32 v80, 0x358637bd, v80
	v_mul_f32_e32 v81, 0x4b800000, v80
	v_cmp_gt_f32_e32 vcc, s84, v80
	s_nop 1
	v_cndmask_b32_e32 v80, v80, v81, vcc
	v_rsq_f32_e32 v80, v80
	s_nop 0
	v_mul_f32_e32 v81, 0x45800000, v80
	v_cndmask_b32_e32 v80, v80, v81, vcc
	v_mul_f32_e32 v81, 0x3db504f3, v80
	v_cndmask_b32_e64 v80, v80, v81, s[46:47]
	v_pk_mul_f32 v[82:83], v[82:83], v[80:81] op_sel_hi:[1,0]
.LBB0_648:
	v_pk_fma_f32 v[78:79], v[64:65], v[78:79], 0 op_sel_hi:[1,1,0]
	v_and_b32_e32 v81, 0xffff0000, v108
	v_pk_fma_f32 v[78:79], v[66:67], v[76:77], v[78:79]
	v_lshlrev_b32_e32 v80, 16, v108
	v_cvt_pk_bf16_f32 v84, v82, v83
	v_add_co_u32_e32 v82, vcc, 0xc444000, v72
	v_pk_fma_f32 v[78:79], v[68:69], v[74:75], v[78:79]
	s_nop 0
	v_addc_co_u32_e32 v83, vcc, 0, v73, vcc
	v_pk_fma_f32 v[78:79], v[70:71], v[80:81], v[78:79]
	global_store_dword v[82:83], v84, off offset:2048
	v_mul_f32_e32 v82, 0xbfb8aa3b, v78
	v_mul_f32_e32 v83, 0xbfb8aa3b, v79
	v_exp_f32_e32 v82, v82
	v_exp_f32_e32 v83, v83
	s_nop 0
	v_pk_add_f32 v[82:83], v[82:83], 1.0 op_sel_hi:[1,0]
	s_nop 0
	v_div_scale_f32 v84, s[60:61], v83, v83, v79
	v_rcp_f32_e32 v85, v84
	s_nop 0
	v_fma_f32 v108, -v84, v85, 1.0
	v_fmac_f32_e32 v85, v108, v85
	v_div_scale_f32 v108, vcc, v79, v83, v79
	v_mul_f32_e32 v109, v108, v85
	v_fma_f32 v110, -v84, v109, v108
	v_fmac_f32_e32 v109, v110, v85
	v_fma_f32 v84, -v84, v109, v108
	v_div_fmas_f32 v84, v84, v85, v109
	v_div_fixup_f32 v83, v84, v83, v79
	v_div_scale_f32 v79, s[60:61], v82, v82, v78
	v_rcp_f32_e32 v84, v79
	s_nop 0
	v_fma_f32 v85, -v79, v84, 1.0
	v_fmac_f32_e32 v84, v85, v84
	v_div_scale_f32 v85, vcc, v78, v82, v78
	v_mul_f32_e32 v108, v85, v84
	v_fma_f32 v109, -v79, v108, v85
	v_fmac_f32_e32 v108, v109, v84
	v_fma_f32 v79, -v79, v108, v85
	v_div_fmas_f32 v79, v79, v84, v108
	v_div_fixup_f32 v82, v79, v82, v78
	s_and_b64 vcc, exec, s[48:49]
	s_cbranch_vccnz .LBB0_650
	v_pk_mul_f32 v[78:79], v[82:83], v[82:83]
	s_nop 0
	v_add_f32_e32 v78, v78, v79
	v_and_b32_e32 v79, 64, v150
	v_add_u32_e32 v79, 64, v79
	v_add_f32_dpp v78, v78, v78 quad_perm:[1,0,3,2] row_mask:0xf bank_mask:0xf bound_ctrl:1
	v_cmp_lt_i32_e32 vcc, v151, v79
	s_nop 0
	v_add_f32_dpp v78, v78, v78 quad_perm:[2,3,0,1] row_mask:0xf bank_mask:0xf bound_ctrl:1
	v_cndmask_b32_e32 v84, v150, v151, vcc
	v_lshlrev_b32_e32 v84, 2, v84
	v_add_f32_dpp v78, v78, v78 row_half_mirror row_mask:0xf bank_mask:0xf bound_ctrl:1
	s_nop 1
	v_add_f32_dpp v78, v78, v78 row_mirror row_mask:0xf bank_mask:0xf bound_ctrl:1
	v_mov_b32_e32 v84, v78
	v_mov_b32_e32 v255, v78
	s_nop 1
	v_permlane16_swap_b32_e32 v84, v255
	s_nop 1
	v_add_f32_e32 v78, v84, v255
	v_xor_b32_e32 v84, 32, v150
	v_cmp_lt_i32_e32 vcc, v84, v79
	s_nop 1
	v_cndmask_b32_e32 v79, v150, v84, vcc
	v_lshlrev_b32_e32 v79, 2, v79
	v_mov_b32_e32 v79, v78
	v_mov_b32_e32 v255, v78
	s_nop 1
	v_permlane32_swap_b32_e32 v79, v255
	s_nop 1
	v_add_f32_e32 v78, v79, v255
	v_add_f32_e32 v78, 0x358637bd, v78
	v_mul_f32_e32 v79, 0x4b800000, v78
	v_cmp_gt_f32_e32 vcc, s84, v78
	s_nop 1
	v_cndmask_b32_e32 v78, v78, v79, vcc
	v_rsq_f32_e32 v78, v78
	s_nop 0
	v_mul_f32_e32 v79, 0x45800000, v78
	v_cndmask_b32_e32 v78, v78, v79, vcc
	v_mul_f32_e32 v79, 0x3db504f3, v78
	v_cndmask_b32_e64 v78, v78, v79, s[46:47]
	v_pk_mul_f32 v[82:83], v[82:83], v[78:79] op_sel_hi:[1,0]
.LBB0_650:
	v_pk_fma_f32 v[76:77], v[64:65], v[76:77], 0 op_sel_hi:[1,1,0]
	v_and_b32_e32 v79, 0xffff0000, v107
	v_pk_fma_f32 v[76:77], v[66:67], v[74:75], v[76:77]
	v_lshlrev_b32_e32 v78, 16, v107
	v_cvt_pk_bf16_f32 v84, v82, v83
	v_add_co_u32_e32 v82, vcc, 0xc445000, v72
	v_pk_fma_f32 v[76:77], v[68:69], v[80:81], v[76:77]
	s_nop 0
	v_addc_co_u32_e32 v83, vcc, 0, v73, vcc
	v_pk_fma_f32 v[76:77], v[70:71], v[78:79], v[76:77]
	global_store_dword v[82:83], v84, off offset:1024
	v_mul_f32_e32 v82, 0xbfb8aa3b, v76
	v_mul_f32_e32 v83, 0xbfb8aa3b, v77
	v_exp_f32_e32 v82, v82
	v_exp_f32_e32 v83, v83
	s_nop 0
	v_pk_add_f32 v[82:83], v[82:83], 1.0 op_sel_hi:[1,0]
	s_nop 0
	v_div_scale_f32 v84, s[60:61], v83, v83, v77
	v_rcp_f32_e32 v85, v84
	s_nop 0
	v_fma_f32 v107, -v84, v85, 1.0
	v_fmac_f32_e32 v85, v107, v85
	v_div_scale_f32 v107, vcc, v77, v83, v77
	v_mul_f32_e32 v108, v107, v85
	v_fma_f32 v109, -v84, v108, v107
	v_fmac_f32_e32 v108, v109, v85
	v_fma_f32 v84, -v84, v108, v107
	v_div_fmas_f32 v84, v84, v85, v108
	v_div_fixup_f32 v83, v84, v83, v77
	v_div_scale_f32 v77, s[60:61], v82, v82, v76
	v_rcp_f32_e32 v84, v77
	s_nop 0
	v_fma_f32 v85, -v77, v84, 1.0
	v_fmac_f32_e32 v84, v85, v84
	v_div_scale_f32 v85, vcc, v76, v82, v76
	v_mul_f32_e32 v107, v85, v84
	v_fma_f32 v108, -v77, v107, v85
	v_fmac_f32_e32 v107, v108, v84
	v_fma_f32 v77, -v77, v107, v85
	v_div_fmas_f32 v77, v77, v84, v107
	v_div_fixup_f32 v82, v77, v82, v76
	s_and_b64 vcc, exec, s[48:49]
	s_cbranch_vccnz .LBB0_652
	v_pk_mul_f32 v[76:77], v[82:83], v[82:83]
	s_nop 0
	v_add_f32_e32 v76, v76, v77
	v_and_b32_e32 v77, 64, v150
	v_add_u32_e32 v77, 64, v77
	v_add_f32_dpp v76, v76, v76 quad_perm:[1,0,3,2] row_mask:0xf bank_mask:0xf bound_ctrl:1
	v_cmp_lt_i32_e32 vcc, v151, v77
	s_nop 0
	v_add_f32_dpp v76, v76, v76 quad_perm:[2,3,0,1] row_mask:0xf bank_mask:0xf bound_ctrl:1
	v_cndmask_b32_e32 v84, v150, v151, vcc
	v_lshlrev_b32_e32 v84, 2, v84
	v_add_f32_dpp v76, v76, v76 row_half_mirror row_mask:0xf bank_mask:0xf bound_ctrl:1
	s_nop 1
	v_add_f32_dpp v76, v76, v76 row_mirror row_mask:0xf bank_mask:0xf bound_ctrl:1
	v_mov_b32_e32 v84, v76
	v_mov_b32_e32 v255, v76
	s_nop 1
	v_permlane16_swap_b32_e32 v84, v255
	s_nop 1
	v_add_f32_e32 v76, v84, v255
	v_xor_b32_e32 v84, 32, v150
	v_cmp_lt_i32_e32 vcc, v84, v77
	s_nop 1
	v_cndmask_b32_e32 v77, v150, v84, vcc
	v_lshlrev_b32_e32 v77, 2, v77
	v_mov_b32_e32 v77, v76
	v_mov_b32_e32 v255, v76
	s_nop 1
	v_permlane32_swap_b32_e32 v77, v255
	s_nop 1
	v_add_f32_e32 v76, v77, v255
	v_add_f32_e32 v76, 0x358637bd, v76
	v_mul_f32_e32 v77, 0x4b800000, v76
	v_cmp_gt_f32_e32 vcc, s84, v76
	s_nop 1
	v_cndmask_b32_e32 v76, v76, v77, vcc
	v_rsq_f32_e32 v76, v76
	s_nop 0
	v_mul_f32_e32 v77, 0x45800000, v76
	v_cndmask_b32_e32 v76, v76, v77, vcc
	v_mul_f32_e32 v77, 0x3db504f3, v76
	v_cndmask_b32_e64 v76, v76, v77, s[46:47]
	v_pk_mul_f32 v[82:83], v[82:83], v[76:77] op_sel_hi:[1,0]
.LBB0_652:
	v_pk_fma_f32 v[74:75], v[64:65], v[74:75], 0 op_sel_hi:[1,1,0]
	v_and_b32_e32 v77, 0xffff0000, v106
	v_pk_fma_f32 v[74:75], v[66:67], v[80:81], v[74:75]
	v_lshlrev_b32_e32 v76, 16, v106
	v_cvt_pk_bf16_f32 v84, v82, v83
	v_add_co_u32_e32 v82, vcc, 0xc446000, v72
	v_pk_fma_f32 v[74:75], v[68:69], v[78:79], v[74:75]
	s_nop 0
	v_addc_co_u32_e32 v83, vcc, 0, v73, vcc
	v_pk_fma_f32 v[74:75], v[70:71], v[76:77], v[74:75]
	global_store_dword v[82:83], v84, off
	v_mul_f32_e32 v82, 0xbfb8aa3b, v74
	v_mul_f32_e32 v83, 0xbfb8aa3b, v75
	v_exp_f32_e32 v82, v82
	v_exp_f32_e32 v83, v83
	s_nop 0
	v_pk_add_f32 v[82:83], v[82:83], 1.0 op_sel_hi:[1,0]
	s_nop 0
	v_div_scale_f32 v84, s[60:61], v83, v83, v75
	v_rcp_f32_e32 v85, v84
	s_nop 0
	v_fma_f32 v106, -v84, v85, 1.0
	v_fmac_f32_e32 v85, v106, v85
	v_div_scale_f32 v106, vcc, v75, v83, v75
	v_mul_f32_e32 v107, v106, v85
	v_fma_f32 v108, -v84, v107, v106
	v_fmac_f32_e32 v107, v108, v85
	v_fma_f32 v84, -v84, v107, v106
	v_div_fmas_f32 v84, v84, v85, v107
	v_div_fixup_f32 v83, v84, v83, v75
	v_div_scale_f32 v75, s[60:61], v82, v82, v74
	v_rcp_f32_e32 v84, v75
	s_nop 0
	v_fma_f32 v85, -v75, v84, 1.0
	v_fmac_f32_e32 v84, v85, v84
	v_div_scale_f32 v85, vcc, v74, v82, v74
	v_mul_f32_e32 v106, v85, v84
	v_fma_f32 v107, -v75, v106, v85
	v_fmac_f32_e32 v106, v107, v84
	v_fma_f32 v75, -v75, v106, v85
	v_div_fmas_f32 v75, v75, v84, v106
	v_div_fixup_f32 v82, v75, v82, v74
	s_and_b64 vcc, exec, s[48:49]
	s_cbranch_vccnz .LBB0_654
	v_pk_mul_f32 v[74:75], v[82:83], v[82:83]
	s_nop 0
	v_add_f32_e32 v74, v74, v75
	v_and_b32_e32 v75, 64, v150
	v_add_u32_e32 v75, 64, v75
	v_add_f32_dpp v74, v74, v74 quad_perm:[1,0,3,2] row_mask:0xf bank_mask:0xf bound_ctrl:1
	v_cmp_lt_i32_e32 vcc, v151, v75
	s_nop 0
	v_add_f32_dpp v74, v74, v74 quad_perm:[2,3,0,1] row_mask:0xf bank_mask:0xf bound_ctrl:1
	v_cndmask_b32_e32 v84, v150, v151, vcc
	v_lshlrev_b32_e32 v84, 2, v84
	v_add_f32_dpp v74, v74, v74 row_half_mirror row_mask:0xf bank_mask:0xf bound_ctrl:1
	s_nop 1
	v_add_f32_dpp v74, v74, v74 row_mirror row_mask:0xf bank_mask:0xf bound_ctrl:1
	v_mov_b32_e32 v84, v74
	v_mov_b32_e32 v255, v74
	s_nop 1
	v_permlane16_swap_b32_e32 v84, v255
	s_nop 1
	v_add_f32_e32 v74, v84, v255
	v_xor_b32_e32 v84, 32, v150
	v_cmp_lt_i32_e32 vcc, v84, v75
	s_nop 1
	v_cndmask_b32_e32 v75, v150, v84, vcc
	v_lshlrev_b32_e32 v75, 2, v75
	v_mov_b32_e32 v75, v74
	v_mov_b32_e32 v255, v74
	s_nop 1
	v_permlane32_swap_b32_e32 v75, v255
	s_nop 1
	v_add_f32_e32 v74, v75, v255
	v_add_f32_e32 v74, 0x358637bd, v74
	v_mul_f32_e32 v75, 0x4b800000, v74
	v_cmp_gt_f32_e32 vcc, s84, v74
	s_nop 1
	v_cndmask_b32_e32 v74, v74, v75, vcc
	v_rsq_f32_e32 v74, v74
	s_nop 0
	v_mul_f32_e32 v75, 0x45800000, v74
	v_cndmask_b32_e32 v74, v74, v75, vcc
	v_mul_f32_e32 v75, 0x3db504f3, v74
	v_cndmask_b32_e64 v74, v74, v75, s[46:47]
	v_pk_mul_f32 v[82:83], v[82:83], v[74:75] op_sel_hi:[1,0]
.LBB0_654:
	v_pk_fma_f32 v[80:81], v[64:65], v[80:81], 0 op_sel_hi:[1,1,0]
	v_lshlrev_b32_e32 v74, 16, v105
	v_pk_fma_f32 v[80:81], v[66:67], v[78:79], v[80:81]
	v_and_b32_e32 v75, 0xffff0000, v105
	v_cvt_pk_bf16_f32 v84, v82, v83
	v_add_co_u32_e32 v82, vcc, 0xc446000, v72
	v_pk_fma_f32 v[80:81], v[68:69], v[76:77], v[80:81]
	s_nop 0
	v_addc_co_u32_e32 v83, vcc, 0, v73, vcc
	v_pk_fma_f32 v[80:81], v[70:71], v[74:75], v[80:81]
	global_store_dword v[82:83], v84, off offset:3072
	v_mul_f32_e32 v82, 0xbfb8aa3b, v80
	v_mul_f32_e32 v83, 0xbfb8aa3b, v81
	v_exp_f32_e32 v82, v82
	v_exp_f32_e32 v83, v83
	s_nop 0
	v_pk_add_f32 v[82:83], v[82:83], 1.0 op_sel_hi:[1,0]
	s_nop 0
	v_div_scale_f32 v84, s[60:61], v83, v83, v81
	v_rcp_f32_e32 v85, v84
	s_nop 0
	v_fma_f32 v105, -v84, v85, 1.0
	v_fmac_f32_e32 v85, v105, v85
	v_div_scale_f32 v105, vcc, v81, v83, v81
	v_mul_f32_e32 v106, v105, v85
	v_fma_f32 v107, -v84, v106, v105
	v_fmac_f32_e32 v106, v107, v85
	v_fma_f32 v84, -v84, v106, v105
	v_div_fmas_f32 v84, v84, v85, v106
	v_div_fixup_f32 v83, v84, v83, v81
	v_div_scale_f32 v81, s[60:61], v82, v82, v80
	v_rcp_f32_e32 v84, v81
	s_nop 0
	v_fma_f32 v85, -v81, v84, 1.0
	v_fmac_f32_e32 v84, v85, v84
	v_div_scale_f32 v85, vcc, v80, v82, v80
	v_mul_f32_e32 v105, v85, v84
	v_fma_f32 v106, -v81, v105, v85
	v_fmac_f32_e32 v105, v106, v84
	v_fma_f32 v81, -v81, v105, v85
	v_div_fmas_f32 v81, v81, v84, v105
	v_div_fixup_f32 v82, v81, v82, v80
	s_and_b64 vcc, exec, s[48:49]
	s_cbranch_vccnz .LBB0_656
	v_pk_mul_f32 v[80:81], v[82:83], v[82:83]
	s_nop 0
	v_add_f32_e32 v80, v80, v81
	v_and_b32_e32 v81, 64, v150
	v_add_u32_e32 v81, 64, v81
	v_add_f32_dpp v80, v80, v80 quad_perm:[1,0,3,2] row_mask:0xf bank_mask:0xf bound_ctrl:1
	v_cmp_lt_i32_e32 vcc, v151, v81
	s_nop 0
	v_add_f32_dpp v80, v80, v80 quad_perm:[2,3,0,1] row_mask:0xf bank_mask:0xf bound_ctrl:1
	v_cndmask_b32_e32 v84, v150, v151, vcc
	v_lshlrev_b32_e32 v84, 2, v84
	v_add_f32_dpp v80, v80, v80 row_half_mirror row_mask:0xf bank_mask:0xf bound_ctrl:1
	s_nop 1
	v_add_f32_dpp v80, v80, v80 row_mirror row_mask:0xf bank_mask:0xf bound_ctrl:1
	v_mov_b32_e32 v84, v80
	v_mov_b32_e32 v255, v80
	s_nop 1
	v_permlane16_swap_b32_e32 v84, v255
	s_nop 1
	v_add_f32_e32 v80, v84, v255
	v_xor_b32_e32 v84, 32, v150
	v_cmp_lt_i32_e32 vcc, v84, v81
	s_nop 1
	v_cndmask_b32_e32 v81, v150, v84, vcc
	v_lshlrev_b32_e32 v81, 2, v81
	v_mov_b32_e32 v81, v80
	v_mov_b32_e32 v255, v80
	s_nop 1
	v_permlane32_swap_b32_e32 v81, v255
	s_nop 1
	v_add_f32_e32 v80, v81, v255
	v_add_f32_e32 v80, 0x358637bd, v80
	v_mul_f32_e32 v81, 0x4b800000, v80
	v_cmp_gt_f32_e32 vcc, s84, v80
	s_nop 1
	v_cndmask_b32_e32 v80, v80, v81, vcc
	v_rsq_f32_e32 v80, v80
	s_nop 0
	v_mul_f32_e32 v81, 0x45800000, v80
	v_cndmask_b32_e32 v80, v80, v81, vcc
	v_mul_f32_e32 v81, 0x3db504f3, v80
	v_cndmask_b32_e64 v80, v80, v81, s[46:47]
	v_pk_mul_f32 v[82:83], v[82:83], v[80:81] op_sel_hi:[1,0]
.LBB0_656:
	v_pk_fma_f32 v[78:79], v[64:65], v[78:79], 0 op_sel_hi:[1,1,0]
	v_lshlrev_b32_e32 v80, 16, v104
	v_pk_fma_f32 v[78:79], v[66:67], v[76:77], v[78:79]
	v_and_b32_e32 v81, 0xffff0000, v104
	v_cvt_pk_bf16_f32 v84, v82, v83
	v_add_co_u32_e32 v82, vcc, 0xc447000, v72
	v_pk_fma_f32 v[78:79], v[68:69], v[74:75], v[78:79]
	s_nop 0
	v_addc_co_u32_e32 v83, vcc, 0, v73, vcc
	v_pk_fma_f32 v[78:79], v[70:71], v[80:81], v[78:79]
	global_store_dword v[82:83], v84, off offset:2048
	v_mul_f32_e32 v82, 0xbfb8aa3b, v78
	v_mul_f32_e32 v83, 0xbfb8aa3b, v79
	v_exp_f32_e32 v82, v82
	v_exp_f32_e32 v83, v83
	s_nop 0
	v_pk_add_f32 v[82:83], v[82:83], 1.0 op_sel_hi:[1,0]
	s_nop 0
	v_div_scale_f32 v84, s[60:61], v83, v83, v79
	v_rcp_f32_e32 v85, v84
	s_nop 0
	v_fma_f32 v104, -v84, v85, 1.0
	v_fmac_f32_e32 v85, v104, v85
	v_div_scale_f32 v104, vcc, v79, v83, v79
	v_mul_f32_e32 v105, v104, v85
	v_fma_f32 v106, -v84, v105, v104
	v_fmac_f32_e32 v105, v106, v85
	v_fma_f32 v84, -v84, v105, v104
	v_div_fmas_f32 v84, v84, v85, v105
	v_div_fixup_f32 v83, v84, v83, v79
	v_div_scale_f32 v79, s[60:61], v82, v82, v78
	v_rcp_f32_e32 v84, v79
	s_nop 0
	v_fma_f32 v85, -v79, v84, 1.0
	v_fmac_f32_e32 v84, v85, v84
	v_div_scale_f32 v85, vcc, v78, v82, v78
	v_mul_f32_e32 v104, v85, v84
	v_fma_f32 v105, -v79, v104, v85
	v_fmac_f32_e32 v104, v105, v84
	v_fma_f32 v79, -v79, v104, v85
	v_div_fmas_f32 v79, v79, v84, v104
	v_div_fixup_f32 v82, v79, v82, v78
	s_and_b64 vcc, exec, s[48:49]
	s_cbranch_vccnz .LBB0_658
	v_pk_mul_f32 v[78:79], v[82:83], v[82:83]
	s_nop 0
	v_add_f32_e32 v78, v78, v79
	v_and_b32_e32 v79, 64, v150
	v_add_u32_e32 v79, 64, v79
	v_add_f32_dpp v78, v78, v78 quad_perm:[1,0,3,2] row_mask:0xf bank_mask:0xf bound_ctrl:1
	v_cmp_lt_i32_e32 vcc, v151, v79
	s_nop 0
	v_add_f32_dpp v78, v78, v78 quad_perm:[2,3,0,1] row_mask:0xf bank_mask:0xf bound_ctrl:1
	v_cndmask_b32_e32 v84, v150, v151, vcc
	v_lshlrev_b32_e32 v84, 2, v84
	v_add_f32_dpp v78, v78, v78 row_half_mirror row_mask:0xf bank_mask:0xf bound_ctrl:1
	s_nop 1
	v_add_f32_dpp v78, v78, v78 row_mirror row_mask:0xf bank_mask:0xf bound_ctrl:1
	v_mov_b32_e32 v84, v78
	v_mov_b32_e32 v255, v78
	s_nop 1
	v_permlane16_swap_b32_e32 v84, v255
	s_nop 1
	v_add_f32_e32 v78, v84, v255
	v_xor_b32_e32 v84, 32, v150
	v_cmp_lt_i32_e32 vcc, v84, v79
	s_nop 1
	v_cndmask_b32_e32 v79, v150, v84, vcc
	v_lshlrev_b32_e32 v79, 2, v79
	v_mov_b32_e32 v79, v78
	v_mov_b32_e32 v255, v78
	s_nop 1
	v_permlane32_swap_b32_e32 v79, v255
	s_nop 1
	v_add_f32_e32 v78, v79, v255
	v_add_f32_e32 v78, 0x358637bd, v78
	v_mul_f32_e32 v79, 0x4b800000, v78
	v_cmp_gt_f32_e32 vcc, s84, v78
	s_nop 1
	v_cndmask_b32_e32 v78, v78, v79, vcc
	v_rsq_f32_e32 v78, v78
	s_nop 0
	v_mul_f32_e32 v79, 0x45800000, v78
	v_cndmask_b32_e32 v78, v78, v79, vcc
	v_mul_f32_e32 v79, 0x3db504f3, v78
	v_cndmask_b32_e64 v78, v78, v79, s[46:47]
	v_pk_mul_f32 v[82:83], v[82:83], v[78:79] op_sel_hi:[1,0]
.LBB0_658:
	v_pk_fma_f32 v[76:77], v[64:65], v[76:77], 0 op_sel_hi:[1,1,0]
	v_lshlrev_b32_e32 v78, 16, v103
	v_pk_fma_f32 v[76:77], v[66:67], v[74:75], v[76:77]
	v_and_b32_e32 v79, 0xffff0000, v103
	v_cvt_pk_bf16_f32 v84, v82, v83
	v_add_co_u32_e32 v82, vcc, 0xc448000, v72
	v_pk_fma_f32 v[76:77], v[68:69], v[80:81], v[76:77]
	s_nop 0
	v_addc_co_u32_e32 v83, vcc, 0, v73, vcc
	v_pk_fma_f32 v[76:77], v[70:71], v[78:79], v[76:77]
	global_store_dword v[82:83], v84, off offset:1024
	v_mul_f32_e32 v82, 0xbfb8aa3b, v76
	v_mul_f32_e32 v83, 0xbfb8aa3b, v77
	v_exp_f32_e32 v82, v82
	v_exp_f32_e32 v83, v83
	s_nop 0
	v_pk_add_f32 v[82:83], v[82:83], 1.0 op_sel_hi:[1,0]
	s_nop 0
	v_div_scale_f32 v84, s[60:61], v83, v83, v77
	v_rcp_f32_e32 v85, v84
	s_nop 0
	v_fma_f32 v103, -v84, v85, 1.0
	v_fmac_f32_e32 v85, v103, v85
	v_div_scale_f32 v103, vcc, v77, v83, v77
	v_mul_f32_e32 v104, v103, v85
	v_fma_f32 v105, -v84, v104, v103
	v_fmac_f32_e32 v104, v105, v85
	v_fma_f32 v84, -v84, v104, v103
	v_div_fmas_f32 v84, v84, v85, v104
	v_div_fixup_f32 v83, v84, v83, v77
	v_div_scale_f32 v77, s[60:61], v82, v82, v76
	v_rcp_f32_e32 v84, v77
	s_nop 0
	v_fma_f32 v85, -v77, v84, 1.0
	v_fmac_f32_e32 v84, v85, v84
	v_div_scale_f32 v85, vcc, v76, v82, v76
	v_mul_f32_e32 v103, v85, v84
	v_fma_f32 v104, -v77, v103, v85
	v_fmac_f32_e32 v103, v104, v84
	v_fma_f32 v77, -v77, v103, v85
	v_div_fmas_f32 v77, v77, v84, v103
	v_div_fixup_f32 v82, v77, v82, v76
	s_and_b64 vcc, exec, s[48:49]
	s_cbranch_vccnz .LBB0_660
	v_pk_mul_f32 v[76:77], v[82:83], v[82:83]
	s_nop 0
	v_add_f32_e32 v76, v76, v77
	v_and_b32_e32 v77, 64, v150
	v_add_u32_e32 v77, 64, v77
	v_add_f32_dpp v76, v76, v76 quad_perm:[1,0,3,2] row_mask:0xf bank_mask:0xf bound_ctrl:1
	v_cmp_lt_i32_e32 vcc, v151, v77
	s_nop 0
	v_add_f32_dpp v76, v76, v76 quad_perm:[2,3,0,1] row_mask:0xf bank_mask:0xf bound_ctrl:1
	v_cndmask_b32_e32 v84, v150, v151, vcc
	v_lshlrev_b32_e32 v84, 2, v84
	v_add_f32_dpp v76, v76, v76 row_half_mirror row_mask:0xf bank_mask:0xf bound_ctrl:1
	s_nop 1
	v_add_f32_dpp v76, v76, v76 row_mirror row_mask:0xf bank_mask:0xf bound_ctrl:1
	v_mov_b32_e32 v84, v76
	v_mov_b32_e32 v255, v76
	s_nop 1
	v_permlane16_swap_b32_e32 v84, v255
	s_nop 1
	v_add_f32_e32 v76, v84, v255
	v_xor_b32_e32 v84, 32, v150
	v_cmp_lt_i32_e32 vcc, v84, v77
	s_nop 1
	v_cndmask_b32_e32 v77, v150, v84, vcc
	v_lshlrev_b32_e32 v77, 2, v77
	v_mov_b32_e32 v77, v76
	v_mov_b32_e32 v255, v76
	s_nop 1
	v_permlane32_swap_b32_e32 v77, v255
	s_nop 1
	v_add_f32_e32 v76, v77, v255
	v_add_f32_e32 v76, 0x358637bd, v76
	v_mul_f32_e32 v77, 0x4b800000, v76
	v_cmp_gt_f32_e32 vcc, s84, v76
	s_nop 1
	v_cndmask_b32_e32 v76, v76, v77, vcc
	v_rsq_f32_e32 v76, v76
	s_nop 0
	v_mul_f32_e32 v77, 0x45800000, v76
	v_cndmask_b32_e32 v76, v76, v77, vcc
	v_mul_f32_e32 v77, 0x3db504f3, v76
	v_cndmask_b32_e64 v76, v76, v77, s[46:47]
	v_pk_mul_f32 v[82:83], v[82:83], v[76:77] op_sel_hi:[1,0]
.LBB0_660:
	v_pk_fma_f32 v[74:75], v[64:65], v[74:75], 0 op_sel_hi:[1,1,0]
	v_lshlrev_b32_e32 v76, 16, v102
	v_pk_fma_f32 v[74:75], v[66:67], v[80:81], v[74:75]
	v_and_b32_e32 v77, 0xffff0000, v102
	v_cvt_pk_bf16_f32 v84, v82, v83
	v_add_co_u32_e32 v82, vcc, 0xc449000, v72
	v_pk_fma_f32 v[74:75], v[68:69], v[78:79], v[74:75]
	s_nop 0
	v_addc_co_u32_e32 v83, vcc, 0, v73, vcc
	v_pk_fma_f32 v[74:75], v[70:71], v[76:77], v[74:75]
	global_store_dword v[82:83], v84, off
	v_mul_f32_e32 v82, 0xbfb8aa3b, v74
	v_mul_f32_e32 v83, 0xbfb8aa3b, v75
	v_exp_f32_e32 v82, v82
	v_exp_f32_e32 v83, v83
	s_nop 0
	v_pk_add_f32 v[82:83], v[82:83], 1.0 op_sel_hi:[1,0]
	s_nop 0
	v_div_scale_f32 v84, s[60:61], v83, v83, v75
	v_rcp_f32_e32 v85, v84
	s_nop 0
	v_fma_f32 v102, -v84, v85, 1.0
	v_fmac_f32_e32 v85, v102, v85
	v_div_scale_f32 v102, vcc, v75, v83, v75
	v_mul_f32_e32 v103, v102, v85
	v_fma_f32 v104, -v84, v103, v102
	v_fmac_f32_e32 v103, v104, v85
	v_fma_f32 v84, -v84, v103, v102
	v_div_fmas_f32 v84, v84, v85, v103
	v_div_fixup_f32 v75, v84, v83, v75
	v_div_scale_f32 v83, s[60:61], v82, v82, v74
	v_rcp_f32_e32 v84, v83
	s_nop 0
	v_fma_f32 v85, -v83, v84, 1.0
	v_fmac_f32_e32 v84, v85, v84
	v_div_scale_f32 v85, vcc, v74, v82, v74
	v_mul_f32_e32 v102, v85, v84
	v_fma_f32 v103, -v83, v102, v85
	v_fmac_f32_e32 v102, v103, v84
	v_fma_f32 v83, -v83, v102, v85
	v_div_fmas_f32 v83, v83, v84, v102
	v_div_fixup_f32 v74, v83, v82, v74
	s_and_b64 vcc, exec, s[48:49]
	s_cbranch_vccnz .LBB0_662
	v_pk_mul_f32 v[82:83], v[74:75], v[74:75]
	s_nop 0
	v_add_f32_e32 v82, v82, v83
	v_and_b32_e32 v83, 64, v150
	v_add_u32_e32 v83, 64, v83
	v_add_f32_dpp v82, v82, v82 quad_perm:[1,0,3,2] row_mask:0xf bank_mask:0xf bound_ctrl:1
	v_cmp_lt_i32_e32 vcc, v151, v83
	s_nop 0
	v_add_f32_dpp v82, v82, v82 quad_perm:[2,3,0,1] row_mask:0xf bank_mask:0xf bound_ctrl:1
	v_cndmask_b32_e32 v84, v150, v151, vcc
	v_lshlrev_b32_e32 v84, 2, v84
	v_add_f32_dpp v82, v82, v82 row_half_mirror row_mask:0xf bank_mask:0xf bound_ctrl:1
	s_nop 1
	v_add_f32_dpp v82, v82, v82 row_mirror row_mask:0xf bank_mask:0xf bound_ctrl:1
	v_mov_b32_e32 v84, v82
	v_mov_b32_e32 v255, v82
	s_nop 1
	v_permlane16_swap_b32_e32 v84, v255
	s_nop 1
	v_add_f32_e32 v82, v84, v255
	v_xor_b32_e32 v84, 32, v150
	v_cmp_lt_i32_e32 vcc, v84, v83
	s_nop 1
	v_cndmask_b32_e32 v83, v150, v84, vcc
	v_lshlrev_b32_e32 v83, 2, v83
	v_mov_b32_e32 v83, v82
	v_mov_b32_e32 v255, v82
	s_nop 1
	v_permlane32_swap_b32_e32 v83, v255
	s_nop 1
	v_add_f32_e32 v82, v83, v255
	v_add_f32_e32 v82, 0x358637bd, v82
	v_mul_f32_e32 v83, 0x4b800000, v82
	v_cmp_gt_f32_e32 vcc, s84, v82
	s_nop 1
	v_cndmask_b32_e32 v82, v82, v83, vcc
	v_rsq_f32_e32 v82, v82
	s_nop 0
	v_mul_f32_e32 v83, 0x45800000, v82
	v_cndmask_b32_e32 v82, v82, v83, vcc
	v_mul_f32_e32 v83, 0x3db504f3, v82
	v_cndmask_b32_e64 v82, v82, v83, s[46:47]
	v_pk_mul_f32 v[74:75], v[74:75], v[82:83] op_sel_hi:[1,0]

.LBB0_664:
	s_or_b64 exec, exec, s[60:61]
	v_pk_fma_f32 v[74:75], v[64:65], v[80:81], 0 op_sel_hi:[1,1,0]
	v_lshlrev_b32_e32 v82, 16, v101
	v_pk_fma_f32 v[74:75], v[66:67], v[78:79], v[74:75]
	v_and_b32_e32 v83, 0xffff0000, v101
	v_pk_fma_f32 v[74:75], v[68:69], v[76:77], v[74:75]
	s_nop 0
	v_pk_fma_f32 v[74:75], v[70:71], v[82:83], v[74:75]
	s_nop 0
	v_mul_f32_e32 v80, 0xbfb8aa3b, v74
	v_mul_f32_e32 v81, 0xbfb8aa3b, v75
	v_exp_f32_e32 v80, v80
	v_exp_f32_e32 v81, v81
	s_nop 0
	v_pk_add_f32 v[80:81], v[80:81], 1.0 op_sel_hi:[1,0]
	s_nop 0
	v_div_scale_f32 v84, s[60:61], v81, v81, v75
	v_rcp_f32_e32 v85, v84
	s_nop 0
	v_fma_f32 v101, -v84, v85, 1.0
	v_fmac_f32_e32 v85, v101, v85
	v_div_scale_f32 v101, vcc, v75, v81, v75
	v_mul_f32_e32 v102, v101, v85
	v_fma_f32 v103, -v84, v102, v101
	v_fmac_f32_e32 v102, v103, v85
	v_fma_f32 v84, -v84, v102, v101
	v_div_fmas_f32 v84, v84, v85, v102
	v_div_fixup_f32 v75, v84, v81, v75
	v_div_scale_f32 v81, s[60:61], v80, v80, v74
	v_rcp_f32_e32 v84, v81
	s_nop 0
	v_fma_f32 v85, -v81, v84, 1.0
	v_fmac_f32_e32 v84, v85, v84
	v_div_scale_f32 v85, vcc, v74, v80, v74
	v_mul_f32_e32 v101, v85, v84
	v_fma_f32 v102, -v81, v101, v85
	v_fmac_f32_e32 v101, v102, v84
	v_fma_f32 v81, -v81, v101, v85
	v_div_fmas_f32 v81, v81, v84, v101
	v_div_fixup_f32 v74, v81, v80, v74
	s_and_b64 vcc, exec, s[48:49]
	s_cbranch_vccnz .LBB0_666
	v_pk_mul_f32 v[80:81], v[74:75], v[74:75]
	s_nop 0
	v_add_f32_e32 v80, v80, v81
	v_and_b32_e32 v81, 64, v150
	v_add_u32_e32 v81, 64, v81
	v_add_f32_dpp v80, v80, v80 quad_perm:[1,0,3,2] row_mask:0xf bank_mask:0xf bound_ctrl:1
	v_cmp_lt_i32_e32 vcc, v151, v81
	s_nop 0
	v_add_f32_dpp v80, v80, v80 quad_perm:[2,3,0,1] row_mask:0xf bank_mask:0xf bound_ctrl:1
	v_cndmask_b32_e32 v84, v150, v151, vcc
	v_lshlrev_b32_e32 v84, 2, v84
	v_add_f32_dpp v80, v80, v80 row_half_mirror row_mask:0xf bank_mask:0xf bound_ctrl:1
	s_nop 1
	v_add_f32_dpp v80, v80, v80 row_mirror row_mask:0xf bank_mask:0xf bound_ctrl:1
	v_mov_b32_e32 v84, v80
	v_mov_b32_e32 v255, v80
	s_nop 1
	v_permlane16_swap_b32_e32 v84, v255
	s_nop 1
	v_add_f32_e32 v80, v84, v255
	v_xor_b32_e32 v84, 32, v150
	v_cmp_lt_i32_e32 vcc, v84, v81
	s_nop 1
	v_cndmask_b32_e32 v81, v150, v84, vcc
	v_lshlrev_b32_e32 v81, 2, v81
	v_mov_b32_e32 v81, v80
	v_mov_b32_e32 v255, v80
	s_nop 1
	v_permlane32_swap_b32_e32 v81, v255
	s_nop 1
	v_add_f32_e32 v80, v81, v255
	v_add_f32_e32 v80, 0x358637bd, v80
	v_mul_f32_e32 v81, 0x4b800000, v80
	v_cmp_gt_f32_e32 vcc, s84, v80
	s_nop 1
	v_cndmask_b32_e32 v80, v80, v81, vcc
	v_rsq_f32_e32 v80, v80
	s_nop 0
	v_mul_f32_e32 v81, 0x45800000, v80
	v_cndmask_b32_e32 v80, v80, v81, vcc
	v_mul_f32_e32 v81, 0x3db504f3, v80
	v_cndmask_b32_e64 v80, v80, v81, s[46:47]
	v_pk_mul_f32 v[74:75], v[74:75], v[80:81] op_sel_hi:[1,0]

.LBB0_668:
	s_or_b64 exec, exec, s[60:61]
	v_pk_fma_f32 v[64:65], v[64:65], v[78:79], 0 op_sel_hi:[1,1,0]
	v_lshlrev_b32_e32 v80, 16, v86
	v_pk_fma_f32 v[64:65], v[66:67], v[76:77], v[64:65]
	v_and_b32_e32 v81, 0xffff0000, v86
	v_pk_fma_f32 v[64:65], v[68:69], v[82:83], v[64:65]
	s_nop 0
	v_pk_fma_f32 v[64:65], v[70:71], v[80:81], v[64:65]
	s_nop 0
	v_mul_f32_e32 v66, 0xbfb8aa3b, v64
	v_mul_f32_e32 v67, 0xbfb8aa3b, v65
	v_exp_f32_e32 v66, v66
	v_exp_f32_e32 v67, v67
	s_nop 0
	v_pk_add_f32 v[66:67], v[66:67], 1.0 op_sel_hi:[1,0]
	s_nop 0
	v_div_scale_f32 v68, s[60:61], v67, v67, v65
	v_rcp_f32_e32 v69, v68
	s_nop 0
	v_fma_f32 v70, -v68, v69, 1.0
	v_fmac_f32_e32 v69, v70, v69
	v_div_scale_f32 v70, vcc, v65, v67, v65
	v_mul_f32_e32 v71, v70, v69
	v_fma_f32 v76, -v68, v71, v70
	v_fmac_f32_e32 v71, v76, v69
	v_fma_f32 v68, -v68, v71, v70
	v_div_fmas_f32 v68, v68, v69, v71
	v_div_fixup_f32 v65, v68, v67, v65
	v_div_scale_f32 v67, s[60:61], v66, v66, v64
	v_rcp_f32_e32 v68, v67
	s_nop 0
	v_fma_f32 v69, -v67, v68, 1.0
	v_fmac_f32_e32 v68, v69, v68
	v_div_scale_f32 v69, vcc, v64, v66, v64
	v_mul_f32_e32 v70, v69, v68
	v_fma_f32 v71, -v67, v70, v69
	v_fmac_f32_e32 v70, v71, v68
	v_fma_f32 v67, -v67, v70, v69
	v_div_fmas_f32 v67, v67, v68, v70
	v_div_fixup_f32 v64, v67, v66, v64
	s_and_b64 vcc, exec, s[48:49]
	s_cbranch_vccnz .LBB0_670
	v_pk_mul_f32 v[66:67], v[64:65], v[64:65]
	s_nop 0
	v_add_f32_e32 v66, v66, v67
	v_and_b32_e32 v67, 64, v150
	v_add_u32_e32 v67, 64, v67
	v_add_f32_dpp v66, v66, v66 quad_perm:[1,0,3,2] row_mask:0xf bank_mask:0xf bound_ctrl:1
	v_cmp_lt_i32_e32 vcc, v151, v67
	s_nop 0
	v_add_f32_dpp v66, v66, v66 quad_perm:[2,3,0,1] row_mask:0xf bank_mask:0xf bound_ctrl:1
	v_cndmask_b32_e32 v68, v150, v151, vcc
	v_lshlrev_b32_e32 v68, 2, v68
	v_add_f32_dpp v66, v66, v66 row_half_mirror row_mask:0xf bank_mask:0xf bound_ctrl:1
	s_nop 1
	v_add_f32_dpp v66, v66, v66 row_mirror row_mask:0xf bank_mask:0xf bound_ctrl:1
	v_mov_b32_e32 v68, v66
	v_mov_b32_e32 v255, v66
	s_nop 1
	v_permlane16_swap_b32_e32 v68, v255
	s_nop 1
	v_add_f32_e32 v66, v68, v255
	v_xor_b32_e32 v68, 32, v150
	v_cmp_lt_i32_e32 vcc, v68, v67
	s_nop 1
	v_cndmask_b32_e32 v67, v150, v68, vcc
	v_lshlrev_b32_e32 v67, 2, v67
	v_mov_b32_e32 v67, v66
	v_mov_b32_e32 v255, v66
	s_nop 1
	v_permlane32_swap_b32_e32 v67, v255
	s_nop 1
	v_add_f32_e32 v66, v67, v255
	v_add_f32_e32 v66, 0x358637bd, v66
	v_mul_f32_e32 v67, 0x4b800000, v66
	v_cmp_gt_f32_e32 vcc, s84, v66
	s_nop 1
	v_cndmask_b32_e32 v66, v66, v67, vcc
	v_rsq_f32_e32 v66, v66
	s_nop 0
	v_mul_f32_e32 v67, 0x45800000, v66
	v_cndmask_b32_e32 v66, v66, v67, vcc
	v_mul_f32_e32 v67, 0x3db504f3, v66
	v_cndmask_b32_e64 v66, v66, v67, s[46:47]
	v_pk_mul_f32 v[64:65], v[64:65], v[66:67] op_sel_hi:[1,0]
